# lru_m1: softplus(-lambda) computed once in P0 into a ws table instead of per item; chains removed
# speedup vs baseline: 1.0086x; 1.0014x over previous
; #define LAS __attribute__((address_space(3)))
; __device__ __forceinline__ void ld8bf(const bf16_t* p, float (&o)[8]) { unpack8(*(const u32x4*)p, o); }
; __device__ __forceinline__ const float* in_ptr(const Args& a, int i) { asm volatile("" : "+s"(i)); return a.in[i]; }
; __device__ __forceinline__ void w_lru_m1(const Args& a, int l, unsigned char* ws, const bf16_t* proj, bf16_t* y, LAS unsigned char* wl, int b, int ck_, int h, int lane) {
;     LAS float* xcf = (LAS float*)wl;
;     const int row0 = b * SEQ + 64 * ck_, lo = lane & 15, fq = lane >> 4;
;     const float* cw = in_ptr(a, I_LCW) + (size_t)l * 4 * 512; const float* cbias = in_ptr(a, I_LCB) + l * 512;
;     const bf16_t* gwt = (const bf16_t*)(ws + WS_GATE) + (size_t)l * 65536;
;     const bf16_t* waT = gwt + h * 4096; const bf16_t* wxT = gwt + 32768 + h * 4096;
;     const float* ba = in_ptr(a, I_BA) + l * 512 + 64 * h; const float* bx = in_ptr(a, I_BX) + l * 512 + 64 * h; const float* lam = in_ptr(a, I_LAM) + l * 512 + 64 * h;
;     bf16x8 nWa[2], nWx[2]; f32x4 nba, nbx, nlam;
; #pragma unroll
;     for (int kk = 0; kk < 2; ++kk) { nWa[kk] = *(const bf16x8*)(waT + lo * 64 + 32 * kk + 8 * fq); nWx[kk] = *(const bf16x8*)(wxT + lo * 64 + 32 * kk + 8 * fq); }
;     nba = *(const f32x4*)(ba + 4 * fq); nbx = *(const f32x4*)(bx + 4 * fq); nlam = *(const f32x4*)(lam + 4 * fq);
;     bf16x8 Xf[4][2];
; #pragma unroll
;     for (int kk = 0; kk < 2; ++kk) { const int ch0 = 64 * h + 32 * kk + 8 * fq; float w[4][8], bs[8];
; #pragma unroll
;         for (int j = 0; j < 8; ++j) { bs[j] = cbias[ch0 + j];
; #pragma unroll
;             for (int k = 0; k < 4; ++k) w[k][j] = cw[k * 512 + ch0 + j]; }
; #pragma unroll
;         for (int tb = 0; tb < 4; ++tb) { const int tok = 16 * tb + lo, t = 64 * ck_ + tok; float s[8];
; #pragma unroll
;             for (int j = 0; j < 8; ++j) s[j] = bs[j];
; #pragma unroll
;             for (int k = 0; k < 4; ++k) { const int tt = t - 3 + k; float x[8];
;                 ld8bf(proj + (size_t)(b * SEQ + (tt >= 0 ? tt : 0)) * NIN + C_LX + ch0, x);
; #pragma unroll
;                 for (int j = 0; j < 8; ++j) s[j] += (tt >= 0 ? w[k][j] : 0.f) * x[j]; }
;             Xf[tb][kk] = pack_frag(s);
; #pragma unroll
;             for (int j = 0; j < 8; ++j) xcf[tok * 65 + 32 * kk + 8 * fq + j] = s[j]; }
;     }
.LBB0_520:
	s_lshr_b32 s20, s24, 8
	s_lshr_b32 s21, s24, 9
	s_add_i32 s20, s20, s24
	s_and_b32 s21, s21, 12
	s_add_i32 s20, s20, s21
	s_and_b32 s91, s20, 15
	s_cmp_gt_u32 s91, 7
	s_cbranch_scc1 .LBB0_519
	s_ashr_i32 s20, s24, 31
	s_ashr_i32 s90, s24, 4
	s_lshr_b32 s20, s20, 25
	s_add_i32 s27, s90, s20
	s_and_b32 s20, s27, 0xffffff80
	v_mov_b32_e32 v122, v144
	s_mov_b32 s34, 3
	s_sub_i32 s46, s90, s20
	s_ashr_i32 s35, s34, 31
	s_lshl_b32 s20, s46, 6
	s_lshl_b64 s[34:35], s[34:35], 3
	s_add_u32 s34, s0, s34
	s_addc_u32 s35, s1, s35
	s_load_dwordx2 s[40:41], s[34:35], 0x0
	s_mov_b32 s34, 4
	s_ashr_i32 s35, s34, 31
	s_lshl_b64 s[34:35], s[34:35], 3
	s_add_u32 s34, s0, s34
	s_addc_u32 s35, s1, s35
	s_lshl_b32 s21, s91, 13
	s_add_u32 s92, s2, s21
	s_addc_u32 s93, s3, 0
	s_load_dwordx2 s[42:43], s[34:35], 0x0
	s_add_u32 s34, s68, s21
	s_mov_b32 s44, 6
	s_addc_u32 s35, s70, 0
	s_ashr_i32 s45, s44, 31
	s_lshl_b64 s[44:45], s[44:45], 3
	s_add_u32 s44, s0, s44
	s_addc_u32 s45, s1, s45
	s_waitcnt lgkmcnt(0)
	s_mov_b32 s48, 8
	s_load_dwordx2 s[44:45], s[44:45], 0x0
	s_ashr_i32 s49, s48, 31
	s_lshl_b32 s21, s91, 6
	s_lshl_b64 s[48:49], s[48:49], 3
	s_add_u32 s48, s0, s48
	s_addc_u32 s49, s1, s49
	s_load_dwordx2 s[48:49], s[48:49], 0x0
	v_ashrrev_i32_e32 v8, 4, v122
	v_and_b32_e32 v136, 15, v122
	v_lshlrev_b32_e32 v4, 3, v8
	v_lshlrev_b32_e32 v2, 7, v136
	s_waitcnt lgkmcnt(0)
	s_add_u32 s47, s48, s88
	s_mov_b32 s48, 9
	s_addc_u32 s50, s49, s89
	s_ashr_i32 s49, s48, 31
	s_lshl_b64 s[48:49], s[48:49], 3
	s_add_u32 s48, s0, s48
	s_addc_u32 s49, s1, s49
	s_add_u32 s48, s78, 0x3b00000
	s_addc_u32 s49, s79, 0x0
	v_ashrrev_i32_e32 v5, 31, v4
	v_lshl_add_u64 v[0:1], s[92:93], 0, v[2:3]
	v_lshlrev_b64 v[100:101], 1, v[4:5]
	v_lshl_add_u64 v[0:1], v[0:1], 0, v[100:101]
	s_waitcnt lgkmcnt(0)
	s_add_u32 s51, s48, s88
	s_addc_u32 s52, s49, s89
	s_lshl_b32 s27, s27, 6
	s_and_b32 s27, s27, 0xffffe000
	s_add_u32 s48, s40, s96
	s_addc_u32 s49, s41, s97
	s_add_u32 s42, s42, s88
	s_addc_u32 s43, s43, s89
	s_add_u32 s40, s44, s88
	s_addc_u32 s41, s45, s89
	s_lshl_b32 s53, s91, 8
	s_add_u32 s40, s40, s53
	v_lshl_add_u64 v[6:7], s[34:35], 0, v[2:3]
	s_addc_u32 s41, s41, 0
	v_lshl_add_u64 v[6:7], v[6:7], 0, v[100:101]
	flat_load_dwordx4 v[52:55], v[0:1]
	flat_load_dwordx4 v[56:59], v[6:7]
	flat_load_dwordx4 v[60:63], v[0:1] offset:64
	flat_load_dwordx4 v[64:67], v[6:7] offset:64
	s_add_u32 s44, s47, s53
	v_lshlrev_b32_e32 v0, 2, v8
	s_addc_u32 s45, s50, 0
	v_ashrrev_i32_e32 v1, 31, v0
	s_add_u32 s50, s51, s53
	v_lshlrev_b64 v[6:7], 2, v[0:1]
	s_addc_u32 s51, s52, 0
	v_lshl_add_u64 v[108:109], s[40:41], 0, v[6:7]
	s_add_i32 s40, s20, -3
	v_add_u32_e32 v78, s21, v4
	v_lshl_add_u64 v[110:111], s[44:45], 0, v[6:7]
	v_lshl_add_u64 v[112:113], s[50:51], 0, v[6:7]
	v_ashrrev_i32_e32 v79, 31, v78
	v_add_u32_e32 v6, s40, v136
	v_lshlrev_b64 v[4:5], 2, v[78:79]
	v_cmp_lt_i32_e64 s[50:51], -1, v6
	v_lshl_add_u64 v[76:77], s[42:43], 0, v[4:5]
	v_lshl_add_u64 v[86:87], s[48:49], 0, v[4:5]
	s_mov_b64 s[42:43], 0x1000
	v_cndmask_b32_e64 v4, 0, v6, s[50:51]
	v_lshl_add_u64 v[36:37], v[86:87], 0, s[42:43]
	s_mov_b64 s[42:43], 0x1800
	v_lshl_add_u64 v[80:81], v[78:79], 1, s[8:9]
	v_add_u32_e32 v79, s27, v4
	v_lshl_add_u64 v[82:83], v[86:87], 0, s[42:43]
	v_mad_i64_i32 v[4:5], s[42:43], v79, s72, v[80:81]
	global_load_dwordx4 v[72:75], v[4:5], off
	v_max_i32_e32 v4, -1, v6
	s_or_b32 s80, s27, 1
	v_add_u32_e32 v92, s80, v4
	v_mad_i64_i32 v[4:5], s[42:43], v92, s72, v[80:81]
	global_load_dwordx4 v[16:19], v[4:5], off
	v_max_i32_e32 v4, -2, v6
	s_or_b32 s81, s27, 2
	v_add_u32_e32 v93, s81, v4
	v_mad_i64_i32 v[4:5], s[42:43], v93, s72, v[80:81]
	s_cmp_gt_i32 s46, -1
	global_load_dwordx4 v[12:15], v[4:5], off
	v_or_b32_e32 v4, s20, v136
	s_cselect_b64 s[42:43], -1, 0
	v_cndmask_b32_e64 v4, 0, v4, s[42:43]
	v_add_u32_e32 v94, s27, v4
	v_mad_i64_i32 v[4:5], s[46:47], v94, s72, v[80:81]
	global_load_dwordx4 v[48:51], v[108:109], off
	global_load_dwordx4 v[44:47], v[110:111], off
	global_load_dwordx4 v[88:91], v[112:113], off
	v_lshl_add_u32 v95, v8, 5, s6
	v_cmp_lt_i32_e64 s[48:49], -2, v6
	v_cmp_lt_i32_e64 s[44:45], -3, v6
	global_load_dwordx4 v[8:11], v[4:5], off
	global_load_dwordx4 v[20:23], v[76:77], off offset:16
	s_nop 0
	global_load_dwordx4 v[4:7], v[76:77], off
	global_load_dwordx4 v[24:27], v[86:87], off offset:16
	global_load_dwordx4 v[32:35], v[86:87], off
	global_load_dwordx4 v[28:31], v[86:87], off offset:2064
	global_load_dwordx4 v[40:43], v[86:87], off offset:2048
	v_add_co_u32_e32 v96, vcc, s73, v86
	v_mad_u32_u24 v121, v136, s76, v95
	s_nop 0
	v_addc_co_u32_e32 v97, vcc, 0, v87, vcc
	global_load_dwordx4 v[68:71], v[96:97], off
	s_nop 0
	global_load_dwordx4 v[36:39], v[36:37], off offset:16
	s_nop 0
	global_load_dwordx4 v[104:107], v[96:97], off offset:2048
	global_load_dwordx4 v[114:117], v[82:83], off offset:16
	v_add_u32_e32 v186, s40, v136
	v_add_u32_e32 v186, s27, v186
	v_add_u32_e32 v187, 16, v186
	v_mad_i64_i32 v[188:189], s[46:47], v187, s72, v[80:81]
	global_load_dwordx4 v[222:225], v[188:189], off
	v_add_u32_e32 v187, 17, v186
	v_mad_i64_i32 v[188:189], s[46:47], v187, s72, v[80:81]
	global_load_dwordx4 v[226:229], v[188:189], off
	v_add_u32_e32 v187, 18, v186
	v_mad_i64_i32 v[188:189], s[46:47], v187, s72, v[80:81]
	global_load_dwordx4 v[230:233], v[188:189], off
	v_add_u32_e32 v187, 19, v186
	v_mad_i64_i32 v[188:189], s[46:47], v187, s72, v[80:81]
	global_load_dwordx4 v[234:237], v[188:189], off
	v_add_u32_e32 v187, 32, v186
	v_mad_i64_i32 v[188:189], s[46:47], v187, s72, v[80:81]
	global_load_dwordx4 v[238:241], v[188:189], off
	v_add_u32_e32 v187, 33, v186
	v_mad_i64_i32 v[188:189], s[46:47], v187, s72, v[80:81]
	global_load_dwordx4 v[242:245], v[188:189], off
	v_add_u32_e32 v187, 34, v186
	v_mad_i64_i32 v[188:189], s[46:47], v187, s72, v[80:81]
	global_load_dwordx4 v[246:249], v[188:189], off
	v_add_u32_e32 v187, 35, v186
	v_mad_i64_i32 v[188:189], s[46:47], v187, s72, v[80:81]
	global_load_dwordx4 v[250:253], v[188:189], off
	v_add_u32_e32 v187, 48, v186
	v_mad_i64_i32 v[188:189], s[46:47], v187, s72, v[80:81]
	global_load_dwordx4 v[190:193], v[188:189], off
	v_add_u32_e32 v187, 49, v186
	v_mad_i64_i32 v[188:189], s[46:47], v187, s72, v[80:81]
	global_load_dwordx4 v[194:197], v[188:189], off
	v_or_b32_e32 v140, 16, v136
	v_or_b32_e32 v139, 32, v136
	v_or_b32_e32 v137, 48, v136
	v_mov_b64_e32 v[102:103], s[8:9]
	s_waitcnt vmcnt(0) lgkmcnt(0)
; __device__ __forceinline__ void ld8bf(const bf16_t* p, float (&o)[8]) { unpack8(*(const u32x4*)p, o); }
; __device__ __forceinline__ bf16x8 pack_frag(const float (&v)[8]) { return __builtin_bit_cast(bf16x8, pack8(v)); }
; __device__ __forceinline__ void w_lru_m1(const Args& a, int l, unsigned char* ws, const bf16_t* proj, bf16_t* y, LAS unsigned char* wl, int b, int ck_, int h, int lane) {
;     ...
;         for (int tb = 0; tb < 4; ++tb) { const int tok = 16 * tb + lo, t = 64 * ck_ + tok; float s[8];
; #pragma unroll
;             for (int j = 0; j < 8; ++j) s[j] = bs[j];
; #pragma unroll
;             for (int k = 0; k < 4; ++k) { const int tt = t - 3 + k; float x[8];
;                 ld8bf(proj + (size_t)(b * SEQ + (tt >= 0 ? tt : 0)) * NIN + C_LX + ch0, x);
; #pragma unroll
;                 for (int j = 0; j < 8; ++j) s[j] += (tt >= 0 ? w[k][j] : 0.f) * x[j]; }
;             Xf[tb][kk] = pack_frag(s);
; #pragma unroll
;             for (int j = 0; j < 8; ++j) xcf[tok * 65 + 32 * kk + 8 * fq + j] = s[j]; }
	v_lshlrev_b32_e32 v82, 16, v72
	v_lshlrev_b32_e32 v84, 16, v73
	v_and_b32_e32 v83, 0xffff0000, v72
	v_and_b32_e32 v85, 0xffff0000, v73
	v_cndmask_b32_e64 v73, 0, v33, s[50:51]
	v_cndmask_b32_e64 v72, 0, v32, s[50:51]
	v_cndmask_b32_e64 v99, 0, v35, s[50:51]
	v_cndmask_b32_e64 v98, 0, v34, s[50:51]
	v_pk_fma_f32 v[84:85], v[98:99], v[84:85], v[6:7]
	v_pk_fma_f32 v[72:73], v[72:73], v[82:83], v[4:5]
	v_lshlrev_b32_e32 v82, 16, v17
	v_lshlrev_b32_e32 v98, 16, v16
	v_and_b32_e32 v83, 0xffff0000, v17
	v_and_b32_e32 v99, 0xffff0000, v16
	v_cndmask_b32_e64 v17, 0, v43, s[48:49]
	v_cndmask_b32_e64 v16, 0, v42, s[48:49]
	v_cndmask_b32_e64 v119, 0, v41, s[48:49]
	v_cndmask_b32_e64 v118, 0, v40, s[48:49]
	v_pk_fma_f32 v[72:73], v[118:119], v[98:99], v[72:73]
	v_pk_fma_f32 v[16:17], v[16:17], v[82:83], v[84:85]
	v_lshlrev_b32_e32 v82, 16, v12
	v_lshlrev_b32_e32 v84, 16, v13
	v_and_b32_e32 v83, 0xffff0000, v12
	v_and_b32_e32 v85, 0xffff0000, v13
	v_cndmask_b32_e64 v13, 0, v69, s[44:45]
	v_cndmask_b32_e64 v12, 0, v68, s[44:45]
	v_cndmask_b32_e64 v99, 0, v71, s[44:45]
	v_cndmask_b32_e64 v98, 0, v70, s[44:45]
	v_pk_fma_f32 v[16:17], v[98:99], v[84:85], v[16:17]
	v_pk_fma_f32 v[12:13], v[12:13], v[82:83], v[72:73]
	v_lshlrev_b32_e32 v84, 16, v9
	v_lshlrev_b32_e32 v98, 16, v8
	v_and_b32_e32 v85, 0xffff0000, v9
	v_and_b32_e32 v99, 0xffff0000, v8
	v_cndmask_b32_e64 v73, 0, v107, s[42:43]
	v_cndmask_b32_e64 v72, 0, v106, s[42:43]
	v_cndmask_b32_e64 v83, 0, v105, s[42:43]
	v_cndmask_b32_e64 v82, 0, v104, s[42:43]
	v_pk_fma_f32 v[8:9], v[82:83], v[98:99], v[12:13]
	v_pk_fma_f32 v[12:13], v[72:73], v[84:85], v[16:17]
	v_cvt_pk_bf16_f32 v16, v8, v9
	v_cvt_pk_bf16_f32 v17, v12, v13
	ds_write2_b32 v121, v12, v13 offset0:2 offset1:3
	ds_write2_b32 v121, v8, v9 offset1:1
	v_lshlrev_b32_e32 v8, 16, v74
	v_lshlrev_b32_e32 v12, 16, v75
	v_and_b32_e32 v9, 0xffff0000, v74
	v_and_b32_e32 v13, 0xffff0000, v75
	v_cndmask_b32_e64 v75, 0, v25, s[50:51]
	v_cndmask_b32_e64 v74, 0, v24, s[50:51]
	v_cndmask_b32_e64 v85, 0, v27, s[50:51]
	v_cndmask_b32_e64 v84, 0, v26, s[50:51]
	v_pk_fma_f32 v[12:13], v[84:85], v[12:13], v[22:23]
	v_pk_fma_f32 v[8:9], v[74:75], v[8:9], v[20:21]
	v_lshlrev_b32_e32 v74, 16, v19
	v_lshlrev_b32_e32 v84, 16, v18
	v_and_b32_e32 v75, 0xffff0000, v19
	v_and_b32_e32 v85, 0xffff0000, v18
	v_cndmask_b32_e64 v19, 0, v31, s[48:49]
	v_cndmask_b32_e64 v18, 0, v30, s[48:49]
	v_cndmask_b32_e64 v99, 0, v29, s[48:49]
	v_cndmask_b32_e64 v98, 0, v28, s[48:49]
	v_pk_fma_f32 v[8:9], v[98:99], v[84:85], v[8:9]
	v_pk_fma_f32 v[12:13], v[18:19], v[74:75], v[12:13]
	v_lshlrev_b32_e32 v18, 16, v14
	v_lshlrev_b32_e32 v74, 16, v15
	v_and_b32_e32 v19, 0xffff0000, v14
	v_and_b32_e32 v75, 0xffff0000, v15
	v_cndmask_b32_e64 v15, 0, v37, s[44:45]
	v_cndmask_b32_e64 v14, 0, v36, s[44:45]
	v_cndmask_b32_e64 v85, 0, v39, s[44:45]
	v_cndmask_b32_e64 v84, 0, v38, s[44:45]
	v_pk_fma_f32 v[12:13], v[84:85], v[74:75], v[12:13]
	v_pk_fma_f32 v[8:9], v[14:15], v[18:19], v[8:9]
	v_lshlrev_b32_e32 v14, 16, v11
	v_lshlrev_b32_e32 v18, 16, v10
	v_and_b32_e32 v15, 0xffff0000, v11
	v_and_b32_e32 v19, 0xffff0000, v10
	v_cndmask_b32_e64 v75, 0, v117, s[42:43]
	v_cndmask_b32_e64 v74, 0, v116, s[42:43]
	v_cndmask_b32_e64 v85, 0, v115, s[42:43]
	v_cndmask_b32_e64 v84, 0, v114, s[42:43]
	v_add_u32_e32 v98, s40, v140
	v_pk_fma_f32 v[8:9], v[84:85], v[18:19], v[8:9]
	v_pk_fma_f32 v[10:11], v[74:75], v[14:15], v[12:13]
	v_cmp_lt_i32_e64 s[62:63], -1, v98
	v_cvt_pk_bf16_f32 v18, v8, v9
	ds_write2_b32 v121, v10, v11 offset0:6 offset1:7
	ds_write2_b32 v121, v8, v9 offset0:4 offset1:5
	v_cndmask_b32_e64 v8, 0, v98, s[62:63]
	v_cmp_lt_i32_e64 s[60:61], -2, v98
	v_max_i32_e32 v12, -1, v98
	v_cmp_lt_i32_e64 s[58:59], -3, v98
	v_max_i32_e32 v98, -2, v98
	v_add_u32_e32 v142, s81, v98
	v_add_u32_e32 v134, s27, v8
	v_mad_i64_i32 v[98:99], s[46:47], v142, s72, v[80:81]
	v_mad_i64_i32 v[8:9], s[46:47], v134, s72, v[80:81]
	v_add_u32_e32 v135, s80, v12
	v_mov_b64_e32 v[104:105], v[230:231]
	v_mov_b64_e32 v[106:107], v[232:233]
	v_or_b32_e32 v98, s20, v140
	v_cvt_pk_bf16_f32 v19, v10, v11
	v_mov_b64_e32 v[8:9], v[222:223]
	v_mov_b64_e32 v[10:11], v[224:225]
	v_mad_i64_i32 v[12:13], s[46:47], v135, s72, v[80:81]
	v_cndmask_b32_e64 v98, 0, v98, s[42:43]
	v_mov_b64_e32 v[12:13], v[226:227]
	v_mov_b64_e32 v[14:15], v[228:229]
	v_add_u32_e32 v143, s27, v98
	v_mad_i64_i32 v[98:99], s[46:47], v143, s72, v[80:81]
	v_mov_b64_e32 v[114:115], v[234:235]
	v_mov_b64_e32 v[116:117], v[236:237]
	v_mov_b32_e32 v98, 0x1040
	v_mad_u32_u24 v123, v136, s76, v98
	v_cndmask_b32_e64 v127, 0, v35, s[62:63]
	v_cndmask_b32_e64 v126, 0, v34, s[62:63]
	v_cndmask_b32_e64 v129, 0, v41, s[60:61]
	v_cndmask_b32_e64 v128, 0, v40, s[60:61]
	v_add_u32_e32 v125, v95, v123
	s_waitcnt vmcnt(0) lgkmcnt(0)
; __device__ __forceinline__ void ld8bf(const bf16_t* p, float (&o)[8]) { unpack8(*(const u32x4*)p, o); }
; __device__ __forceinline__ bf16x8 pack_frag(const float (&v)[8]) { return __builtin_bit_cast(bf16x8, pack8(v)); }
; __device__ __forceinline__ void w_lru_m1(const Args& a, int l, unsigned char* ws, const bf16_t* proj, bf16_t* y, LAS unsigned char* wl, int b, int ck_, int h, int lane) {
;     ...
;         for (int tb = 0; tb < 4; ++tb) { const int tok = 16 * tb + lo, t = 64 * ck_ + tok; float s[8];
; #pragma unroll
;             for (int j = 0; j < 8; ++j) s[j] = bs[j];
; #pragma unroll
;             for (int k = 0; k < 4; ++k) { const int tt = t - 3 + k; float x[8];
;                 ld8bf(proj + (size_t)(b * SEQ + (tt >= 0 ? tt : 0)) * NIN + C_LX + ch0, x);
; #pragma unroll
;                 for (int j = 0; j < 8; ++j) s[j] += (tt >= 0 ? w[k][j] : 0.f) * x[j]; }
;             Xf[tb][kk] = pack_frag(s);
; #pragma unroll
;             for (int j = 0; j < 8; ++j) xcf[tok * 65 + 32 * kk + 8 * fq + j] = s[j]; }
	v_lshlrev_b32_e32 v98, 16, v8
	v_lshlrev_b32_e32 v118, 16, v9
	v_and_b32_e32 v99, 0xffff0000, v8
	v_and_b32_e32 v119, 0xffff0000, v9
	v_cndmask_b32_e64 v9, 0, v33, s[62:63]
	v_cndmask_b32_e64 v8, 0, v32, s[62:63]
	v_pk_fma_f32 v[118:119], v[126:127], v[118:119], v[6:7]
	v_pk_fma_f32 v[8:9], v[8:9], v[98:99], v[4:5]
	v_lshlrev_b32_e32 v98, 16, v13
	v_lshlrev_b32_e32 v126, 16, v12
	v_and_b32_e32 v99, 0xffff0000, v13
	v_and_b32_e32 v127, 0xffff0000, v12
	v_cndmask_b32_e64 v13, 0, v43, s[60:61]
	v_cndmask_b32_e64 v12, 0, v42, s[60:61]
	v_pk_fma_f32 v[8:9], v[128:129], v[126:127], v[8:9]
	v_pk_fma_f32 v[12:13], v[12:13], v[98:99], v[118:119]
	v_lshlrev_b32_e32 v98, 16, v104
	v_lshlrev_b32_e32 v118, 16, v105
	v_and_b32_e32 v99, 0xffff0000, v104
	v_and_b32_e32 v119, 0xffff0000, v105
	v_cndmask_b32_e64 v105, 0, v69, s[58:59]
	v_cndmask_b32_e64 v104, 0, v68, s[58:59]
	v_cndmask_b32_e64 v127, 0, v71, s[58:59]
	v_cndmask_b32_e64 v126, 0, v70, s[58:59]
	v_pk_fma_f32 v[12:13], v[126:127], v[118:119], v[12:13]
	v_pk_fma_f32 v[8:9], v[104:105], v[98:99], v[8:9]
	v_lshlrev_b32_e32 v98, 16, v115
	v_lshlrev_b32_e32 v104, 16, v114
	v_and_b32_e32 v99, 0xffff0000, v115
	v_and_b32_e32 v105, 0xffff0000, v114
	v_pk_fma_f32 v[8:9], v[82:83], v[104:105], v[8:9]
	v_pk_fma_f32 v[98:99], v[72:73], v[98:99], v[12:13]
	v_cvt_pk_bf16_f32 v12, v8, v9
	v_cvt_pk_bf16_f32 v13, v98, v99
	ds_write2_b32 v125, v98, v99 offset0:2 offset1:3
	ds_write2_b32 v125, v8, v9 offset1:1
	v_lshlrev_b32_e32 v8, 16, v10
	v_lshlrev_b32_e32 v98, 16, v11
	v_and_b32_e32 v9, 0xffff0000, v10
	v_and_b32_e32 v99, 0xffff0000, v11
	v_cndmask_b32_e64 v11, 0, v25, s[62:63]
	v_cndmask_b32_e64 v10, 0, v24, s[62:63]
	v_cndmask_b32_e64 v105, 0, v27, s[62:63]
	v_cndmask_b32_e64 v104, 0, v26, s[62:63]
	v_pk_fma_f32 v[98:99], v[104:105], v[98:99], v[22:23]
	v_pk_fma_f32 v[8:9], v[10:11], v[8:9], v[20:21]
	v_lshlrev_b32_e32 v10, 16, v15
	v_lshlrev_b32_e32 v104, 16, v14
	v_and_b32_e32 v11, 0xffff0000, v15
	v_and_b32_e32 v105, 0xffff0000, v14
	v_cndmask_b32_e64 v15, 0, v31, s[60:61]
	v_cndmask_b32_e64 v14, 0, v30, s[60:61]
	v_cndmask_b32_e64 v115, 0, v29, s[60:61]
	v_cndmask_b32_e64 v114, 0, v28, s[60:61]
	v_pk_fma_f32 v[8:9], v[114:115], v[104:105], v[8:9]
	v_pk_fma_f32 v[10:11], v[14:15], v[10:11], v[98:99]
	v_lshlrev_b32_e32 v14, 16, v106
	v_lshlrev_b32_e32 v98, 16, v107
	v_and_b32_e32 v15, 0xffff0000, v106
	v_and_b32_e32 v99, 0xffff0000, v107
	v_cndmask_b32_e64 v105, 0, v37, s[58:59]
	v_cndmask_b32_e64 v104, 0, v36, s[58:59]
	v_cndmask_b32_e64 v107, 0, v39, s[58:59]
	v_cndmask_b32_e64 v106, 0, v38, s[58:59]
	v_pk_fma_f32 v[10:11], v[106:107], v[98:99], v[10:11]
	v_pk_fma_f32 v[8:9], v[104:105], v[14:15], v[8:9]
	v_lshlrev_b32_e32 v14, 16, v117
	v_lshlrev_b32_e32 v98, 16, v116
	v_and_b32_e32 v15, 0xffff0000, v117
	v_and_b32_e32 v99, 0xffff0000, v116
	v_add_u32_e32 v114, s40, v139
	v_pk_fma_f32 v[8:9], v[84:85], v[98:99], v[8:9]
	v_pk_fma_f32 v[10:11], v[74:75], v[14:15], v[10:11]
	v_cmp_lt_i32_e64 s[56:57], -1, v114
	v_cvt_pk_bf16_f32 v14, v8, v9
	ds_write2_b32 v125, v10, v11 offset0:6 offset1:7
	ds_write2_b32 v125, v8, v9 offset0:4 offset1:5
	v_cndmask_b32_e64 v8, 0, v114, s[56:57]
	v_max_i32_e32 v98, -1, v114
	v_add_u32_e32 v130, s27, v8
	v_add_u32_e32 v131, s80, v98
	v_mad_i64_i32 v[8:9], s[46:47], v130, s72, v[80:81]
	v_mad_i64_i32 v[98:99], s[46:47], v131, s72, v[80:81]
	v_cvt_pk_bf16_f32 v15, v10, v11
	v_mov_b64_e32 v[8:9], v[238:239]
	v_mov_b64_e32 v[10:11], v[240:241]
	v_cmp_lt_i32_e64 s[54:55], -2, v114
	v_mov_b64_e32 v[104:105], v[242:243]
	v_mov_b64_e32 v[106:107], v[244:245]
	v_max_i32_e32 v98, -2, v114
	v_add_u32_e32 v132, s81, v98
	v_mad_i64_i32 v[98:99], s[46:47], v132, s72, v[80:81]
	v_cmp_lt_i32_e64 s[52:53], -3, v114
	v_mov_b64_e32 v[114:115], v[246:247]
	v_mov_b64_e32 v[116:117], v[248:249]
	v_or_b32_e32 v98, s20, v139
	v_cndmask_b32_e64 v98, 0, v98, s[42:43]
	v_add_u32_e32 v133, s27, v98
	v_mad_i64_i32 v[98:99], s[46:47], v133, s72, v[80:81]
	v_mov_b64_e32 v[126:127], v[250:251]
	v_mov_b64_e32 v[128:129], v[252:253]
	v_mov_b32_e32 v98, 0x2080
	v_mad_u32_u24 v141, v136, s76, v98
	v_cndmask_b32_e64 v147, 0, v35, s[56:57]
	v_cndmask_b32_e64 v146, 0, v34, s[56:57]
	v_cndmask_b32_e64 v149, 0, v41, s[54:55]
	v_cndmask_b32_e64 v148, 0, v40, s[54:55]
	v_add_u32_e32 v124, v95, v141
	s_waitcnt vmcnt(0) lgkmcnt(0)
; __device__ __forceinline__ void ld8bf(const bf16_t* p, float (&o)[8]) { unpack8(*(const u32x4*)p, o); }
; __device__ __forceinline__ bf16x8 pack_frag(const float (&v)[8]) { return __builtin_bit_cast(bf16x8, pack8(v)); }
; __device__ __forceinline__ void w_lru_m1(const Args& a, int l, unsigned char* ws, const bf16_t* proj, bf16_t* y, LAS unsigned char* wl, int b, int ck_, int h, int lane) {
;     ...
;         for (int tb = 0; tb < 4; ++tb) { const int tok = 16 * tb + lo, t = 64 * ck_ + tok; float s[8];
; #pragma unroll
;             for (int j = 0; j < 8; ++j) s[j] = bs[j];
; #pragma unroll
;             for (int k = 0; k < 4; ++k) { const int tt = t - 3 + k; float x[8];
;                 ld8bf(proj + (size_t)(b * SEQ + (tt >= 0 ? tt : 0)) * NIN + C_LX + ch0, x);
; #pragma unroll
;                 for (int j = 0; j < 8; ++j) s[j] += (tt >= 0 ? w[k][j] : 0.f) * x[j]; }
;             Xf[tb][kk] = pack_frag(s);
; #pragma unroll
;             for (int j = 0; j < 8; ++j) xcf[tok * 65 + 32 * kk + 8 * fq + j] = s[j]; }
	v_lshlrev_b32_e32 v98, 16, v8
	v_lshlrev_b32_e32 v118, 16, v9
	v_and_b32_e32 v99, 0xffff0000, v8
	v_and_b32_e32 v119, 0xffff0000, v9
	v_cndmask_b32_e64 v9, 0, v33, s[56:57]
	v_cndmask_b32_e64 v8, 0, v32, s[56:57]
	v_pk_fma_f32 v[118:119], v[146:147], v[118:119], v[6:7]
	v_pk_fma_f32 v[8:9], v[8:9], v[98:99], v[4:5]
	v_lshlrev_b32_e32 v98, 16, v105
	v_lshlrev_b32_e32 v146, 16, v104
	v_and_b32_e32 v99, 0xffff0000, v105
	v_and_b32_e32 v147, 0xffff0000, v104
	v_cndmask_b32_e64 v105, 0, v43, s[54:55]
	v_cndmask_b32_e64 v104, 0, v42, s[54:55]
	v_pk_fma_f32 v[8:9], v[148:149], v[146:147], v[8:9]
	v_pk_fma_f32 v[98:99], v[104:105], v[98:99], v[118:119]
	v_lshlrev_b32_e32 v104, 16, v114
	v_lshlrev_b32_e32 v118, 16, v115
	v_and_b32_e32 v105, 0xffff0000, v114
	v_and_b32_e32 v119, 0xffff0000, v115
	v_cndmask_b32_e64 v115, 0, v69, s[52:53]
	v_cndmask_b32_e64 v114, 0, v68, s[52:53]
	v_cndmask_b32_e64 v147, 0, v71, s[52:53]
	v_cndmask_b32_e64 v146, 0, v70, s[52:53]
	v_pk_fma_f32 v[98:99], v[146:147], v[118:119], v[98:99]
	v_pk_fma_f32 v[8:9], v[114:115], v[104:105], v[8:9]
	v_lshlrev_b32_e32 v104, 16, v127
	v_lshlrev_b32_e32 v114, 16, v126
	v_and_b32_e32 v105, 0xffff0000, v127
	v_and_b32_e32 v115, 0xffff0000, v126
	v_pk_fma_f32 v[114:115], v[82:83], v[114:115], v[8:9]
	v_pk_fma_f32 v[98:99], v[72:73], v[104:105], v[98:99]
	v_cvt_pk_bf16_f32 v8, v114, v115
	v_cvt_pk_bf16_f32 v9, v98, v99
	ds_write2_b32 v124, v98, v99 offset0:2 offset1:3
	ds_write2_b32 v124, v114, v115 offset1:1
	v_lshlrev_b32_e32 v98, 16, v10
	v_lshlrev_b32_e32 v104, 16, v11
	v_and_b32_e32 v99, 0xffff0000, v10
	v_and_b32_e32 v105, 0xffff0000, v11
	v_cndmask_b32_e64 v11, 0, v25, s[56:57]
	v_cndmask_b32_e64 v10, 0, v24, s[56:57]
	v_cndmask_b32_e64 v115, 0, v27, s[56:57]
	v_cndmask_b32_e64 v114, 0, v26, s[56:57]
	v_pk_fma_f32 v[104:105], v[114:115], v[104:105], v[22:23]
	v_pk_fma_f32 v[10:11], v[10:11], v[98:99], v[20:21]
	v_lshlrev_b32_e32 v98, 16, v107
	v_lshlrev_b32_e32 v114, 16, v106
	v_and_b32_e32 v99, 0xffff0000, v107
	v_and_b32_e32 v115, 0xffff0000, v106
	v_cndmask_b32_e64 v107, 0, v31, s[54:55]
	v_cndmask_b32_e64 v106, 0, v30, s[54:55]
	v_cndmask_b32_e64 v119, 0, v29, s[54:55]
	v_cndmask_b32_e64 v118, 0, v28, s[54:55]
	v_pk_fma_f32 v[10:11], v[118:119], v[114:115], v[10:11]
	v_pk_fma_f32 v[98:99], v[106:107], v[98:99], v[104:105]
	v_lshlrev_b32_e32 v104, 16, v116
	v_lshlrev_b32_e32 v106, 16, v117
	v_and_b32_e32 v105, 0xffff0000, v116
	v_and_b32_e32 v107, 0xffff0000, v117
	v_cndmask_b32_e64 v115, 0, v37, s[52:53]
	v_cndmask_b32_e64 v114, 0, v36, s[52:53]
	v_cndmask_b32_e64 v117, 0, v39, s[52:53]
	v_cndmask_b32_e64 v116, 0, v38, s[52:53]
	v_pk_fma_f32 v[98:99], v[116:117], v[106:107], v[98:99]
	v_pk_fma_f32 v[10:11], v[114:115], v[104:105], v[10:11]
	v_lshlrev_b32_e32 v104, 16, v129
	v_and_b32_e32 v105, 0xffff0000, v129
	v_add_u32_e32 v118, s40, v137
	v_lshlrev_b32_e32 v106, 16, v128
	v_and_b32_e32 v107, 0xffff0000, v128
	v_pk_fma_f32 v[98:99], v[74:75], v[104:105], v[98:99]
	v_cmp_lt_i32_e64 s[46:47], -1, v118
	v_pk_fma_f32 v[106:107], v[84:85], v[106:107], v[10:11]
	v_cvt_pk_bf16_f32 v11, v98, v99
	ds_write2_b32 v124, v98, v99 offset0:6 offset1:7
	ds_write2_b32 v124, v106, v107 offset0:4 offset1:5
	v_cndmask_b32_e64 v98, 0, v118, s[46:47]
	v_add_u32_e32 v126, s27, v98
	v_mad_i64_i32 v[98:99], s[40:41], v126, s72, v[80:81]
	v_cvt_pk_bf16_f32 v10, v106, v107
	v_mov_b64_e32 v[104:105], v[190:191]
	v_mov_b64_e32 v[106:107], v[192:193]
	v_max_i32_e32 v98, -1, v118
	v_add_u32_e32 v127, s80, v98
	v_mad_i64_i32 v[98:99], vcc, v127, s72, v[80:81]
	v_mov_b64_e32 v[114:115], v[194:195]
	v_mov_b64_e32 v[116:117], v[196:197]
	v_max_i32_e32 v98, -2, v118
	v_add_u32_e32 v128, s81, v98
	v_mad_i64_i32 v[98:99], s[80:81], v128, s72, v[80:81]
	global_load_dwordx4 v[146:149], v[98:99], off
	v_or_b32_e32 v98, s20, v137
	v_cndmask_b32_e64 v98, 0, v98, s[42:43]
	v_add_u32_e32 v129, s27, v98
	v_mad_i64_i32 v[80:81], s[80:81], v129, s72, v[80:81]
	global_load_dwordx4 v[150:153], v[80:81], off
	v_mov_b32_e32 v80, 0x30c0
	v_cmp_lt_i32_e64 s[40:41], -2, v118
	v_mad_u32_u24 v138, v136, s76, v80
	v_cndmask_b32_e64 v33, 0, v33, s[46:47]
	v_cndmask_b32_e64 v32, 0, v32, s[46:47]
	v_cndmask_b32_e64 v35, 0, v35, s[46:47]
	v_cndmask_b32_e64 v34, 0, v34, s[46:47]
	v_cmp_lt_i32_e32 vcc, -3, v118
	v_cndmask_b32_e64 v43, 0, v43, s[40:41]
	v_cndmask_b32_e64 v42, 0, v42, s[40:41]
	v_cndmask_b32_e64 v41, 0, v41, s[40:41]
	v_cndmask_b32_e64 v40, 0, v40, s[40:41]
	v_add_u32_e32 v120, v95, v138
	v_cndmask_b32_e64 v25, 0, v25, s[46:47]
	v_cndmask_b32_e64 v24, 0, v24, s[46:47]
	v_cndmask_b32_e64 v27, 0, v27, s[46:47]
	v_cndmask_b32_e64 v26, 0, v26, s[46:47]
	v_cndmask_b32_e64 v29, 0, v29, s[40:41]
	v_cndmask_b32_e64 v28, 0, v28, s[40:41]
	s_mov_b64 s[80:81], 0x1080
	s_waitcnt vmcnt(0) lgkmcnt(0)
; __device__ __forceinline__ void ld8bf(const bf16_t* p, float (&o)[8]) { unpack8(*(const u32x4*)p, o); }
; __device__ __forceinline__ bf16x8 pack_frag(const float (&v)[8]) { return __builtin_bit_cast(bf16x8, pack8(v)); }
; __device__ __forceinline__ void w_lru_m1(const Args& a, int l, unsigned char* ws, const bf16_t* proj, bf16_t* y, LAS unsigned char* wl, int b, int ck_, int h, int lane) {
;     ...
;     for (int kk = 0; kk < 2; ++kk) { const int ch0 = 64 * h + 32 * kk + 8 * fq; float w[4][8], bs[8];
; #pragma unroll
;         for (int j = 0; j < 8; ++j) { bs[j] = cbias[ch0 + j];
; #pragma unroll
;             for (int k = 0; k < 4; ++k) w[k][j] = cw[k * 512 + ch0 + j]; }
; #pragma unroll
;         for (int tb = 0; tb < 4; ++tb) { const int tok = 16 * tb + lo, t = 64 * ck_ + tok; float s[8];
; #pragma unroll
;             for (int j = 0; j < 8; ++j) s[j] = bs[j];
; #pragma unroll
;             for (int k = 0; k < 4; ++k) { const int tt = t - 3 + k; float x[8];
;                 ld8bf(proj + (size_t)(b * SEQ + (tt >= 0 ? tt : 0)) * NIN + C_LX + ch0, x);
; #pragma unroll
;                 for (int j = 0; j < 8; ++j) s[j] += (tt >= 0 ? w[k][j] : 0.f) * x[j]; }
;             Xf[tb][kk] = pack_frag(s);
; #pragma unroll
;             for (int j = 0; j < 8; ++j) xcf[tok * 65 + 32 * kk + 8 * fq + j] = s[j]; }
	v_lshlrev_b32_e32 v80, 16, v104
	v_lshlrev_b32_e32 v98, 16, v105
	v_and_b32_e32 v81, 0xffff0000, v104
	v_and_b32_e32 v99, 0xffff0000, v105
	v_pk_fma_f32 v[6:7], v[34:35], v[98:99], v[6:7]
	v_pk_fma_f32 v[4:5], v[32:33], v[80:81], v[4:5]
	v_lshlrev_b32_e32 v32, 16, v115
	v_lshlrev_b32_e32 v34, 16, v114
	v_and_b32_e32 v33, 0xffff0000, v115
	v_and_b32_e32 v35, 0xffff0000, v114
	v_pk_fma_f32 v[4:5], v[40:41], v[34:35], v[4:5]
	v_pk_fma_f32 v[6:7], v[42:43], v[32:33], v[6:7]
	v_lshlrev_b32_e32 v32, 16, v146
	v_lshlrev_b32_e32 v34, 16, v147
	v_and_b32_e32 v33, 0xffff0000, v146
	v_and_b32_e32 v35, 0xffff0000, v147
	v_cndmask_b32_e32 v41, 0, v69, vcc
	v_cndmask_b32_e32 v40, 0, v68, vcc
	v_cndmask_b32_e32 v43, 0, v71, vcc
	v_cndmask_b32_e32 v42, 0, v70, vcc
	v_pk_fma_f32 v[6:7], v[42:43], v[34:35], v[6:7]
	v_pk_fma_f32 v[4:5], v[40:41], v[32:33], v[4:5]
	v_lshlrev_b32_e32 v32, 16, v151
	v_and_b32_e32 v33, 0xffff0000, v151
	v_lshlrev_b32_e32 v34, 16, v150
	v_and_b32_e32 v35, 0xffff0000, v150
	v_pk_fma_f32 v[6:7], v[72:73], v[32:33], v[6:7]
	v_pk_fma_f32 v[34:35], v[82:83], v[34:35], v[4:5]
	v_cvt_pk_bf16_f32 v5, v6, v7
	ds_write2_b32 v120, v6, v7 offset0:2 offset1:3
	ds_write2_b32 v120, v34, v35 offset1:1
	v_lshlrev_b32_e32 v6, 16, v106
	v_lshlrev_b32_e32 v32, 16, v107
	v_and_b32_e32 v7, 0xffff0000, v106
	v_and_b32_e32 v33, 0xffff0000, v107
	v_pk_fma_f32 v[22:23], v[26:27], v[32:33], v[22:23]
	v_pk_fma_f32 v[6:7], v[24:25], v[6:7], v[20:21]
	v_lshlrev_b32_e32 v20, 16, v117
	v_lshlrev_b32_e32 v24, 16, v116
	v_and_b32_e32 v21, 0xffff0000, v117
	v_and_b32_e32 v25, 0xffff0000, v116
	v_cndmask_b32_e64 v27, 0, v31, s[40:41]
	v_cndmask_b32_e64 v26, 0, v30, s[40:41]
	v_pk_fma_f32 v[6:7], v[28:29], v[24:25], v[6:7]
	v_pk_fma_f32 v[20:21], v[26:27], v[20:21], v[22:23]
	v_lshlrev_b32_e32 v22, 16, v148
	v_lshlrev_b32_e32 v24, 16, v149
	v_and_b32_e32 v23, 0xffff0000, v148
	v_and_b32_e32 v25, 0xffff0000, v149
	v_cndmask_b32_e32 v27, 0, v37, vcc
	v_cndmask_b32_e32 v26, 0, v36, vcc
	v_cndmask_b32_e32 v29, 0, v39, vcc
	v_cndmask_b32_e32 v28, 0, v38, vcc
	v_pk_fma_f32 v[20:21], v[28:29], v[24:25], v[20:21]
	v_pk_fma_f32 v[6:7], v[26:27], v[22:23], v[6:7]
	v_lshlrev_b32_e32 v22, 16, v153
	v_and_b32_e32 v23, 0xffff0000, v153
	v_lshlrev_b32_e32 v24, 16, v152
	v_and_b32_e32 v25, 0xffff0000, v152
	v_pk_fma_f32 v[20:21], v[74:75], v[22:23], v[20:21]
	v_pk_fma_f32 v[24:25], v[84:85], v[24:25], v[6:7]
	v_cvt_pk_bf16_f32 v7, v20, v21
	ds_write2_b32 v120, v20, v21 offset0:6 offset1:7
	ds_write2_b32 v120, v24, v25 offset0:4 offset1:5
	v_add_u32_e32 v20, 32, v78
	v_ashrrev_i32_e32 v21, 31, v20
	v_lshl_add_u64 v[84:85], v[86:87], 0, s[80:81]
	s_mov_b64 s[80:81], 0x1880
	v_lshl_add_u64 v[106:107], v[86:87], 0, s[80:81]
	v_mad_i64_i32 v[22:23], s[80:81], v79, s72, v[102:103]
	v_lshlrev_b64 v[104:105], 1, v[20:21]
	v_lshl_add_u64 v[20:21], v[22:23], 0, v[104:105]
	flat_load_dwordx4 v[80:83], v[20:21]
	v_mad_i64_i32 v[20:21], s[80:81], v92, s72, v[102:103]
	v_lshl_add_u64 v[20:21], v[20:21], 0, v[104:105]
	v_cvt_pk_bf16_f32 v4, v34, v35
	flat_load_dwordx4 v[32:35], v[20:21]
	v_mad_i64_i32 v[20:21], s[80:81], v93, s72, v[102:103]
	v_lshl_add_u64 v[20:21], v[20:21], 0, v[104:105]
	flat_load_dwordx4 v[28:31], v[20:21]
	v_mad_i64_i32 v[20:21], s[80:81], v94, s72, v[102:103]
	v_lshl_add_u64 v[20:21], v[20:21], 0, v[104:105]
	v_cvt_pk_bf16_f32 v6, v24, v25
	flat_load_dwordx4 v[24:27], v[20:21]
	global_load_dwordx4 v[40:43], v[76:77], off offset:144
	global_load_dwordx4 v[72:75], v[76:77], off offset:128
	global_load_dwordx4 v[68:71], v[86:87], off offset:144
	s_nop 0
	global_load_dwordx4 v[76:79], v[86:87], off offset:128
	global_load_dwordx4 v[36:39], v[86:87], off offset:2192
	global_load_dwordx4 v[20:23], v[86:87], off offset:2176
	global_load_dwordx4 v[92:95], v[96:97], off offset:128
	s_nop 0
	global_load_dwordx4 v[84:87], v[84:85], off offset:16
	s_nop 0
	global_load_dwordx4 v[96:99], v[96:97], off offset:2176
	s_nop 0
	global_load_dwordx4 v[146:149], v[106:107], off offset:16
	s_waitcnt vmcnt(0) lgkmcnt(0)
	v_lshlrev_b32_e32 v106, 16, v80
	v_lshlrev_b32_e32 v114, 16, v81
	v_and_b32_e32 v107, 0xffff0000, v80
	v_and_b32_e32 v115, 0xffff0000, v81
	v_cndmask_b32_e64 v81, 0, v77, s[50:51]
	v_cndmask_b32_e64 v80, 0, v76, s[50:51]
	v_cndmask_b32_e64 v117, 0, v79, s[50:51]
	v_cndmask_b32_e64 v116, 0, v78, s[50:51]
	v_pk_fma_f32 v[114:115], v[116:117], v[114:115], v[74:75]
	v_pk_fma_f32 v[80:81], v[80:81], v[106:107], v[72:73]
	v_lshlrev_b32_e32 v106, 16, v33
	v_lshlrev_b32_e32 v116, 16, v32
	v_and_b32_e32 v107, 0xffff0000, v33
	v_and_b32_e32 v117, 0xffff0000, v32
	v_cndmask_b32_e64 v33, 0, v23, s[48:49]
	v_cndmask_b32_e64 v32, 0, v22, s[48:49]
	v_cndmask_b32_e64 v119, 0, v21, s[48:49]
	v_cndmask_b32_e64 v118, 0, v20, s[48:49]
	v_pk_fma_f32 v[80:81], v[118:119], v[116:117], v[80:81]
	v_pk_fma_f32 v[32:33], v[32:33], v[106:107], v[114:115]
	v_lshlrev_b32_e32 v106, 16, v28
	v_lshlrev_b32_e32 v114, 16, v29
	v_and_b32_e32 v107, 0xffff0000, v28
	v_and_b32_e32 v115, 0xffff0000, v29
	v_cndmask_b32_e64 v29, 0, v93, s[44:45]
	v_cndmask_b32_e64 v28, 0, v92, s[44:45]
	v_cndmask_b32_e64 v117, 0, v95, s[44:45]
	v_cndmask_b32_e64 v116, 0, v94, s[44:45]
	v_pk_fma_f32 v[32:33], v[116:117], v[114:115], v[32:33]
	v_pk_fma_f32 v[28:29], v[28:29], v[106:107], v[80:81]
	v_lshlrev_b32_e32 v80, 16, v25
	v_lshlrev_b32_e32 v116, 16, v24
	v_and_b32_e32 v81, 0xffff0000, v25
	v_and_b32_e32 v117, 0xffff0000, v24
	v_cndmask_b32_e64 v107, 0, v99, s[42:43]
	v_cndmask_b32_e64 v106, 0, v98, s[42:43]
	v_cndmask_b32_e64 v115, 0, v97, s[42:43]
	v_cndmask_b32_e64 v114, 0, v96, s[42:43]
	v_pk_fma_f32 v[24:25], v[114:115], v[116:117], v[28:29]
; __device__ __forceinline__ void ld8bf(const bf16_t* p, float (&o)[8]) { unpack8(*(const u32x4*)p, o); }
; __device__ __forceinline__ bf16x8 pack_frag(const float (&v)[8]) { return __builtin_bit_cast(bf16x8, pack8(v)); }
; __device__ __forceinline__ void w_lru_m1(const Args& a, int l, unsigned char* ws, const bf16_t* proj, bf16_t* y, LAS unsigned char* wl, int b, int ck_, int h, int lane) {
;     ...
;         for (int tb = 0; tb < 4; ++tb) { const int tok = 16 * tb + lo, t = 64 * ck_ + tok; float s[8];
; #pragma unroll
;             for (int j = 0; j < 8; ++j) s[j] = bs[j];
; #pragma unroll
;             for (int k = 0; k < 4; ++k) { const int tt = t - 3 + k; float x[8];
;                 ld8bf(proj + (size_t)(b * SEQ + (tt >= 0 ? tt : 0)) * NIN + C_LX + ch0, x);
; #pragma unroll
;                 for (int j = 0; j < 8; ++j) s[j] += (tt >= 0 ? w[k][j] : 0.f) * x[j]; }
;             Xf[tb][kk] = pack_frag(s);
; #pragma unroll
;             for (int j = 0; j < 8; ++j) xcf[tok * 65 + 32 * kk + 8 * fq + j] = s[j]; }
	v_pk_fma_f32 v[28:29], v[106:107], v[80:81], v[32:33]
	v_cvt_pk_bf16_f32 v32, v24, v25
	v_cvt_pk_bf16_f32 v33, v28, v29
	ds_write2_b32 v121, v28, v29 offset0:34 offset1:35
	ds_write2_b32 v121, v24, v25 offset0:32 offset1:33
	v_lshlrev_b32_e32 v24, 16, v82
	v_lshlrev_b32_e32 v28, 16, v83
	v_and_b32_e32 v25, 0xffff0000, v82
	v_and_b32_e32 v29, 0xffff0000, v83
	v_cndmask_b32_e64 v81, 0, v69, s[50:51]
	v_cndmask_b32_e64 v80, 0, v68, s[50:51]
	v_cndmask_b32_e64 v83, 0, v71, s[50:51]
	v_cndmask_b32_e64 v82, 0, v70, s[50:51]
	v_pk_fma_f32 v[28:29], v[82:83], v[28:29], v[42:43]
	v_pk_fma_f32 v[24:25], v[80:81], v[24:25], v[40:41]
	v_lshlrev_b32_e32 v80, 16, v35
	v_lshlrev_b32_e32 v82, 16, v34
	v_and_b32_e32 v81, 0xffff0000, v35
	v_and_b32_e32 v83, 0xffff0000, v34
	v_cndmask_b32_e64 v35, 0, v39, s[48:49]
	v_cndmask_b32_e64 v34, 0, v38, s[48:49]
	v_cndmask_b32_e64 v97, 0, v37, s[48:49]
	v_cndmask_b32_e64 v96, 0, v36, s[48:49]
	v_pk_fma_f32 v[24:25], v[96:97], v[82:83], v[24:25]
	v_pk_fma_f32 v[28:29], v[34:35], v[80:81], v[28:29]
	v_lshlrev_b32_e32 v34, 16, v30
	v_lshlrev_b32_e32 v80, 16, v31
	v_and_b32_e32 v35, 0xffff0000, v30
	v_and_b32_e32 v81, 0xffff0000, v31
	v_cndmask_b32_e64 v31, 0, v85, s[44:45]
	v_cndmask_b32_e64 v30, 0, v84, s[44:45]
	v_cndmask_b32_e64 v83, 0, v87, s[44:45]
	v_cndmask_b32_e64 v82, 0, v86, s[44:45]
	v_pk_fma_f32 v[28:29], v[82:83], v[80:81], v[28:29]
	v_pk_fma_f32 v[24:25], v[30:31], v[34:35], v[24:25]
	v_lshlrev_b32_e32 v30, 16, v27
	v_lshlrev_b32_e32 v34, 16, v26
	v_and_b32_e32 v31, 0xffff0000, v27
	v_and_b32_e32 v35, 0xffff0000, v26
	v_cndmask_b32_e64 v117, 0, v149, s[42:43]
	v_cndmask_b32_e64 v116, 0, v148, s[42:43]
	v_cndmask_b32_e64 v119, 0, v147, s[42:43]
	v_cndmask_b32_e64 v118, 0, v146, s[42:43]
	v_pk_fma_f32 v[24:25], v[118:119], v[34:35], v[24:25]
	v_pk_fma_f32 v[26:27], v[116:117], v[30:31], v[28:29]
	v_cvt_pk_bf16_f32 v34, v24, v25
	ds_write2_b32 v121, v26, v27 offset0:38 offset1:39
	ds_write2_b32 v121, v24, v25 offset0:36 offset1:37
	v_mad_i64_i32 v[24:25], s[42:43], v134, s72, v[102:103]
	v_lshl_add_u64 v[24:25], v[24:25], 0, v[104:105]
	v_mad_i64_i32 v[28:29], s[42:43], v135, s72, v[102:103]
	v_cvt_pk_bf16_f32 v35, v26, v27
	flat_load_dwordx4 v[24:27], v[24:25]
	v_lshl_add_u64 v[28:29], v[28:29], 0, v[104:105]
	v_mad_i64_i32 v[80:81], s[42:43], v142, s72, v[102:103]
	flat_load_dwordx4 v[28:31], v[28:29]
	v_lshl_add_u64 v[80:81], v[80:81], 0, v[104:105]
	v_mad_i64_i32 v[96:97], s[42:43], v143, s72, v[102:103]
	flat_load_dwordx4 v[80:83], v[80:81]
	v_lshl_add_u64 v[96:97], v[96:97], 0, v[104:105]
	flat_load_dwordx4 v[96:99], v[96:97]
	v_cndmask_b32_e64 v147, 0, v79, s[62:63]
	v_cndmask_b32_e64 v146, 0, v78, s[62:63]
	v_cndmask_b32_e64 v149, 0, v21, s[60:61]
	v_cndmask_b32_e64 v148, 0, v20, s[60:61]
	s_add_i32 s48, s20, s27
	s_lshl_b32 s20, s91, 7
	s_add_u32 s44, s10, s20
	s_addc_u32 s45, s11, 0
	s_waitcnt vmcnt(0) lgkmcnt(0)
	v_lshlrev_b32_e32 v134, 16, v24
	v_lshlrev_b32_e32 v142, 16, v25
	v_and_b32_e32 v135, 0xffff0000, v24
	v_and_b32_e32 v143, 0xffff0000, v25
	v_cndmask_b32_e64 v25, 0, v77, s[62:63]
	v_cndmask_b32_e64 v24, 0, v76, s[62:63]
	v_pk_fma_f32 v[142:143], v[146:147], v[142:143], v[74:75]
	v_pk_fma_f32 v[24:25], v[24:25], v[134:135], v[72:73]
	v_lshlrev_b32_e32 v134, 16, v29
	v_lshlrev_b32_e32 v146, 16, v28
	v_and_b32_e32 v135, 0xffff0000, v29
	v_and_b32_e32 v147, 0xffff0000, v28
	v_cndmask_b32_e64 v29, 0, v23, s[60:61]
	v_cndmask_b32_e64 v28, 0, v22, s[60:61]
	v_pk_fma_f32 v[24:25], v[148:149], v[146:147], v[24:25]
	v_pk_fma_f32 v[28:29], v[28:29], v[134:135], v[142:143]
	v_lshlrev_b32_e32 v134, 16, v80
	v_lshlrev_b32_e32 v142, 16, v81
	v_and_b32_e32 v135, 0xffff0000, v80
	v_and_b32_e32 v143, 0xffff0000, v81
	v_cndmask_b32_e64 v81, 0, v93, s[58:59]
	v_cndmask_b32_e64 v80, 0, v92, s[58:59]
	v_cndmask_b32_e64 v147, 0, v95, s[58:59]
	v_cndmask_b32_e64 v146, 0, v94, s[58:59]
	v_pk_fma_f32 v[28:29], v[146:147], v[142:143], v[28:29]
	v_pk_fma_f32 v[24:25], v[80:81], v[134:135], v[24:25]
	v_lshlrev_b32_e32 v80, 16, v97
	v_lshlrev_b32_e32 v134, 16, v96
	v_and_b32_e32 v81, 0xffff0000, v97
	v_and_b32_e32 v135, 0xffff0000, v96
	v_pk_fma_f32 v[24:25], v[114:115], v[134:135], v[24:25]
	v_pk_fma_f32 v[80:81], v[106:107], v[80:81], v[28:29]
	v_cvt_pk_bf16_f32 v28, v24, v25
	v_cvt_pk_bf16_f32 v29, v80, v81
	ds_write2_b32 v125, v80, v81 offset0:34 offset1:35
	ds_write2_b32 v125, v24, v25 offset0:32 offset1:33
	v_lshlrev_b32_e32 v24, 16, v26
	v_lshlrev_b32_e32 v80, 16, v27
	v_and_b32_e32 v25, 0xffff0000, v26
	v_and_b32_e32 v81, 0xffff0000, v27
	v_cndmask_b32_e64 v27, 0, v69, s[62:63]
	v_cndmask_b32_e64 v26, 0, v68, s[62:63]
	v_cndmask_b32_e64 v97, 0, v71, s[62:63]
	v_cndmask_b32_e64 v96, 0, v70, s[62:63]
	v_pk_fma_f32 v[80:81], v[96:97], v[80:81], v[42:43]
	v_pk_fma_f32 v[24:25], v[26:27], v[24:25], v[40:41]
	v_lshlrev_b32_e32 v26, 16, v31
	v_lshlrev_b32_e32 v96, 16, v30
	v_and_b32_e32 v27, 0xffff0000, v31
	v_and_b32_e32 v97, 0xffff0000, v30
	v_cndmask_b32_e64 v31, 0, v39, s[60:61]
	v_cndmask_b32_e64 v30, 0, v38, s[60:61]
	v_cndmask_b32_e64 v135, 0, v37, s[60:61]
	v_cndmask_b32_e64 v134, 0, v36, s[60:61]
	v_pk_fma_f32 v[24:25], v[134:135], v[96:97], v[24:25]
	v_pk_fma_f32 v[26:27], v[30:31], v[26:27], v[80:81]
	v_lshlrev_b32_e32 v30, 16, v82
	v_lshlrev_b32_e32 v80, 16, v83
	v_and_b32_e32 v31, 0xffff0000, v82
	v_and_b32_e32 v81, 0xffff0000, v83
	v_cndmask_b32_e64 v83, 0, v85, s[58:59]
	v_cndmask_b32_e64 v82, 0, v84, s[58:59]
	v_cndmask_b32_e64 v97, 0, v87, s[58:59]
	v_cndmask_b32_e64 v96, 0, v86, s[58:59]
	v_pk_fma_f32 v[26:27], v[96:97], v[80:81], v[26:27]
	v_pk_fma_f32 v[24:25], v[82:83], v[30:31], v[24:25]
	v_lshlrev_b32_e32 v30, 16, v99
	v_lshlrev_b32_e32 v80, 16, v98
	v_and_b32_e32 v31, 0xffff0000, v99
	v_and_b32_e32 v81, 0xffff0000, v98
	v_pk_fma_f32 v[24:25], v[118:119], v[80:81], v[24:25]
	v_pk_fma_f32 v[26:27], v[116:117], v[30:31], v[26:27]
	v_cvt_pk_bf16_f32 v30, v24, v25
	ds_write2_b32 v125, v26, v27 offset0:38 offset1:39
	ds_write2_b32 v125, v24, v25 offset0:36 offset1:37
	v_mad_i64_i32 v[24:25], s[42:43], v130, s72, v[102:103]
	v_lshl_add_u64 v[24:25], v[24:25], 0, v[104:105]
	v_mad_i64_i32 v[80:81], s[42:43], v131, s72, v[102:103]
	v_cvt_pk_bf16_f32 v31, v26, v27
	flat_load_dwordx4 v[24:27], v[24:25]
	v_lshl_add_u64 v[80:81], v[80:81], 0, v[104:105]
	v_mad_i64_i32 v[96:97], s[42:43], v132, s72, v[102:103]
	flat_load_dwordx4 v[80:83], v[80:81]
	v_lshl_add_u64 v[96:97], v[96:97], 0, v[104:105]
	v_mad_i64_i32 v[130:131], s[42:43], v133, s72, v[102:103]
	flat_load_dwordx4 v[96:99], v[96:97]
	v_lshl_add_u64 v[130:131], v[130:131], 0, v[104:105]
	flat_load_dwordx4 v[130:133], v[130:131]
	v_cndmask_b32_e64 v147, 0, v79, s[56:57]
	v_cndmask_b32_e64 v146, 0, v78, s[56:57]
	v_cndmask_b32_e64 v149, 0, v21, s[54:55]
	v_cndmask_b32_e64 v148, 0, v20, s[54:55]
	v_cndmask_b32_e64 v79, 0, v79, s[46:47]
	v_cndmask_b32_e64 v78, 0, v78, s[46:47]
	v_cndmask_b32_e64 v21, 0, v21, s[40:41]
	v_cndmask_b32_e64 v20, 0, v20, s[40:41]
	s_waitcnt vmcnt(0) lgkmcnt(0)
; __device__ __forceinline__ void ld8bf(const bf16_t* p, float (&o)[8]) { unpack8(*(const u32x4*)p, o); }
; __device__ __forceinline__ bf16x8 pack_frag(const float (&v)[8]) { return __builtin_bit_cast(bf16x8, pack8(v)); }
; __device__ __forceinline__ void w_lru_m1(const Args& a, int l, unsigned char* ws, const bf16_t* proj, bf16_t* y, LAS unsigned char* wl, int b, int ck_, int h, int lane) {
;     ...
;         for (int tb = 0; tb < 4; ++tb) { const int tok = 16 * tb + lo, t = 64 * ck_ + tok; float s[8];
; #pragma unroll
;             for (int j = 0; j < 8; ++j) s[j] = bs[j];
; #pragma unroll
;             for (int k = 0; k < 4; ++k) { const int tt = t - 3 + k; float x[8];
;                 ld8bf(proj + (size_t)(b * SEQ + (tt >= 0 ? tt : 0)) * NIN + C_LX + ch0, x);
; #pragma unroll
;                 for (int j = 0; j < 8; ++j) s[j] += (tt >= 0 ? w[k][j] : 0.f) * x[j]; }
;             Xf[tb][kk] = pack_frag(s);
; #pragma unroll
;             for (int j = 0; j < 8; ++j) xcf[tok * 65 + 32 * kk + 8 * fq + j] = s[j]; }
	v_lshlrev_b32_e32 v134, 16, v24
	v_lshlrev_b32_e32 v142, 16, v25
	v_and_b32_e32 v135, 0xffff0000, v24
	v_and_b32_e32 v143, 0xffff0000, v25
	v_cndmask_b32_e64 v25, 0, v77, s[56:57]
	v_cndmask_b32_e64 v24, 0, v76, s[56:57]
	v_pk_fma_f32 v[142:143], v[146:147], v[142:143], v[74:75]
	v_pk_fma_f32 v[24:25], v[24:25], v[134:135], v[72:73]
	v_lshlrev_b32_e32 v134, 16, v81
	v_lshlrev_b32_e32 v146, 16, v80
	v_and_b32_e32 v135, 0xffff0000, v81
	v_and_b32_e32 v147, 0xffff0000, v80
	v_cndmask_b32_e64 v81, 0, v23, s[54:55]
	v_cndmask_b32_e64 v80, 0, v22, s[54:55]
	v_pk_fma_f32 v[24:25], v[148:149], v[146:147], v[24:25]
	v_pk_fma_f32 v[80:81], v[80:81], v[134:135], v[142:143]
	v_lshlrev_b32_e32 v134, 16, v96
	v_lshlrev_b32_e32 v142, 16, v97
	v_and_b32_e32 v135, 0xffff0000, v96
	v_and_b32_e32 v143, 0xffff0000, v97
	v_cndmask_b32_e64 v97, 0, v93, s[52:53]
	v_cndmask_b32_e64 v96, 0, v92, s[52:53]
	v_cndmask_b32_e64 v147, 0, v95, s[52:53]
	v_cndmask_b32_e64 v146, 0, v94, s[52:53]
	v_pk_fma_f32 v[80:81], v[146:147], v[142:143], v[80:81]
	v_pk_fma_f32 v[24:25], v[96:97], v[134:135], v[24:25]
	v_lshlrev_b32_e32 v96, 16, v131
	v_lshlrev_b32_e32 v134, 16, v130
	v_and_b32_e32 v97, 0xffff0000, v131
	v_and_b32_e32 v135, 0xffff0000, v130
	v_pk_fma_f32 v[130:131], v[114:115], v[134:135], v[24:25]
	v_pk_fma_f32 v[80:81], v[106:107], v[96:97], v[80:81]
	v_cvt_pk_bf16_f32 v24, v130, v131
	v_cvt_pk_bf16_f32 v25, v80, v81
	ds_write2_b32 v124, v80, v81 offset0:34 offset1:35
	ds_write2_b32 v124, v130, v131 offset0:32 offset1:33
	v_lshlrev_b32_e32 v80, 16, v26
	v_lshlrev_b32_e32 v96, 16, v27
	v_and_b32_e32 v81, 0xffff0000, v26
	v_and_b32_e32 v97, 0xffff0000, v27
	v_cndmask_b32_e64 v27, 0, v69, s[56:57]
	v_cndmask_b32_e64 v26, 0, v68, s[56:57]
	v_cndmask_b32_e64 v131, 0, v71, s[56:57]
	v_cndmask_b32_e64 v130, 0, v70, s[56:57]
	v_pk_fma_f32 v[96:97], v[130:131], v[96:97], v[42:43]
	v_pk_fma_f32 v[26:27], v[26:27], v[80:81], v[40:41]
	v_lshlrev_b32_e32 v80, 16, v83
	v_lshlrev_b32_e32 v130, 16, v82
	v_and_b32_e32 v81, 0xffff0000, v83
	v_and_b32_e32 v131, 0xffff0000, v82
	v_cndmask_b32_e64 v83, 0, v39, s[54:55]
	v_cndmask_b32_e64 v82, 0, v38, s[54:55]
	v_cndmask_b32_e64 v135, 0, v37, s[54:55]
	v_cndmask_b32_e64 v134, 0, v36, s[54:55]
	v_pk_fma_f32 v[26:27], v[134:135], v[130:131], v[26:27]
	v_pk_fma_f32 v[80:81], v[82:83], v[80:81], v[96:97]
	v_lshlrev_b32_e32 v82, 16, v98
	v_lshlrev_b32_e32 v96, 16, v99
	v_and_b32_e32 v83, 0xffff0000, v98
	v_and_b32_e32 v97, 0xffff0000, v99
	v_cndmask_b32_e64 v99, 0, v85, s[52:53]
	v_cndmask_b32_e64 v98, 0, v84, s[52:53]
	v_cndmask_b32_e64 v131, 0, v87, s[52:53]
	v_cndmask_b32_e64 v130, 0, v86, s[52:53]
	v_pk_fma_f32 v[80:81], v[130:131], v[96:97], v[80:81]
	v_pk_fma_f32 v[26:27], v[98:99], v[82:83], v[26:27]
	v_lshlrev_b32_e32 v82, 16, v133
	v_and_b32_e32 v83, 0xffff0000, v133
	v_lshlrev_b32_e32 v96, 16, v132
	v_and_b32_e32 v97, 0xffff0000, v132
	v_pk_fma_f32 v[80:81], v[116:117], v[82:83], v[80:81]
	v_pk_fma_f32 v[96:97], v[118:119], v[96:97], v[26:27]
	v_cvt_pk_bf16_f32 v27, v80, v81
	ds_write2_b32 v124, v80, v81 offset0:38 offset1:39
	ds_write2_b32 v124, v96, v97 offset0:36 offset1:37
	v_mad_i64_i32 v[80:81], s[42:43], v126, s72, v[102:103]
	v_lshl_add_u64 v[80:81], v[80:81], 0, v[104:105]
	flat_load_dwordx4 v[130:133], v[80:81]
	v_mad_i64_i32 v[80:81], s[42:43], v127, s72, v[102:103]
	v_lshl_add_u64 v[80:81], v[80:81], 0, v[104:105]
	flat_load_dwordx4 v[124:127], v[80:81]
	v_mad_i64_i32 v[80:81], s[42:43], v128, s72, v[102:103]
	v_lshl_add_u64 v[80:81], v[80:81], 0, v[104:105]
	v_cvt_pk_bf16_f32 v26, v96, v97
	flat_load_dwordx4 v[96:99], v[80:81]
	v_mad_i64_i32 v[80:81], s[42:43], v129, s72, v[102:103]
	v_lshl_add_u64 v[80:81], v[80:81], 0, v[104:105]
	flat_load_dwordx4 v[80:83], v[80:81]
	v_cndmask_b32_e64 v77, 0, v77, s[46:47]
	v_cndmask_b32_e64 v76, 0, v76, s[46:47]
	v_cndmask_b32_e64 v23, 0, v23, s[40:41]
	v_cndmask_b32_e64 v22, 0, v22, s[40:41]
	v_cndmask_b32_e64 v69, 0, v69, s[46:47]
	v_cndmask_b32_e64 v68, 0, v68, s[46:47]
	v_cndmask_b32_e64 v71, 0, v71, s[46:47]
	v_cndmask_b32_e64 v70, 0, v70, s[46:47]
	v_cndmask_b32_e64 v39, 0, v39, s[40:41]
	v_cndmask_b32_e64 v38, 0, v38, s[40:41]
	v_cndmask_b32_e64 v37, 0, v37, s[40:41]
	v_cndmask_b32_e64 v36, 0, v36, s[40:41]
	s_add_u32 s46, s71, s20
	s_addc_u32 s47, s64, 0
	s_ashr_i32 s91, s90, 31
	s_lshl_b64 s[42:43], s[90:91], 9
	s_or_b32 s42, s42, s21
	s_waitcnt vmcnt(0) lgkmcnt(0)
; __device__ __forceinline__ float sigmoidf_(float x) { return __builtin_amdgcn_rcpf(1.0f + __expf(-x)); }
; #define WAVE_LDS_FENCE() asm volatile("s_waitcnt lgkmcnt(0)" ::: "memory")
; __device__ __forceinline__ void w_lru_m1(const Args& a, int l, unsigned char* ws, const bf16_t* proj, bf16_t* y, LAS unsigned char* wl, int b, int ck_, int h, int lane) {
;     ...
; #pragma unroll
;                 for (int j = 0; j < 8; ++j) s[j] += (tt >= 0 ? w[k][j] : 0.f) * x[j]; }
;             Xf[tb][kk] = pack_frag(s);
; #pragma unroll
;             for (int j = 0; j < 8; ++j) xcf[tok * 65 + 32 * kk + 8 * fq + j] = s[j]; }
;     }
;     WAVE_LDS_FENCE();
; #pragma unroll
;     for (int jb = 0; jb < 4; ++jb) {
;         bf16x8 WaF[2], WxF[2]; f32x4 pba, pbx, plam;
; #pragma unroll
;         for (int kk = 0; kk < 2; ++kk) { WaF[kk] = nWa[kk]; WxF[kk] = nWx[kk]; }
;         pba = nba; pbx = nbx; plam = nlam;
;         if (jb < 3) {
; #pragma unroll
;             for (int kk = 0; kk < 2; ++kk) { nWa[kk] = *(const bf16x8*)(waT + (16 * (jb + 1) + lo) * 64 + 32 * kk + 8 * fq); nWx[kk] = *(const bf16x8*)(wxT + (16 * (jb + 1) + lo) * 64 + 32 * kk + 8 * fq); }
;             nba = *(const f32x4*)(ba + 16 * (jb + 1) + 4 * fq); nbx = *(const f32x4*)(bx + 16 * (jb + 1) + 4 * fq); nlam = *(const f32x4*)(lam + 16 * (jb + 1) + 4 * fq);
;         }
;         const int j0 = 16 * jb + 4 * fq;
;         float bav[4], bxv[4], sp[4], hc[4], Pc[4];
; #pragma unroll
;         for (int r = 0; r < 4; ++r) { bav[r] = pba[r]; bxv[r] = pbx[r]; sp[r] = log1pf(__expf(-plam[r])); hc[r] = 0.f; Pc[r] = 1.f; }
; #pragma unroll
;         for (int tb = 0; tb < 4; ++tb) { const int tok = 16 * tb + lo;
;             f32x4 ga = {0.f, 0.f, 0.f, 0.f}, gx = {0.f, 0.f, 0.f, 0.f};
; #pragma unroll
;             for (int kk = 0; kk < 2; ++kk) { ga = __builtin_amdgcn_mfma_f32_16x16x32_bf16(WaF[kk], Xf[tb][kk], ga, 0, 0, 0); gx = __builtin_amdgcn_mfma_f32_16x16x32_bf16(WxF[kk], Xf[tb][kk], gx, 0, 0, 0); }
;             float hv[4], pv[4];
; #pragma unroll
;             for (int r = 0; r < 4; ++r) {
;                 const float rg = sigmoidf_(ga[r] + bav[r]), ig = sigmoidf_(gx[r] + bxv[r]);
;                 const float la = -8.0f * rg * sp[r]; float A = __expf(la);
;                 float U = __builtin_amdgcn_sqrtf(1.0f - A * A) * (ig * xcf[tok * 65 + j0 + r]);
	v_lshlrev_b32_e32 v102, 16, v130
	v_lshlrev_b32_e32 v104, 16, v131
	v_and_b32_e32 v103, 0xffff0000, v130
	v_and_b32_e32 v105, 0xffff0000, v131
	v_pk_fma_f32 v[74:75], v[78:79], v[104:105], v[74:75]
	v_pk_fma_f32 v[72:73], v[76:77], v[102:103], v[72:73]
	v_lshlrev_b32_e32 v76, 16, v125
	v_lshlrev_b32_e32 v78, 16, v124
	v_and_b32_e32 v77, 0xffff0000, v125
	v_and_b32_e32 v79, 0xffff0000, v124
	v_pk_fma_f32 v[20:21], v[20:21], v[78:79], v[72:73]
	v_pk_fma_f32 v[22:23], v[22:23], v[76:77], v[74:75]
	v_lshlrev_b32_e32 v72, 16, v96
	v_lshlrev_b32_e32 v74, 16, v97
	v_and_b32_e32 v73, 0xffff0000, v96
	v_and_b32_e32 v75, 0xffff0000, v97
	v_cndmask_b32_e32 v77, 0, v93, vcc
	v_cndmask_b32_e32 v76, 0, v92, vcc
	v_cndmask_b32_e32 v79, 0, v95, vcc
	v_cndmask_b32_e32 v78, 0, v94, vcc
	v_pk_fma_f32 v[22:23], v[78:79], v[74:75], v[22:23]
	v_pk_fma_f32 v[20:21], v[76:77], v[72:73], v[20:21]
	v_lshlrev_b32_e32 v72, 16, v81
	v_and_b32_e32 v73, 0xffff0000, v81
	v_lshlrev_b32_e32 v74, 16, v80
	v_and_b32_e32 v75, 0xffff0000, v80
	v_pk_fma_f32 v[22:23], v[106:107], v[72:73], v[22:23]
	v_pk_fma_f32 v[74:75], v[114:115], v[74:75], v[20:21]
	v_cvt_pk_bf16_f32 v21, v22, v23
	ds_write2_b32 v120, v22, v23 offset0:34 offset1:35
	ds_write2_b32 v120, v74, v75 offset0:32 offset1:33
	v_lshlrev_b32_e32 v22, 16, v132
	v_lshlrev_b32_e32 v72, 16, v133
	v_and_b32_e32 v23, 0xffff0000, v132
	v_and_b32_e32 v73, 0xffff0000, v133
	v_pk_fma_f32 v[42:43], v[70:71], v[72:73], v[42:43]
	v_pk_fma_f32 v[22:23], v[68:69], v[22:23], v[40:41]
	v_lshlrev_b32_e32 v40, 16, v127
	v_lshlrev_b32_e32 v68, 16, v126
	v_and_b32_e32 v41, 0xffff0000, v127
	v_and_b32_e32 v69, 0xffff0000, v126
	v_pk_fma_f32 v[22:23], v[36:37], v[68:69], v[22:23]
	v_pk_fma_f32 v[36:37], v[38:39], v[40:41], v[42:43]
	v_lshlrev_b32_e32 v38, 16, v98
	v_lshlrev_b32_e32 v40, 16, v99
	v_and_b32_e32 v39, 0xffff0000, v98
	v_and_b32_e32 v41, 0xffff0000, v99
	v_cndmask_b32_e32 v43, 0, v85, vcc
	v_cndmask_b32_e32 v42, 0, v84, vcc
	v_cndmask_b32_e32 v69, 0, v87, vcc
	v_cndmask_b32_e32 v68, 0, v86, vcc
	v_pk_fma_f32 v[36:37], v[68:69], v[40:41], v[36:37]
	v_pk_fma_f32 v[22:23], v[42:43], v[38:39], v[22:23]
	v_lshlrev_b32_e32 v38, 16, v83
	v_and_b32_e32 v39, 0xffff0000, v83
	v_lshlrev_b32_e32 v40, 16, v82
	v_and_b32_e32 v41, 0xffff0000, v82
	v_pk_fma_f32 v[36:37], v[116:117], v[38:39], v[36:37]
	v_pk_fma_f32 v[40:41], v[118:119], v[40:41], v[22:23]
	v_cvt_pk_bf16_f32 v23, v36, v37
	ds_write2_b32 v120, v36, v37 offset0:38 offset1:39
	ds_write2_b32 v120, v40, v41 offset0:36 offset1:37
	v_lshlrev_b32_e32 v36, 2, v122
	v_lshl_add_u64 v[118:119], s[92:93], 0, v[100:101]
	v_lshl_add_u64 v[120:121], s[34:35], 0, v[100:101]
	v_and_b32_e32 v143, 0xc0, v36
	v_lshl_add_u64 v[36:37], v[118:119], 0, v[2:3]
	v_lshl_add_u64 v[38:39], v[120:121], 0, v[2:3]
	s_nop 7
	s_waitcnt lgkmcnt(0)
	v_cvt_pk_bf16_f32 v20, v74, v75
	v_cvt_pk_bf16_f32 v22, v40, v41
	s_nop 7
	global_load_dwordx4 v[68:71], v[36:37], off offset:2048
	global_load_dwordx4 v[72:75], v[38:39], off offset:2048
	global_load_dwordx4 v[76:79], v[36:37], off offset:2112
	global_load_dwordx4 v[80:83], v[38:39], off offset:2112
	global_load_dwordx4 v[40:43], v[108:109], off offset:64
	s_nop 0
	global_load_dwordx4 v[36:39], v[110:111], off offset:64
	global_load_dwordx4 v[84:87], v[112:113], off offset:64
	s_nop 7
	v_mov_b32_e32 v104, 1.0
	s_nop 7
	v_mov_b32_e32 v105, 1.0
	s_nop 7
	v_cmp_eq_u32_e32 vcc, 0, v136
	s_nop 0
	s_nop 7
	s_nop 1
	s_nop 7
	s_nop 1
	s_nop 7
	v_mov_b32_e32 v145, v88
	s_nop 7
	s_nop 0
	s_nop 7
	s_nop 0
	s_nop 7
	s_nop 0
	s_nop 7
	s_nop 0
	s_nop 7
	s_nop 0
	s_nop 7
	s_nop 0
	s_nop 7
	s_nop 1
	s_nop 7
	s_nop 1
	s_nop 7
	s_nop 1
	s_nop 7
	v_mov_b32_e32 v147, v89
	s_nop 7
	s_nop 0
	s_nop 7
	s_nop 0
	s_nop 7
	v_mov_b32_e32 v103, 1.0
	s_nop 7
	s_nop 0
	s_nop 7
	s_nop 1
	s_nop 7
	s_nop 1
	s_nop 7
	s_nop 1
	s_nop 7
	v_mov_b32_e32 v2, v90
	s_nop 7
	s_nop 0
	s_nop 7
	s_nop 0
	s_nop 7
	s_nop 0
	s_nop 7
	s_nop 0
	s_nop 7
	v_mov_b32_e32 v100, 1.0
	s_nop 7
	v_mov_b32_e32 v101, 1.0
	s_nop 7
	v_mfma_f32_16x16x32_bf16 v[92:95], v[56:59], v[16:19], 0
	v_mov_b32_e32 v98, 1.0
	s_nop 7
	v_mfma_f32_16x16x32_bf16 v[92:95], v[64:67], v[32:35], v[92:95]
	v_mov_b32_e32 v99, 1.0
	s_nop 7
	s_nop 1
	s_nop 7
	v_mov_b32_e32 v146, v91
	v_and_b32_e32 v88, -16, v122
	v_add_u32_e32 v142, s6, v88
	v_lshlrev_b64 v[88:89], 1, v[0:1]
	v_lshl_add_u64 v[114:115], s[44:45], 0, v[88:89]
	v_lshl_add_u64 v[116:117], s[46:47], 0, v[88:89]
	v_mfma_f32_16x16x32_bf16 v[88:91], v[52:55], v[16:19], 0
	v_mad_u32_u24 v122, v136, s76, v142
	ds_read2_b32 v[124:125], v122 offset1:1
	ds_read2_b32 v[128:129], v122 offset0:2 offset1:3
	v_mfma_f32_16x16x32_bf16 v[88:91], v[60:63], v[32:35], v[88:91]
	v_mov_b32_e32 v102, 1.0
	v_add_u32_e32 v148, v142, v123
	v_add_u32_e32 v150, v142, v141
	s_nop 4
	v_add_f32_e32 v88, v48, v88
	v_add_f32_e32 v89, v49, v89
	v_mul_f32_e32 v88, 0xbfb8aa3b, v88
	v_mul_f32_e32 v89, 0xbfb8aa3b, v89
	v_exp_f32_e32 v88, v88
	v_exp_f32_e32 v89, v89
	v_add_f32_e32 v90, v50, v90
	v_mul_f32_e32 v90, 0xbfb8aa3b, v90
	v_add_f32_e32 v88, 1.0, v88
	v_add_f32_e32 v89, 1.0, v89
	v_rcp_f32_e32 v96, v88
	v_rcp_f32_e32 v97, v89
	v_add_f32_e32 v88, v44, v92
	v_add_f32_e32 v89, v45, v93
	v_mul_f32_e32 v92, 0xc1000000, v96
	v_mul_f32_e32 v93, 0xc1000000, v97
	v_mul_f32_e32 v88, 0xbfb8aa3b, v88
	v_mul_f32_e32 v92, v145, v92
	v_mul_f32_e32 v89, 0xbfb8aa3b, v89
	v_mul_f32_e32 v93, v147, v93
	v_exp_f32_e32 v88, v88
	v_mul_f32_e32 v92, 0x3fb8aa3b, v92
	v_exp_f32_e32 v89, v89
	v_mul_f32_e32 v93, 0x3fb8aa3b, v93
	v_exp_f32_e32 v92, v92
	v_exp_f32_e32 v93, v93
	v_add_f32_e32 v88, 1.0, v88
	v_add_f32_e32 v89, 1.0, v89
	v_rcp_f32_e32 v88, v88
	v_fma_f32 v96, -v92, v92, 1.0
	v_rcp_f32_e32 v89, v89
	v_fma_f32 v97, -v93, v93, 1.0
	v_sqrt_f32_e32 v96, v96
	v_sqrt_f32_e32 v97, v97
	s_waitcnt lgkmcnt(0)
; __device__ __forceinline__ unsigned pk2(float lo, float hi) { const f32x2_t v = {lo, hi}; const bf16x2_t b = __builtin_convertvector(v, bf16x2_t); return __builtin_bit_cast(unsigned, b); }
; __device__ __forceinline__ float sigmoidf_(float x) { return __builtin_amdgcn_rcpf(1.0f + __expf(-x)); }
; __device__ __forceinline__ float bcast15(float v, int lane) { return bperm_f((lane & 48) | 15, v); }
; __device__ __forceinline__ void w_lru_m1(const Args& a, int l, unsigned char* ws, const bf16_t* proj, bf16_t* y, LAS unsigned char* wl, int b, int ck_, int h, int lane) {
;     ...
; #pragma unroll
;         for (int tb = 0; tb < 4; ++tb) { const int tok = 16 * tb + lo;
;             f32x4 ga = {0.f, 0.f, 0.f, 0.f}, gx = {0.f, 0.f, 0.f, 0.f};
; #pragma unroll
;             for (int kk = 0; kk < 2; ++kk) { ga = __builtin_amdgcn_mfma_f32_16x16x32_bf16(WaF[kk], Xf[tb][kk], ga, 0, 0, 0); gx = __builtin_amdgcn_mfma_f32_16x16x32_bf16(WxF[kk], Xf[tb][kk], gx, 0, 0, 0); }
;             float hv[4], pv[4];
; #pragma unroll
;             for (int r = 0; r < 4; ++r) {
;                 const float rg = sigmoidf_(ga[r] + bav[r]), ig = sigmoidf_(gx[r] + bxv[r]);
;                 const float la = -8.0f * rg * sp[r]; float A = __expf(la);
;                 float U = __builtin_amdgcn_sqrtf(1.0f - A * A) * (ig * xcf[tok * 65 + j0 + r]);
;                 { const float As = dpp_shr1<1>(A), Us = dpp_shr0<1>(U); U = A * Us + U; A = A * As; }
;                 { const float As = dpp_shr1<2>(A), Us = dpp_shr0<2>(U); U = A * Us + U; A = A * As; }
;                 { const float As = dpp_shr1<4>(A), Us = dpp_shr0<4>(U); U = A * Us + U; A = A * As; }
;                 { const float As = dpp_shr1<8>(A), Us = dpp_shr0<8>(U); U = A * Us + U; A = A * As; }
;                 const float hh = U + A * hc[r], PP = A * Pc[r];
;                 hc[r] = bcast15(hh, lane); Pc[r] = bcast15(PP, lane); hv[r] = hh; pv[r] = PP; }
;             *(unsigned long long*)(y + (size_t)(row0 + tok) * DM + 64 * h + j0) = (unsigned long long)pk2(hv[0], hv[1]) | ((unsigned long long)pk2(hv[2], hv[3]) << 32);
;             *(unsigned long long*)((bf16_t*)(ws + WS_P) + (size_t)(row0 + tok) * 512 + 64 * h + j0) = (unsigned long long)pk2(pv[0], pv[1]) | ((unsigned long long)pk2(pv[2], pv[3]) << 32);
;         }
	v_pk_mul_f32 v[88:89], v[124:125], v[88:89]
	v_mov_b32_dpp v98, v92 row_shr:1 row_mask:0xf bank_mask:0xf
	v_mov_b32_dpp v99, v93 row_shr:1 row_mask:0xf bank_mask:0xf
	v_pk_mul_f32 v[88:89], v[88:89], v[96:97]
	v_pk_mul_f32 v[98:99], v[92:93], v[98:99]
	v_exp_f32_e32 v90, v90
	v_mov_b32_dpp v96, v88 row_shr:1 row_mask:0xf bank_mask:0xf bound_ctrl:1
	v_mov_b32_dpp v97, v89 row_shr:1 row_mask:0xf bank_mask:0xf bound_ctrl:1
	v_pk_fma_f32 v[88:89], v[92:93], v[96:97], v[88:89]
	v_mov_b32_dpp v100, v98 row_shr:2 row_mask:0xf bank_mask:0xf
	v_mov_b32_dpp v101, v99 row_shr:2 row_mask:0xf bank_mask:0xf
	v_mov_b32_dpp v92, v88 row_shr:2 row_mask:0xf bank_mask:0xf bound_ctrl:1
	v_mov_b32_dpp v93, v89 row_shr:2 row_mask:0xf bank_mask:0xf bound_ctrl:1
	v_pk_fma_f32 v[88:89], v[98:99], v[92:93], v[88:89]
	v_pk_mul_f32 v[100:101], v[98:99], v[100:101]
	v_add_f32_e32 v90, 1.0, v90
	v_mov_b32_dpp v92, v88 row_shr:4 row_mask:0xf bank_mask:0xf bound_ctrl:1
	v_mov_b32_dpp v93, v89 row_shr:4 row_mask:0xf bank_mask:0xf bound_ctrl:1
	v_mov_b32_dpp v102, v100 row_shr:4 row_mask:0xf bank_mask:0xf
	v_mov_b32_dpp v103, v101 row_shr:4 row_mask:0xf bank_mask:0xf
	v_pk_fma_f32 v[88:89], v[100:101], v[92:93], v[88:89]
	v_pk_mul_f32 v[102:103], v[100:101], v[102:103]
	v_add_f32_e32 v91, v51, v91
	v_mov_b32_dpp v92, v88 row_shr:8 row_mask:0xf bank_mask:0xf bound_ctrl:1
	v_mov_b32_dpp v93, v89 row_shr:8 row_mask:0xf bank_mask:0xf bound_ctrl:1
	v_pk_fma_f32 v[88:89], v[102:103], v[92:93], v[88:89]
	v_rcp_f32_e32 v92, v90
	v_mul_f32_e32 v91, 0xbfb8aa3b, v91
	v_exp_f32_e32 v91, v91
	v_add_f32_e32 v90, v46, v94
	v_mul_f32_e32 v92, 0xc1000000, v92
	v_mul_f32_e32 v92, v2, v92
	v_mul_f32_e32 v92, 0x3fb8aa3b, v92
	v_exp_f32_e32 v92, v92
	v_add_f32_e32 v91, 1.0, v91
	v_mul_f32_e32 v90, 0xbfb8aa3b, v90
	v_exp_f32_e32 v90, v90
	v_fma_f32 v93, -v92, v92, 1.0
	v_sqrt_f32_e32 v94, v93
	v_rcp_f32_e32 v93, v91
	v_add_f32_e32 v91, v47, v95
	v_mul_f32_e32 v91, 0xbfb8aa3b, v91
	v_exp_f32_e32 v91, v91
	v_mul_f32_e32 v93, 0xc1000000, v93
	v_mul_f32_e32 v93, v146, v93
	v_mul_f32_e32 v93, 0x3fb8aa3b, v93
	v_exp_f32_e32 v93, v93
	v_add_f32_e32 v90, 1.0, v90
	v_add_f32_e32 v91, 1.0, v91
	v_rcp_f32_e32 v90, v90
	v_rcp_f32_e32 v91, v91
	v_fma_f32 v95, -v93, v93, 1.0
	v_sqrt_f32_e32 v95, v95
	v_mov_b32_e32 v96, 1.0
	v_pk_mul_f32 v[90:91], v[90:91], v[128:129]
	v_mov_b32_e32 v97, 1.0
	v_pk_mul_f32 v[90:91], v[94:95], v[90:91]
	v_mov_b32_dpp v96, v92 row_shr:1 row_mask:0xf bank_mask:0xf
	v_mov_b32_dpp v97, v93 row_shr:1 row_mask:0xf bank_mask:0xf
	v_mov_b32_dpp v94, v90 row_shr:1 row_mask:0xf bank_mask:0xf bound_ctrl:1
	v_mov_b32_dpp v95, v91 row_shr:1 row_mask:0xf bank_mask:0xf bound_ctrl:1
	v_pk_mul_f32 v[96:97], v[92:93], v[96:97]
	v_mov_b32_e32 v100, 1.0
	v_mov_b32_e32 v101, 1.0
	v_pk_fma_f32 v[90:91], v[92:93], v[94:95], v[90:91]
	v_mov_b32_dpp v104, v102 row_shr:8 row_mask:0xf bank_mask:0xf
	v_mov_b32_dpp v105, v103 row_shr:8 row_mask:0xf bank_mask:0xf
	v_mov_b32_dpp v100, v96 row_shr:2 row_mask:0xf bank_mask:0xf
	v_mov_b32_dpp v101, v97 row_shr:2 row_mask:0xf bank_mask:0xf
	v_mov_b32_dpp v92, v90 row_shr:2 row_mask:0xf bank_mask:0xf bound_ctrl:1
	v_mov_b32_dpp v93, v91 row_shr:2 row_mask:0xf bank_mask:0xf bound_ctrl:1
	v_pk_mul_f32 v[106:107], v[102:103], v[104:105]
	v_pk_mul_f32 v[100:101], v[96:97], v[100:101]
	v_mov_b32_e32 v102, 1.0
	v_mov_b32_e32 v103, 1.0
	v_pk_fma_f32 v[90:91], v[96:97], v[92:93], v[90:91]
	v_mov_b32_dpp v102, v100 row_shr:4 row_mask:0xf bank_mask:0xf
	v_mov_b32_dpp v103, v101 row_shr:4 row_mask:0xf bank_mask:0xf
	v_mov_b32_dpp v92, v90 row_shr:4 row_mask:0xf bank_mask:0xf bound_ctrl:1
	v_mov_b32_dpp v93, v91 row_shr:4 row_mask:0xf bank_mask:0xf bound_ctrl:1
	v_pk_mul_f32 v[102:103], v[100:101], v[102:103]
	v_mov_b32_e32 v124, 1.0
	v_mov_b32_e32 v125, 1.0
	v_pk_fma_f32 v[90:91], v[100:101], v[92:93], v[90:91]
	v_mov_b32_dpp v124, v102 row_shr:8 row_mask:0xf bank_mask:0xf
	v_mov_b32_dpp v125, v103 row_shr:8 row_mask:0xf bank_mask:0xf
	v_mov_b32_dpp v92, v90 row_shr:8 row_mask:0xf bank_mask:0xf bound_ctrl:1
	v_mov_b32_dpp v93, v91 row_shr:8 row_mask:0xf bank_mask:0xf bound_ctrl:1
	v_pk_mul_f32 v[126:127], v[102:103], v[124:125]
	v_pk_fma_f32 v[90:91], v[102:103], v[92:93], v[90:91]
	v_pk_fma_f32 v[88:89], v[106:107], 0, v[88:89] op_sel_hi:[1,0,1]
	v_pk_fma_f32 v[90:91], v[126:127], 0, v[90:91] op_sel_hi:[1,0,1]
	ds_bpermute_b32 v98, v143, v88 offset:60
	ds_bpermute_b32 v99, v143, v89 offset:60
	ds_bpermute_b32 v96, v143, v90 offset:60
	v_cvt_pk_bf16_f32 v88, v88, v89
	v_cvt_pk_bf16_f32 v89, v90, v91
	v_or_b32_e32 v90, s48, v136
	ds_bpermute_b32 v97, v143, v91 offset:60
	v_ashrrev_i32_e32 v91, 31, v90
	v_lshlrev_b64 v[92:93], 11, v[90:91]
	v_lshl_add_u64 v[100:101], v[114:115], 0, v[92:93]
	v_lshlrev_b64 v[90:91], 10, v[90:91]
	global_store_dwordx2 v[100:101], v[88:89], off
	v_cvt_pk_bf16_f32 v88, v106, v107
	v_cvt_pk_bf16_f32 v89, v126, v127
	v_lshl_add_u64 v[102:103], v[116:117], 0, v[90:91]
	global_store_dwordx2 v[102:103], v[88:89], off
	v_mfma_f32_16x16x32_bf16 v[88:91], v[52:55], v[12:15], 0
	ds_bpermute_b32 v124, v143, v126 offset:60
	ds_bpermute_b32 v125, v143, v127 offset:60
	ds_bpermute_b32 v104, v143, v106 offset:60
	v_mfma_f32_16x16x32_bf16 v[126:129], v[56:59], v[12:15], 0
	ds_bpermute_b32 v105, v143, v107 offset:60
	v_mfma_f32_16x16x32_bf16 v[92:95], v[60:63], v[28:31], v[88:91]
	v_mfma_f32_16x16x32_bf16 v[88:91], v[64:67], v[28:31], v[126:129]
	s_nop 6
	v_add_f32_e32 v92, v48, v92
	v_mul_f32_e32 v92, 0xbfb8aa3b, v92
	v_exp_f32_e32 v92, v92
	v_add_f32_e32 v88, v44, v88
	v_mul_f32_e32 v88, 0xbfb8aa3b, v88
	v_exp_f32_e32 v88, v88
	v_add_f32_e32 v92, 1.0, v92
; __device__ __forceinline__ float sigmoidf_(float x) { return __builtin_amdgcn_rcpf(1.0f + __expf(-x)); }
; __device__ __forceinline__ float bcast15(float v, int lane) { return bperm_f((lane & 48) | 15, v); }
; __device__ __forceinline__ void w_lru_m1(const Args& a, int l, unsigned char* ws, const bf16_t* proj, bf16_t* y, LAS unsigned char* wl, int b, int ck_, int h, int lane) {
;     ...
;         for (int tb = 0; tb < 4; ++tb) { const int tok = 16 * tb + lo;
;             f32x4 ga = {0.f, 0.f, 0.f, 0.f}, gx = {0.f, 0.f, 0.f, 0.f};
; #pragma unroll
;             for (int kk = 0; kk < 2; ++kk) { ga = __builtin_amdgcn_mfma_f32_16x16x32_bf16(WaF[kk], Xf[tb][kk], ga, 0, 0, 0); gx = __builtin_amdgcn_mfma_f32_16x16x32_bf16(WxF[kk], Xf[tb][kk], gx, 0, 0, 0); }
;             float hv[4], pv[4];
; #pragma unroll
;             for (int r = 0; r < 4; ++r) {
;                 const float rg = sigmoidf_(ga[r] + bav[r]), ig = sigmoidf_(gx[r] + bxv[r]);
;                 const float la = -8.0f * rg * sp[r]; float A = __expf(la);
;                 float U = __builtin_amdgcn_sqrtf(1.0f - A * A) * (ig * xcf[tok * 65 + j0 + r]);
;                 { const float As = dpp_shr1<1>(A), Us = dpp_shr0<1>(U); U = A * Us + U; A = A * As; }
;                 { const float As = dpp_shr1<2>(A), Us = dpp_shr0<2>(U); U = A * Us + U; A = A * As; }
;                 { const float As = dpp_shr1<4>(A), Us = dpp_shr0<4>(U); U = A * Us + U; A = A * As; }
;                 { const float As = dpp_shr1<8>(A), Us = dpp_shr0<8>(U); U = A * Us + U; A = A * As; }
;                 const float hh = U + A * hc[r], PP = A * Pc[r];
;                 hc[r] = bcast15(hh, lane); Pc[r] = bcast15(PP, lane); hv[r] = hh; pv[r] = PP; }
	v_rcp_f32_e32 v92, v92
	v_add_f32_e32 v89, v45, v89
	v_add_f32_e32 v88, 1.0, v88
	v_rcp_f32_e32 v106, v88
	v_mul_f32_e32 v88, 0xc1000000, v92
	v_add_f32_e32 v92, v49, v93
	v_mul_f32_e32 v92, 0xbfb8aa3b, v92
	v_exp_f32_e32 v92, v92
	v_mul_f32_e32 v89, 0xbfb8aa3b, v89
	v_exp_f32_e32 v89, v89
	v_mul_f32_e32 v88, v145, v88
	v_add_f32_e32 v92, 1.0, v92
	v_rcp_f32_e32 v92, v92
	v_add_f32_e32 v89, 1.0, v89
	v_rcp_f32_e32 v107, v89
	v_mul_f32_e32 v88, 0x3fb8aa3b, v88
	v_mul_f32_e32 v89, 0xc1000000, v92
	v_mul_f32_e32 v89, v147, v89
	v_mul_f32_e32 v89, 0x3fb8aa3b, v89
	v_exp_f32_e32 v122, v88
	v_exp_f32_e32 v123, v89
	v_add_f32_e32 v94, v50, v94
	v_add_f32_e32 v95, v51, v95
	v_fma_f32 v88, -v122, v122, 1.0
	v_fma_f32 v89, -v123, v123, 1.0
	v_sqrt_f32_e32 v126, v88
	v_mov_b32_e32 v88, 1.0
	v_sqrt_f32_e32 v127, v89
	v_mov_b32_e32 v89, 1.0
	v_mov_b32_dpp v88, v122 row_shr:1 row_mask:0xf bank_mask:0xf
	v_mul_f32_e32 v94, 0xbfb8aa3b, v94
	v_mov_b32_dpp v89, v123 row_shr:1 row_mask:0xf bank_mask:0xf
	v_pk_mul_f32 v[128:129], v[122:123], v[88:89]
	v_mov_b32_e32 v88, 1.0
	v_mov_b32_e32 v89, 1.0
	v_mul_f32_e32 v95, 0xbfb8aa3b, v95
	v_mov_b32_dpp v88, v128 row_shr:2 row_mask:0xf bank_mask:0xf
	v_mov_b32_dpp v89, v129 row_shr:2 row_mask:0xf bank_mask:0xf
	v_pk_mul_f32 v[130:131], v[128:129], v[88:89]
	v_mov_b32_e32 v88, 1.0
	v_mov_b32_e32 v89, 1.0
	v_exp_f32_e32 v94, v94
	v_mov_b32_dpp v88, v130 row_shr:4 row_mask:0xf bank_mask:0xf
	v_mov_b32_dpp v89, v131 row_shr:4 row_mask:0xf bank_mask:0xf
	v_pk_mul_f32 v[132:133], v[130:131], v[88:89]
	v_mov_b32_e32 v88, 1.0
	v_mov_b32_e32 v89, 1.0
	v_exp_f32_e32 v95, v95
	v_mov_b32_dpp v88, v132 row_shr:8 row_mask:0xf bank_mask:0xf
	v_mov_b32_dpp v89, v133 row_shr:8 row_mask:0xf bank_mask:0xf
	v_pk_mul_f32 v[134:135], v[132:133], v[88:89]
	v_add_f32_e32 v90, v46, v90
	s_waitcnt lgkmcnt(0)
	v_pk_mul_f32 v[92:93], v[134:135], v[104:105]
	ds_read2_b32 v[104:105], v148 offset1:1
	v_add_f32_e32 v91, v47, v91
	v_mul_f32_e32 v90, 0xbfb8aa3b, v90
	v_mul_f32_e32 v91, 0xbfb8aa3b, v91
	v_add_f32_e32 v94, 1.0, v94
	s_waitcnt lgkmcnt(0)
	v_pk_mul_f32 v[104:105], v[104:105], v[106:107]
	v_exp_f32_e32 v90, v90
	v_pk_mul_f32 v[104:105], v[104:105], v[126:127]
	v_add_f32_e32 v95, 1.0, v95
	v_exp_f32_e32 v91, v91
	v_mov_b32_dpp v106, v104 row_shr:1 row_mask:0xf bank_mask:0xf bound_ctrl:1
	v_mov_b32_dpp v107, v105 row_shr:1 row_mask:0xf bank_mask:0xf bound_ctrl:1
	v_pk_fma_f32 v[104:105], v[122:123], v[106:107], v[104:105]
	v_rcp_f32_e32 v94, v94
	v_rcp_f32_e32 v95, v95
	v_mov_b32_dpp v106, v104 row_shr:2 row_mask:0xf bank_mask:0xf bound_ctrl:1
	v_mov_b32_dpp v107, v105 row_shr:2 row_mask:0xf bank_mask:0xf bound_ctrl:1
	v_pk_fma_f32 v[104:105], v[128:129], v[106:107], v[104:105]
	v_add_f32_e32 v90, 1.0, v90
	v_add_f32_e32 v91, 1.0, v91
	v_mov_b32_dpp v106, v104 row_shr:4 row_mask:0xf bank_mask:0xf bound_ctrl:1
	v_mov_b32_dpp v107, v105 row_shr:4 row_mask:0xf bank_mask:0xf bound_ctrl:1
	v_pk_fma_f32 v[104:105], v[130:131], v[106:107], v[104:105]
	ds_bpermute_b32 v88, v143, v92 offset:60
	ds_bpermute_b32 v89, v143, v93 offset:60
	v_mov_b32_dpp v106, v104 row_shr:8 row_mask:0xf bank_mask:0xf bound_ctrl:1
	v_mov_b32_dpp v107, v105 row_shr:8 row_mask:0xf bank_mask:0xf bound_ctrl:1
	v_pk_fma_f32 v[104:105], v[132:133], v[106:107], v[104:105]
	v_rcp_f32_e32 v106, v90
	v_mul_f32_e32 v90, 0xc1000000, v94
	v_rcp_f32_e32 v107, v91
	v_mul_f32_e32 v91, 0xc1000000, v95
	v_mul_f32_e32 v90, v2, v90
	v_mul_f32_e32 v91, v146, v91
	v_mul_f32_e32 v90, 0x3fb8aa3b, v90
	v_mul_f32_e32 v91, 0x3fb8aa3b, v91
	v_exp_f32_e32 v94, v90
	v_exp_f32_e32 v95, v91
	v_pk_fma_f32 v[104:105], v[134:135], v[98:99], v[104:105]
	ds_read2_b32 v[134:135], v148 offset0:2 offset1:3
	v_fma_f32 v90, -v94, v94, 1.0
	v_fma_f32 v91, -v95, v95, 1.0
	v_sqrt_f32_e32 v122, v90
	v_sqrt_f32_e32 v123, v91
	s_waitcnt lgkmcnt(0)
	v_pk_mul_f32 v[106:107], v[106:107], v[134:135]
	v_mov_b32_e32 v90, 1.0
	v_mov_b32_e32 v91, 1.0
	v_pk_mul_f32 v[106:107], v[122:123], v[106:107]
	v_mov_b32_dpp v90, v94 row_shr:1 row_mask:0xf bank_mask:0xf
	v_mov_b32_dpp v91, v95 row_shr:1 row_mask:0xf bank_mask:0xf
	v_mov_b32_dpp v122, v106 row_shr:1 row_mask:0xf bank_mask:0xf bound_ctrl:1
	v_mov_b32_dpp v123, v107 row_shr:1 row_mask:0xf bank_mask:0xf bound_ctrl:1
	v_pk_mul_f32 v[126:127], v[94:95], v[90:91]
	v_mov_b32_e32 v90, 1.0
	v_mov_b32_e32 v91, 1.0
	v_pk_fma_f32 v[94:95], v[94:95], v[122:123], v[106:107]
	v_mov_b32_dpp v90, v126 row_shr:2 row_mask:0xf bank_mask:0xf
	v_mov_b32_dpp v91, v127 row_shr:2 row_mask:0xf bank_mask:0xf
	v_mov_b32_dpp v106, v94 row_shr:2 row_mask:0xf bank_mask:0xf bound_ctrl:1
	v_mov_b32_dpp v107, v95 row_shr:2 row_mask:0xf bank_mask:0xf bound_ctrl:1
	v_pk_mul_f32 v[128:129], v[126:127], v[90:91]
	v_mov_b32_e32 v90, 1.0
	v_mov_b32_e32 v91, 1.0
	v_pk_fma_f32 v[94:95], v[126:127], v[106:107], v[94:95]
	v_mov_b32_dpp v90, v128 row_shr:4 row_mask:0xf bank_mask:0xf
	v_mov_b32_dpp v91, v129 row_shr:4 row_mask:0xf bank_mask:0xf
	v_mov_b32_dpp v106, v94 row_shr:4 row_mask:0xf bank_mask:0xf bound_ctrl:1
	v_mov_b32_dpp v107, v95 row_shr:4 row_mask:0xf bank_mask:0xf bound_ctrl:1
	v_pk_mul_f32 v[130:131], v[128:129], v[90:91]
	v_mov_b32_e32 v90, 1.0
	v_mov_b32_e32 v91, 1.0
	v_pk_fma_f32 v[94:95], v[128:129], v[106:107], v[94:95]
	v_mov_b32_dpp v90, v130 row_shr:8 row_mask:0xf bank_mask:0xf
	v_mov_b32_dpp v91, v131 row_shr:8 row_mask:0xf bank_mask:0xf
	v_mov_b32_dpp v106, v94 row_shr:8 row_mask:0xf bank_mask:0xf bound_ctrl:1
	v_mov_b32_dpp v107, v95 row_shr:8 row_mask:0xf bank_mask:0xf bound_ctrl:1
	v_pk_mul_f32 v[132:133], v[130:131], v[90:91]
	v_pk_fma_f32 v[94:95], v[130:131], v[106:107], v[94:95]
; __device__ __forceinline__ unsigned pk2(float lo, float hi) { const f32x2_t v = {lo, hi}; const bf16x2_t b = __builtin_convertvector(v, bf16x2_t); return __builtin_bit_cast(unsigned, b); }
; __device__ __forceinline__ float sigmoidf_(float x) { return __builtin_amdgcn_rcpf(1.0f + __expf(-x)); }
; __device__ __forceinline__ float bcast15(float v, int lane) { return bperm_f((lane & 48) | 15, v); }
; __device__ __forceinline__ void w_lru_m1(const Args& a, int l, unsigned char* ws, const bf16_t* proj, bf16_t* y, LAS unsigned char* wl, int b, int ck_, int h, int lane) {
;     ...
;         for (int tb = 0; tb < 4; ++tb) { const int tok = 16 * tb + lo;
;             f32x4 ga = {0.f, 0.f, 0.f, 0.f}, gx = {0.f, 0.f, 0.f, 0.f};
; #pragma unroll
;             for (int kk = 0; kk < 2; ++kk) { ga = __builtin_amdgcn_mfma_f32_16x16x32_bf16(WaF[kk], Xf[tb][kk], ga, 0, 0, 0); gx = __builtin_amdgcn_mfma_f32_16x16x32_bf16(WxF[kk], Xf[tb][kk], gx, 0, 0, 0); }
;             float hv[4], pv[4];
; #pragma unroll
;             for (int r = 0; r < 4; ++r) {
;                 const float rg = sigmoidf_(ga[r] + bav[r]), ig = sigmoidf_(gx[r] + bxv[r]);
;                 const float la = -8.0f * rg * sp[r]; float A = __expf(la);
;                 float U = __builtin_amdgcn_sqrtf(1.0f - A * A) * (ig * xcf[tok * 65 + j0 + r]);
;                 { const float As = dpp_shr1<1>(A), Us = dpp_shr0<1>(U); U = A * Us + U; A = A * As; }
;                 { const float As = dpp_shr1<2>(A), Us = dpp_shr0<2>(U); U = A * Us + U; A = A * As; }
;                 { const float As = dpp_shr1<4>(A), Us = dpp_shr0<4>(U); U = A * Us + U; A = A * As; }
;                 { const float As = dpp_shr1<8>(A), Us = dpp_shr0<8>(U); U = A * Us + U; A = A * As; }
;                 const float hh = U + A * hc[r], PP = A * Pc[r];
;                 hc[r] = bcast15(hh, lane); Pc[r] = bcast15(PP, lane); hv[r] = hh; pv[r] = PP; }
;             *(unsigned long long*)(y + (size_t)(row0 + tok) * DM + 64 * h + j0) = (unsigned long long)pk2(hv[0], hv[1]) | ((unsigned long long)pk2(hv[2], hv[3]) << 32);
;             *(unsigned long long*)((bf16_t*)(ws + WS_P) + (size_t)(row0 + tok) * 512 + 64 * h + j0) = (unsigned long long)pk2(pv[0], pv[1]) | ((unsigned long long)pk2(pv[2], pv[3]) << 32);
;         }
	ds_bpermute_b32 v98, v143, v104 offset:60
	v_pk_fma_f32 v[94:95], v[132:133], v[96:97], v[94:95]
	ds_bpermute_b32 v96, v143, v94 offset:60
	v_cvt_pk_bf16_f32 v107, v94, v95
	v_or_b32_e32 v94, s48, v140
	ds_bpermute_b32 v97, v143, v95 offset:60
	v_ashrrev_i32_e32 v95, 31, v94
	ds_bpermute_b32 v99, v143, v105 offset:60
	v_cvt_pk_bf16_f32 v106, v104, v105
	v_lshlrev_b64 v[104:105], 11, v[94:95]
	v_pk_mul_f32 v[124:125], v[132:133], v[124:125]
	v_lshl_add_u64 v[104:105], v[114:115], 0, v[104:105]
	v_lshlrev_b64 v[94:95], 10, v[94:95]
	global_store_dwordx2 v[104:105], v[106:107], off
	v_cvt_pk_bf16_f32 v92, v92, v93
	v_cvt_pk_bf16_f32 v93, v124, v125
	v_lshl_add_u64 v[106:107], v[116:117], 0, v[94:95]
	global_store_dwordx2 v[106:107], v[92:93], off
	v_mfma_f32_16x16x32_bf16 v[92:95], v[52:55], v[8:11], 0
	ds_bpermute_b32 v90, v143, v124 offset:60
	ds_bpermute_b32 v91, v143, v125 offset:60
	v_mfma_f32_16x16x32_bf16 v[126:129], v[60:63], v[24:27], v[92:95]
	v_mfma_f32_16x16x32_bf16 v[122:125], v[56:59], v[8:11], 0
	v_mfma_f32_16x16x32_bf16 v[122:125], v[64:67], v[24:27], v[122:125]
	s_nop 5
	v_add_f32_e32 v92, v48, v126
	v_mul_f32_e32 v92, 0xbfb8aa3b, v92
	v_exp_f32_e32 v92, v92
	v_mfma_f32_16x16x32_bf16 v[52:55], v[52:55], v[4:7], 0
	v_add_f32_e32 v92, 1.0, v92
	v_rcp_f32_e32 v93, v92
	v_add_f32_e32 v92, v44, v122
	v_mov_b32_e32 v122, 1.0
	v_mul_f32_e32 v92, 0xbfb8aa3b, v92
	v_mul_f32_e32 v93, 0xc1000000, v93
	v_mul_f32_e32 v93, v145, v93
	v_mul_f32_e32 v93, 0x3fb8aa3b, v93
	v_exp_f32_e32 v94, v93
	v_exp_f32_e32 v92, v92
	v_fma_f32 v93, -v94, v94, 1.0
	v_sqrt_f32_e32 v126, v93
	v_add_f32_e32 v93, v49, v127
	v_mul_f32_e32 v93, 0xbfb8aa3b, v93
	v_exp_f32_e32 v93, v93
	v_mov_b32_dpp v122, v94 row_shr:1 row_mask:0xf bank_mask:0xf
	v_add_f32_e32 v92, 1.0, v92
	v_rcp_f32_e32 v92, v92
	v_add_f32_e32 v93, 1.0, v93
	v_rcp_f32_e32 v95, v93
	v_add_f32_e32 v93, v45, v123
	v_mul_f32_e32 v93, 0xbfb8aa3b, v93
	v_exp_f32_e32 v93, v93
	v_mul_f32_e32 v95, 0xc1000000, v95
	v_mul_f32_e32 v95, v147, v95
	v_mul_f32_e32 v95, 0x3fb8aa3b, v95
	v_exp_f32_e32 v95, v95
	v_add_f32_e32 v93, 1.0, v93
	v_rcp_f32_e32 v93, v93
	v_fma_f32 v123, -v95, v95, 1.0
	v_sqrt_f32_e32 v127, v123
	v_mov_b32_e32 v123, 1.0
	s_nop 1
	v_mov_b32_dpp v123, v95 row_shr:1 row_mask:0xf bank_mask:0xf
	v_pk_mul_f32 v[130:131], v[94:95], v[122:123]
	v_mov_b32_e32 v122, 1.0
	v_mov_b32_e32 v123, 1.0
	s_nop 0
	v_mov_b32_dpp v122, v130 row_shr:2 row_mask:0xf bank_mask:0xf
	v_mov_b32_dpp v123, v131 row_shr:2 row_mask:0xf bank_mask:0xf
	v_pk_mul_f32 v[132:133], v[130:131], v[122:123]
	v_mov_b32_e32 v122, 1.0
	v_mov_b32_e32 v123, 1.0
	s_nop 0
	v_mov_b32_dpp v122, v132 row_shr:4 row_mask:0xf bank_mask:0xf
	v_mov_b32_dpp v123, v133 row_shr:4 row_mask:0xf bank_mask:0xf
	v_pk_mul_f32 v[134:135], v[132:133], v[122:123]
	v_mov_b32_e32 v122, 1.0
	v_mov_b32_e32 v123, 1.0
	s_nop 0
	v_mov_b32_dpp v122, v134 row_shr:8 row_mask:0xf bank_mask:0xf
	v_mov_b32_dpp v123, v135 row_shr:8 row_mask:0xf bank_mask:0xf
	v_pk_mul_f32 v[140:141], v[134:135], v[122:123]
	s_nop 0
	v_pk_mul_f32 v[148:149], v[140:141], v[88:89]
	ds_read2_b32 v[88:89], v150 offset1:1
	ds_bpermute_b32 v122, v143, v148 offset:60
	ds_bpermute_b32 v123, v143, v149 offset:60
	s_waitcnt lgkmcnt(0)
	v_pk_mul_f32 v[88:89], v[88:89], v[92:93]
	s_nop 0
	v_pk_mul_f32 v[88:89], v[88:89], v[126:127]
	s_nop 1
	v_mov_b32_dpp v92, v88 row_shr:1 row_mask:0xf bank_mask:0xf bound_ctrl:1
	v_mov_b32_dpp v93, v89 row_shr:1 row_mask:0xf bank_mask:0xf bound_ctrl:1
	v_pk_fma_f32 v[88:89], v[94:95], v[92:93], v[88:89]
	s_nop 1
	v_mov_b32_dpp v92, v88 row_shr:2 row_mask:0xf bank_mask:0xf bound_ctrl:1
	v_mov_b32_dpp v93, v89 row_shr:2 row_mask:0xf bank_mask:0xf bound_ctrl:1
	v_pk_fma_f32 v[88:89], v[130:131], v[92:93], v[88:89]
	s_nop 1
	v_mov_b32_dpp v92, v88 row_shr:4 row_mask:0xf bank_mask:0xf bound_ctrl:1
	v_mov_b32_dpp v93, v89 row_shr:4 row_mask:0xf bank_mask:0xf bound_ctrl:1
	v_pk_fma_f32 v[88:89], v[132:133], v[92:93], v[88:89]
	s_nop 1
	v_mov_b32_dpp v92, v88 row_shr:8 row_mask:0xf bank_mask:0xf bound_ctrl:1
	v_mov_b32_dpp v93, v89 row_shr:8 row_mask:0xf bank_mask:0xf bound_ctrl:1
	v_pk_fma_f32 v[88:89], v[134:135], v[92:93], v[88:89]
	v_mov_b32_e32 v92, 1.0
	v_pk_fma_f32 v[98:99], v[140:141], v[98:99], v[88:89]
	v_add_f32_e32 v88, v50, v128
	v_mul_f32_e32 v88, 0xbfb8aa3b, v88
	v_exp_f32_e32 v88, v88
	ds_read2_b32 v[140:141], v150 offset0:2 offset1:3
	ds_bpermute_b32 v94, v143, v98 offset:60
	ds_bpermute_b32 v95, v143, v99 offset:60
	v_add_f32_e32 v88, 1.0, v88
	v_rcp_f32_e32 v89, v88
	v_add_f32_e32 v88, v46, v124
	v_mul_f32_e32 v88, 0xbfb8aa3b, v88
	v_exp_f32_e32 v88, v88
	v_mul_f32_e32 v89, 0xc1000000, v89
	v_mul_f32_e32 v89, v2, v89
	v_mul_f32_e32 v89, 0x3fb8aa3b, v89
	v_exp_f32_e32 v124, v89
	v_add_f32_e32 v88, 1.0, v88
	v_rcp_f32_e32 v88, v88
	v_cvt_pk_bf16_f32 v98, v98, v99
	v_fma_f32 v89, -v124, v124, 1.0
	v_sqrt_f32_e32 v126, v89
	v_add_f32_e32 v89, v51, v129
	v_mul_f32_e32 v89, 0xbfb8aa3b, v89
	v_exp_f32_e32 v89, v89
	v_mov_b32_dpp v92, v124 row_shr:1 row_mask:0xf bank_mask:0xf
	v_add_f32_e32 v89, 1.0, v89
	v_rcp_f32_e32 v93, v89
	v_add_f32_e32 v89, v47, v125
	v_mul_f32_e32 v89, 0xbfb8aa3b, v89
	v_exp_f32_e32 v89, v89
	v_mul_f32_e32 v93, 0xc1000000, v93
	v_mul_f32_e32 v93, v146, v93
	v_mul_f32_e32 v93, 0x3fb8aa3b, v93
	v_exp_f32_e32 v125, v93
	v_add_f32_e32 v89, 1.0, v89
	v_rcp_f32_e32 v89, v89
	v_fma_f32 v93, -v125, v125, 1.0
	v_sqrt_f32_e32 v127, v93
	s_waitcnt lgkmcnt(0)
; __device__ __forceinline__ unsigned pk2(float lo, float hi) { const f32x2_t v = {lo, hi}; const bf16x2_t b = __builtin_convertvector(v, bf16x2_t); return __builtin_bit_cast(unsigned, b); }
; __device__ __forceinline__ float sigmoidf_(float x) { return __builtin_amdgcn_rcpf(1.0f + __expf(-x)); }
; __device__ __forceinline__ float bcast15(float v, int lane) { return bperm_f((lane & 48) | 15, v); }
; __device__ __forceinline__ void w_lru_m1(const Args& a, int l, unsigned char* ws, const bf16_t* proj, bf16_t* y, LAS unsigned char* wl, int b, int ck_, int h, int lane) {
;     ...
;         for (int tb = 0; tb < 4; ++tb) { const int tok = 16 * tb + lo;
;             f32x4 ga = {0.f, 0.f, 0.f, 0.f}, gx = {0.f, 0.f, 0.f, 0.f};
; #pragma unroll
;             for (int kk = 0; kk < 2; ++kk) { ga = __builtin_amdgcn_mfma_f32_16x16x32_bf16(WaF[kk], Xf[tb][kk], ga, 0, 0, 0); gx = __builtin_amdgcn_mfma_f32_16x16x32_bf16(WxF[kk], Xf[tb][kk], gx, 0, 0, 0); }
;             float hv[4], pv[4];
; #pragma unroll
;             for (int r = 0; r < 4; ++r) {
;                 const float rg = sigmoidf_(ga[r] + bav[r]), ig = sigmoidf_(gx[r] + bxv[r]);
;                 const float la = -8.0f * rg * sp[r]; float A = __expf(la);
;                 float U = __builtin_amdgcn_sqrtf(1.0f - A * A) * (ig * xcf[tok * 65 + j0 + r]);
;                 { const float As = dpp_shr1<1>(A), Us = dpp_shr0<1>(U); U = A * Us + U; A = A * As; }
;                 { const float As = dpp_shr1<2>(A), Us = dpp_shr0<2>(U); U = A * Us + U; A = A * As; }
;                 { const float As = dpp_shr1<4>(A), Us = dpp_shr0<4>(U); U = A * Us + U; A = A * As; }
;                 { const float As = dpp_shr1<8>(A), Us = dpp_shr0<8>(U); U = A * Us + U; A = A * As; }
;                 const float hh = U + A * hc[r], PP = A * Pc[r];
;                 hc[r] = bcast15(hh, lane); Pc[r] = bcast15(PP, lane); hv[r] = hh; pv[r] = PP; }
;             *(unsigned long long*)(y + (size_t)(row0 + tok) * DM + 64 * h + j0) = (unsigned long long)pk2(hv[0], hv[1]) | ((unsigned long long)pk2(hv[2], hv[3]) << 32);
;             *(unsigned long long*)((bf16_t*)(ws + WS_P) + (size_t)(row0 + tok) * 512 + 64 * h + j0) = (unsigned long long)pk2(pv[0], pv[1]) | ((unsigned long long)pk2(pv[2], pv[3]) << 32);
;         }
	v_pk_mul_f32 v[88:89], v[88:89], v[140:141]
	v_mov_b32_e32 v93, 1.0
	v_pk_mul_f32 v[88:89], v[126:127], v[88:89]
	s_nop 0
	v_mov_b32_dpp v93, v125 row_shr:1 row_mask:0xf bank_mask:0xf
	v_mov_b32_dpp v126, v88 row_shr:1 row_mask:0xf bank_mask:0xf bound_ctrl:1
	v_mov_b32_dpp v127, v89 row_shr:1 row_mask:0xf bank_mask:0xf bound_ctrl:1
	v_pk_mul_f32 v[128:129], v[124:125], v[92:93]
	v_mov_b32_e32 v92, 1.0
	v_mov_b32_e32 v93, 1.0
	v_pk_fma_f32 v[88:89], v[124:125], v[126:127], v[88:89]
	v_mov_b32_dpp v92, v128 row_shr:2 row_mask:0xf bank_mask:0xf
	v_mov_b32_dpp v93, v129 row_shr:2 row_mask:0xf bank_mask:0xf
	v_mov_b32_dpp v124, v88 row_shr:2 row_mask:0xf bank_mask:0xf bound_ctrl:1
	v_mov_b32_dpp v125, v89 row_shr:2 row_mask:0xf bank_mask:0xf bound_ctrl:1
	v_pk_mul_f32 v[130:131], v[128:129], v[92:93]
	v_mov_b32_e32 v92, 1.0
	v_mov_b32_e32 v93, 1.0
	v_pk_fma_f32 v[88:89], v[128:129], v[124:125], v[88:89]
	v_mov_b32_dpp v92, v130 row_shr:4 row_mask:0xf bank_mask:0xf
	v_mov_b32_dpp v93, v131 row_shr:4 row_mask:0xf bank_mask:0xf
	v_mov_b32_dpp v124, v88 row_shr:4 row_mask:0xf bank_mask:0xf bound_ctrl:1
	v_mov_b32_dpp v125, v89 row_shr:4 row_mask:0xf bank_mask:0xf bound_ctrl:1
	v_pk_mul_f32 v[132:133], v[130:131], v[92:93]
	v_mov_b32_e32 v92, 1.0
	v_mov_b32_e32 v93, 1.0
	v_pk_fma_f32 v[88:89], v[130:131], v[124:125], v[88:89]
	v_mov_b32_dpp v92, v132 row_shr:8 row_mask:0xf bank_mask:0xf
	v_mov_b32_dpp v93, v133 row_shr:8 row_mask:0xf bank_mask:0xf
	v_mov_b32_dpp v124, v88 row_shr:8 row_mask:0xf bank_mask:0xf bound_ctrl:1
	v_mov_b32_dpp v125, v89 row_shr:8 row_mask:0xf bank_mask:0xf bound_ctrl:1
	v_pk_mul_f32 v[134:135], v[132:133], v[92:93]
	v_pk_fma_f32 v[88:89], v[132:133], v[124:125], v[88:89]
	v_or_b32_e32 v124, s48, v139
	v_pk_fma_f32 v[96:97], v[134:135], v[96:97], v[88:89]
	v_ashrrev_i32_e32 v125, 31, v124
	v_pk_mul_f32 v[90:91], v[134:135], v[90:91]
	ds_bpermute_b32 v88, v143, v96 offset:60
	ds_bpermute_b32 v89, v143, v97 offset:60
	v_cvt_pk_bf16_f32 v99, v96, v97
	v_lshlrev_b64 v[96:97], 11, v[124:125]
	ds_bpermute_b32 v92, v143, v90 offset:60
	ds_bpermute_b32 v93, v143, v91 offset:60
	v_lshl_add_u64 v[96:97], v[114:115], 0, v[96:97]
	v_cvt_pk_bf16_f32 v127, v90, v91
	v_lshlrev_b64 v[90:91], 10, v[124:125]
	global_store_dwordx2 v[96:97], v[98:99], off
	v_cvt_pk_bf16_f32 v126, v148, v149
	v_lshl_add_u64 v[98:99], v[116:117], 0, v[90:91]
	global_store_dwordx2 v[98:99], v[126:127], off
	v_mfma_f32_16x16x32_bf16 v[124:127], v[56:59], v[4:7], 0
	v_mfma_f32_16x16x32_bf16 v[56:59], v[60:63], v[20:23], v[52:55]
	v_mfma_f32_16x16x32_bf16 v[52:55], v[64:67], v[20:23], v[124:127]
	s_nop 5
	v_add_u32_e32 v124, v142, v138
	v_add_f32_e32 v48, v48, v56
	v_add_f32_e32 v49, v49, v57
	v_mul_f32_e32 v48, 0xbfb8aa3b, v48
	v_mul_f32_e32 v49, 0xbfb8aa3b, v49
	v_exp_f32_e32 v48, v48
	v_exp_f32_e32 v49, v49
	v_add_f32_e32 v44, v44, v52
	v_add_f32_e32 v45, v45, v53
	v_mul_f32_e32 v44, 0xbfb8aa3b, v44
	v_mul_f32_e32 v45, 0xbfb8aa3b, v45
	v_add_f32_e32 v48, 1.0, v48
	v_exp_f32_e32 v44, v44
	v_add_f32_e32 v49, 1.0, v49
	v_exp_f32_e32 v45, v45
	v_rcp_f32_e32 v56, v48
	v_rcp_f32_e32 v52, v49
	v_add_f32_e32 v44, 1.0, v44
	v_add_f32_e32 v45, 1.0, v45
	v_rcp_f32_e32 v48, v44
	v_mul_f32_e32 v44, 0xc1000000, v56
	v_rcp_f32_e32 v49, v45
	v_mul_f32_e32 v45, 0xc1000000, v52
	v_mul_f32_e32 v44, v145, v44
	v_mul_f32_e32 v45, v147, v45
	v_mul_f32_e32 v44, 0x3fb8aa3b, v44
	v_mul_f32_e32 v45, 0x3fb8aa3b, v45
	v_exp_f32_e32 v56, v44
	v_exp_f32_e32 v57, v45
	v_add_f32_e32 v50, v50, v58
	v_mul_f32_e32 v50, 0xbfb8aa3b, v50
	v_fma_f32 v44, -v56, v56, 1.0
	v_fma_f32 v45, -v57, v57, 1.0
	v_sqrt_f32_e32 v60, v44
	v_mov_b32_e32 v44, 1.0
	v_sqrt_f32_e32 v61, v45
	v_mov_b32_e32 v45, 1.0
	v_exp_f32_e32 v50, v50
	v_mov_b32_dpp v44, v56 row_shr:1 row_mask:0xf bank_mask:0xf
	v_mov_b32_dpp v45, v57 row_shr:1 row_mask:0xf bank_mask:0xf
	v_pk_mul_f32 v[62:63], v[56:57], v[44:45]
	v_mov_b32_e32 v44, 1.0
	v_mov_b32_e32 v45, 1.0
	v_add_f32_e32 v46, v46, v54
	v_mov_b32_dpp v44, v62 row_shr:2 row_mask:0xf bank_mask:0xf
	v_mov_b32_dpp v45, v63 row_shr:2 row_mask:0xf bank_mask:0xf
	v_mul_f32_e32 v46, 0xbfb8aa3b, v46
	v_pk_mul_f32 v[64:65], v[62:63], v[44:45]
	v_mov_b32_e32 v44, 1.0
	v_mov_b32_e32 v45, 1.0
	v_add_f32_e32 v50, 1.0, v50
	v_exp_f32_e32 v46, v46
	v_mov_b32_dpp v44, v64 row_shr:4 row_mask:0xf bank_mask:0xf
	v_mov_b32_dpp v45, v65 row_shr:4 row_mask:0xf bank_mask:0xf
	v_rcp_f32_e32 v50, v50
	v_pk_mul_f32 v[66:67], v[64:65], v[44:45]
	v_mov_b32_e32 v44, 1.0
	v_mov_b32_e32 v45, 1.0
	v_add_f32_e32 v46, 1.0, v46
	v_mov_b32_dpp v44, v66 row_shr:8 row_mask:0xf bank_mask:0xf
	v_mov_b32_dpp v45, v67 row_shr:8 row_mask:0xf bank_mask:0xf
	v_pk_mul_f32 v[90:91], v[66:67], v[44:45]
	v_rcp_f32_e32 v54, v46
	v_pk_mul_f32 v[52:53], v[90:91], v[122:123]
	ds_read2_b32 v[122:123], v124 offset1:1
	v_mul_f32_e32 v46, 0xc1000000, v50
	v_mul_f32_e32 v2, v2, v46
	v_mul_f32_e32 v2, 0x3fb8aa3b, v2
	v_exp_f32_e32 v50, v2
	s_waitcnt lgkmcnt(0)
; __device__ __forceinline__ unsigned pk2(float lo, float hi) { const f32x2_t v = {lo, hi}; const bf16x2_t b = __builtin_convertvector(v, bf16x2_t); return __builtin_bit_cast(unsigned, b); }
; __device__ __forceinline__ float sigmoidf_(float x) { return __builtin_amdgcn_rcpf(1.0f + __expf(-x)); }
; __device__ __forceinline__ float bcast15(float v, int lane) { return bperm_f((lane & 48) | 15, v); }
; __device__ __forceinline__ void w_lru_m1(const Args& a, int l, unsigned char* ws, const bf16_t* proj, bf16_t* y, LAS unsigned char* wl, int b, int ck_, int h, int lane) {
;     ...
;             for (int r = 0; r < 4; ++r) {
;                 const float rg = sigmoidf_(ga[r] + bav[r]), ig = sigmoidf_(gx[r] + bxv[r]);
;                 const float la = -8.0f * rg * sp[r]; float A = __expf(la);
;                 float U = __builtin_amdgcn_sqrtf(1.0f - A * A) * (ig * xcf[tok * 65 + j0 + r]);
;                 { const float As = dpp_shr1<1>(A), Us = dpp_shr0<1>(U); U = A * Us + U; A = A * As; }
;                 { const float As = dpp_shr1<2>(A), Us = dpp_shr0<2>(U); U = A * Us + U; A = A * As; }
;                 { const float As = dpp_shr1<4>(A), Us = dpp_shr0<4>(U); U = A * Us + U; A = A * As; }
;                 { const float As = dpp_shr1<8>(A), Us = dpp_shr0<8>(U); U = A * Us + U; A = A * As; }
;                 const float hh = U + A * hc[r], PP = A * Pc[r];
;                 hc[r] = bcast15(hh, lane); Pc[r] = bcast15(PP, lane); hv[r] = hh; pv[r] = PP; }
;             *(unsigned long long*)(y + (size_t)(row0 + tok) * DM + 64 * h + j0) = (unsigned long long)pk2(hv[0], hv[1]) | ((unsigned long long)pk2(hv[2], hv[3]) << 32);
;             *(unsigned long long*)((bf16_t*)(ws + WS_P) + (size_t)(row0 + tok) * 512 + 64 * h + j0) = (unsigned long long)pk2(pv[0], pv[1]) | ((unsigned long long)pk2(pv[2], pv[3]) << 32);
;         }
;         if (lo == 0) { const size_t so = (size_t)(b * NCH + ck_) * 512 + 64 * h + j0;
; #pragma unroll
;             for (int r = 0; r < 4; ++r) { ((float*)(ws + WS_LRUA))[so + r] = Pc[r]; ((float*)(ws + WS_LRUH))[so + r] = hc[r]; } }
	v_pk_mul_f32 v[48:49], v[122:123], v[48:49]
	v_add_f32_e32 v47, v47, v55
	v_pk_mul_f32 v[48:49], v[48:49], v[60:61]
	v_fma_f32 v2, -v50, v50, 1.0
	v_mul_f32_e32 v47, 0xbfb8aa3b, v47
	v_mov_b32_dpp v60, v48 row_shr:1 row_mask:0xf bank_mask:0xf bound_ctrl:1
	v_mov_b32_dpp v61, v49 row_shr:1 row_mask:0xf bank_mask:0xf bound_ctrl:1
	v_pk_fma_f32 v[48:49], v[56:57], v[60:61], v[48:49]
	v_sqrt_f32_e32 v60, v2
	v_add_f32_e32 v2, v51, v59
	v_mul_f32_e32 v2, 0xbfb8aa3b, v2
	v_exp_f32_e32 v2, v2
	v_exp_f32_e32 v47, v47
	v_mov_b32_e32 v46, 1.0
	v_mov_b32_dpp v56, v48 row_shr:2 row_mask:0xf bank_mask:0xf bound_ctrl:1
	v_add_f32_e32 v2, 1.0, v2
	v_rcp_f32_e32 v2, v2
	v_add_f32_e32 v47, 1.0, v47
	v_rcp_f32_e32 v55, v47
	v_mov_b32_e32 v47, 1.0
	v_mul_f32_e32 v2, 0xc1000000, v2
	v_mul_f32_e32 v2, v146, v2
	v_mul_f32_e32 v2, 0x3fb8aa3b, v2
	v_exp_f32_e32 v51, v2
	v_mov_b32_dpp v57, v49 row_shr:2 row_mask:0xf bank_mask:0xf bound_ctrl:1
	v_mov_b32_dpp v46, v50 row_shr:1 row_mask:0xf bank_mask:0xf
	v_pk_fma_f32 v[48:49], v[62:63], v[56:57], v[48:49]
	v_mov_b32_dpp v47, v51 row_shr:1 row_mask:0xf bank_mask:0xf
	v_pk_mul_f32 v[62:63], v[50:51], v[46:47]
	v_mov_b32_e32 v46, 1.0
	v_mov_b32_e32 v47, 1.0
	v_mov_b32_dpp v56, v48 row_shr:4 row_mask:0xf bank_mask:0xf bound_ctrl:1
	v_mov_b32_dpp v57, v49 row_shr:4 row_mask:0xf bank_mask:0xf bound_ctrl:1
	v_mov_b32_dpp v46, v62 row_shr:2 row_mask:0xf bank_mask:0xf
	v_mov_b32_dpp v47, v63 row_shr:2 row_mask:0xf bank_mask:0xf
	v_pk_fma_f32 v[48:49], v[64:65], v[56:57], v[48:49]
	v_pk_mul_f32 v[64:65], v[62:63], v[46:47]
	v_mov_b32_e32 v46, 1.0
	v_mov_b32_e32 v47, 1.0
	v_mov_b32_dpp v56, v48 row_shr:8 row_mask:0xf bank_mask:0xf bound_ctrl:1
	v_mov_b32_dpp v57, v49 row_shr:8 row_mask:0xf bank_mask:0xf bound_ctrl:1
	v_mov_b32_dpp v46, v64 row_shr:4 row_mask:0xf bank_mask:0xf
	v_mov_b32_dpp v47, v65 row_shr:4 row_mask:0xf bank_mask:0xf
	v_pk_fma_f32 v[48:49], v[66:67], v[56:57], v[48:49]
	v_pk_mul_f32 v[66:67], v[64:65], v[46:47]
	v_mov_b32_e32 v46, 1.0
	v_mov_b32_e32 v47, 1.0
	v_pk_fma_f32 v[56:57], v[90:91], v[94:95], v[48:49]
	v_mov_b32_dpp v46, v66 row_shr:8 row_mask:0xf bank_mask:0xf
	v_mov_b32_dpp v47, v67 row_shr:8 row_mask:0xf bank_mask:0xf
	v_pk_mul_f32 v[90:91], v[66:67], v[46:47]
	v_fma_f32 v2, -v51, v51, 1.0
	v_pk_mul_f32 v[58:59], v[90:91], v[92:93]
	ds_read2_b32 v[92:93], v124 offset0:2 offset1:3
	v_sqrt_f32_e32 v61, v2
	ds_bpermute_b32 v44, v143, v52 offset:60
	ds_bpermute_b32 v48, v143, v56 offset:60
	ds_bpermute_b32 v49, v143, v57 offset:60
	s_waitcnt lgkmcnt(0)
	v_pk_mul_f32 v[54:55], v[54:55], v[92:93]
	ds_bpermute_b32 v45, v143, v53 offset:60
	v_pk_mul_f32 v[54:55], v[60:61], v[54:55]
	ds_bpermute_b32 v46, v143, v58 offset:60
	ds_bpermute_b32 v47, v143, v59 offset:60
	v_mov_b32_dpp v60, v54 row_shr:1 row_mask:0xf bank_mask:0xf bound_ctrl:1
	v_mov_b32_dpp v61, v55 row_shr:1 row_mask:0xf bank_mask:0xf bound_ctrl:1
	v_pk_fma_f32 v[50:51], v[50:51], v[60:61], v[54:55]
	v_cvt_pk_bf16_f32 v56, v56, v57
	v_cvt_pk_bf16_f32 v52, v52, v53
	v_mov_b32_dpp v54, v50 row_shr:2 row_mask:0xf bank_mask:0xf bound_ctrl:1
	v_mov_b32_dpp v55, v51 row_shr:2 row_mask:0xf bank_mask:0xf bound_ctrl:1
	v_pk_fma_f32 v[50:51], v[62:63], v[54:55], v[50:51]
	v_cvt_pk_bf16_f32 v53, v58, v59
	s_nop 0
	v_mov_b32_dpp v54, v50 row_shr:4 row_mask:0xf bank_mask:0xf bound_ctrl:1
	v_mov_b32_dpp v55, v51 row_shr:4 row_mask:0xf bank_mask:0xf bound_ctrl:1
	v_pk_fma_f32 v[50:51], v[64:65], v[54:55], v[50:51]
	s_nop 1
	v_mov_b32_dpp v54, v50 row_shr:8 row_mask:0xf bank_mask:0xf bound_ctrl:1
	v_mov_b32_dpp v55, v51 row_shr:8 row_mask:0xf bank_mask:0xf bound_ctrl:1
	v_pk_fma_f32 v[50:51], v[66:67], v[54:55], v[50:51]
	s_nop 0
	v_pk_fma_f32 v[54:55], v[90:91], v[88:89], v[50:51]
	ds_bpermute_b32 v50, v143, v54 offset:60
	ds_bpermute_b32 v51, v143, v55 offset:60
	v_cvt_pk_bf16_f32 v57, v54, v55
	v_or_b32_e32 v54, s48, v137
	v_ashrrev_i32_e32 v55, 31, v54
	v_lshlrev_b64 v[60:61], 11, v[54:55]
	v_lshlrev_b64 v[54:55], 10, v[54:55]
	v_lshl_add_u64 v[114:115], v[114:115], 0, v[60:61]
	v_lshl_add_u64 v[116:117], v[116:117], 0, v[54:55]
	global_store_dwordx2 v[114:115], v[56:57], off
	global_store_dwordx2 v[116:117], v[52:53], off
	s_and_saveexec_b64 s[34:35], vcc
	s_cbranch_execz .LBB0_523
	v_lshl_add_u64 v[52:53], s[42:43], 0, v[0:1]
	v_lshlrev_b64 v[52:53], 2, v[52:53]
	v_lshl_add_u64 v[54:55], s[84:85], 0, v[52:53]
	v_lshl_add_u64 v[52:53], s[86:87], 0, v[52:53]
	s_waitcnt lgkmcnt(0)
	global_store_dwordx4 v[54:55], v[44:47], off
	global_store_dwordx4 v[52:53], v[48:51], off
; __device__ __forceinline__ void w_lru_m1(const Args& a, int l, unsigned char* ws, const bf16_t* proj, bf16_t* y, LAS unsigned char* wl, int b, int ck_, int h, int lane) {
;     ...
;         if (jb < 3) {
; #pragma unroll
;             for (int kk = 0; kk < 2; ++kk) { nWa[kk] = *(const bf16x8*)(waT + (16 * (jb + 1) + lo) * 64 + 32 * kk + 8 * fq); nWx[kk] = *(const bf16x8*)(wxT + (16 * (jb + 1) + lo) * 64 + 32 * kk + 8 * fq); }
;             nba = *(const f32x4*)(ba + 16 * (jb + 1) + 4 * fq); nbx = *(const f32x4*)(bx + 16 * (jb + 1) + 4 * fq); nlam = *(const f32x4*)(lam + 16 * (jb + 1) + 4 * fq);
;         }
;         const int j0 = 16 * jb + 4 * fq;
;         float bav[4], bxv[4], sp[4], hc[4], Pc[4];
; #pragma unroll
;         for (int r = 0; r < 4; ++r) { bav[r] = pba[r]; bxv[r] = pbx[r]; sp[r] = log1pf(__expf(-plam[r])); hc[r] = 0.f; Pc[r] = 1.f; }
; #pragma unroll
;         for (int tb = 0; tb < 4; ++tb) { const int tok = 16 * tb + lo;
;             f32x4 ga = {0.f, 0.f, 0.f, 0.f}, gx = {0.f, 0.f, 0.f, 0.f};
; #pragma unroll
;             for (int kk = 0; kk < 2; ++kk) { ga = __builtin_amdgcn_mfma_f32_16x16x32_bf16(WaF[kk], Xf[tb][kk], ga, 0, 0, 0); gx = __builtin_amdgcn_mfma_f32_16x16x32_bf16(WxF[kk], Xf[tb][kk], gx, 0, 0, 0); }
;             float hv[4], pv[4];
; #pragma unroll
;             for (int r = 0; r < 4; ++r) {
;                 const float rg = sigmoidf_(ga[r] + bav[r]), ig = sigmoidf_(gx[r] + bxv[r]);
;                 const float la = -8.0f * rg * sp[r]; float A = __expf(la);
;                 float U = __builtin_amdgcn_sqrtf(1.0f - A * A) * (ig * xcf[tok * 65 + j0 + r]);
;                 { const float As = dpp_shr1<1>(A), Us = dpp_shr0<1>(U); U = A * Us + U; A = A * As; }
;                 { const float As = dpp_shr1<2>(A), Us = dpp_shr0<2>(U); U = A * Us + U; A = A * As; }
;                 { const float As = dpp_shr1<4>(A), Us = dpp_shr0<4>(U); U = A * Us + U; A = A * As; }
;                 { const float As = dpp_shr1<8>(A), Us = dpp_shr0<8>(U); U = A * Us + U; A = A * As; }
;                 const float hh = U + A * hc[r], PP = A * Pc[r];
;                 hc[r] = bcast15(hh, lane); Pc[r] = bcast15(PP, lane); hv[r] = hh; pv[r] = PP; }
;             *(unsigned long long*)(y + (size_t)(row0 + tok) * DM + 64 * h + j0) = (unsigned long long)pk2(hv[0], hv[1]) | ((unsigned long long)pk2(hv[2], hv[3]) << 32);
.LBB0_523:
	s_or_b64 exec, exec, s[34:35]
	v_lshlrev_b32_e32 v146, 6, v136
	v_lshl_or_b32 v2, v146, 1, v209
	s_waitcnt lgkmcnt(0)
	v_lshl_add_u64 v[44:45], v[118:119], 0, v[2:3]
	v_lshl_add_u64 v[46:47], v[120:121], 0, v[2:3]
	s_waitcnt vmcnt(8)
	s_nop 7
	v_mul_u32_u24_e32 v92, 0x104, v136
	v_add_u32_e32 v145, v142, v92
	global_load_dwordx4 v[64:67], v[44:45], off
	global_load_dwordx4 v[60:63], v[46:47], off
	global_load_dwordx4 v[56:59], v[44:45], off offset:64
	global_load_dwordx4 v[52:55], v[46:47], off offset:64
	global_load_dwordx4 v[48:51], v[108:109], off offset:128
	s_nop 0
	global_load_dwordx4 v[44:47], v[110:111], off offset:128
	global_load_dwordx4 v[88:91], v[112:113], off offset:128
	s_nop 7
	v_mov_b32_e32 v132, 1.0
	s_nop 7
	v_mov_b32_e32 v133, 1.0
	s_nop 7
	v_or_b32_e32 v1, 60, v143
	ds_read2_b32 v[136:137], v145 offset0:18 offset1:19
	s_nop 7
	s_nop 1
	s_nop 7
	s_nop 1
	s_nop 7
	v_mov_b32_e32 v147, v84
	s_nop 7
	s_nop 0
	s_nop 7
	s_nop 0
	s_nop 7
	s_nop 0
	s_nop 7
	s_nop 0
	s_nop 7
	s_nop 1
	s_nop 7
	s_nop 1
	s_nop 7
	s_nop 1
	s_nop 7
	v_mov_b32_e32 v149, v85
	s_nop 7
	s_nop 0
	s_nop 7
	s_nop 0
	s_nop 7
	v_mov_b32_e32 v130, 1.0
	s_nop 7
	v_mov_b32_e32 v131, 1.0
	s_nop 7
	s_nop 1
	s_nop 7
	s_nop 1
	s_nop 7
	s_nop 1
	s_nop 7
	v_mov_b32_e32 v2, v86
	s_nop 7
	s_nop 0
	s_nop 7
	s_nop 0
	s_nop 7
	s_nop 0
	s_nop 7
	s_nop 0
	s_nop 7
	v_mov_b32_e32 v128, 1.0
	s_nop 7
	v_mov_b32_e32 v129, 1.0
	s_nop 7
	v_mfma_f32_16x16x32_bf16 v[122:125], v[72:75], v[16:19], 0
	s_nop 0
	s_nop 7
	v_mfma_f32_16x16x32_bf16 v[124:127], v[80:83], v[32:35], v[122:125]
	s_nop 0
	s_nop 7
	s_nop 1
	s_nop 7
	v_mov_b32_e32 v148, v87
	v_mfma_f32_16x16x32_bf16 v[84:87], v[68:71], v[16:19], 0
	v_mfma_f32_16x16x32_bf16 v[84:87], v[76:79], v[32:35], v[84:87]
	s_nop 7
	v_add_f32_e32 v84, v40, v84
	v_mul_f32_e32 v84, 0xbfb8aa3b, v84
	v_exp_f32_e32 v84, v84
	v_add_f32_e32 v85, v41, v85
	v_mul_f32_e32 v85, 0xbfb8aa3b, v85
	v_exp_f32_e32 v85, v85
	v_add_f32_e32 v84, 1.0, v84
	v_rcp_f32_e32 v93, v84
	v_add_f32_e32 v84, v36, v124
	v_add_f32_e32 v85, 1.0, v85
	v_mul_f32_e32 v84, 0xbfb8aa3b, v84
	v_mul_f32_e32 v93, 0xc1000000, v93
	v_mul_f32_e32 v93, v147, v93
	v_mul_f32_e32 v93, 0x3fb8aa3b, v93
	v_exp_f32_e32 v94, v93
	v_exp_f32_e32 v84, v84
	v_mov_b32_e32 v124, 1.0
	v_add_f32_e32 v86, v42, v86
	v_fma_f32 v93, -v94, v94, 1.0
	v_sqrt_f32_e32 v122, v93
	v_rcp_f32_e32 v93, v85
	v_add_f32_e32 v85, v37, v125
	v_mul_f32_e32 v85, 0xbfb8aa3b, v85
	v_exp_f32_e32 v85, v85
	v_mul_f32_e32 v93, 0xc1000000, v93
	v_mul_f32_e32 v93, v149, v93
	v_mul_f32_e32 v93, 0x3fb8aa3b, v93
	v_exp_f32_e32 v95, v93
	v_add_f32_e32 v84, 1.0, v84
	v_add_f32_e32 v85, 1.0, v85
	v_rcp_f32_e32 v84, v84
	v_fma_f32 v93, -v95, v95, 1.0
	v_sqrt_f32_e32 v123, v93
	ds_read2_b32 v[92:93], v145 offset0:16 offset1:17
	v_rcp_f32_e32 v85, v85
	v_mov_b32_e32 v125, 1.0
	v_mov_b32_dpp v124, v94 row_shr:1 row_mask:0xf bank_mask:0xf
	v_mul_f32_e32 v86, 0xbfb8aa3b, v86
	s_waitcnt lgkmcnt(0)
	v_pk_mul_f32 v[84:85], v[92:93], v[84:85]
	v_mov_b32_dpp v125, v95 row_shr:1 row_mask:0xf bank_mask:0xf
	v_pk_mul_f32 v[84:85], v[84:85], v[122:123]
	v_pk_mul_f32 v[124:125], v[94:95], v[124:125]
	v_exp_f32_e32 v86, v86
	v_mov_b32_dpp v92, v84 row_shr:1 row_mask:0xf bank_mask:0xf bound_ctrl:1
	v_mov_b32_dpp v93, v85 row_shr:1 row_mask:0xf bank_mask:0xf bound_ctrl:1
	v_pk_fma_f32 v[84:85], v[94:95], v[92:93], v[84:85]
	v_mov_b32_dpp v128, v124 row_shr:2 row_mask:0xf bank_mask:0xf
	v_mov_b32_dpp v129, v125 row_shr:2 row_mask:0xf bank_mask:0xf
	v_mov_b32_dpp v92, v84 row_shr:2 row_mask:0xf bank_mask:0xf bound_ctrl:1
	v_mov_b32_dpp v93, v85 row_shr:2 row_mask:0xf bank_mask:0xf bound_ctrl:1
	v_pk_fma_f32 v[84:85], v[124:125], v[92:93], v[84:85]
	v_pk_mul_f32 v[128:129], v[124:125], v[128:129]
	v_add_f32_e32 v86, 1.0, v86
	v_mov_b32_dpp v92, v84 row_shr:4 row_mask:0xf bank_mask:0xf bound_ctrl:1
	v_mov_b32_dpp v93, v85 row_shr:4 row_mask:0xf bank_mask:0xf bound_ctrl:1
	v_mov_b32_dpp v130, v128 row_shr:4 row_mask:0xf bank_mask:0xf
	v_mov_b32_dpp v131, v129 row_shr:4 row_mask:0xf bank_mask:0xf
	v_pk_fma_f32 v[84:85], v[128:129], v[92:93], v[84:85]
	v_pk_mul_f32 v[130:131], v[128:129], v[130:131]
	v_add_f32_e32 v87, v43, v87
	v_mov_b32_dpp v92, v84 row_shr:8 row_mask:0xf bank_mask:0xf bound_ctrl:1
	v_mov_b32_dpp v93, v85 row_shr:8 row_mask:0xf bank_mask:0xf bound_ctrl:1
	v_pk_fma_f32 v[84:85], v[130:131], v[92:93], v[84:85]
	v_rcp_f32_e32 v92, v86
	v_mul_f32_e32 v87, 0xbfb8aa3b, v87
	v_exp_f32_e32 v87, v87
	v_add_f32_e32 v86, v38, v126
	v_mul_f32_e32 v92, 0xc1000000, v92
	v_mul_f32_e32 v92, v2, v92
	v_mul_f32_e32 v92, 0x3fb8aa3b, v92
	v_exp_f32_e32 v92, v92
	v_add_f32_e32 v87, 1.0, v87
	v_mul_f32_e32 v86, 0xbfb8aa3b, v86
	v_exp_f32_e32 v86, v86
	v_fma_f32 v93, -v92, v92, 1.0
	v_sqrt_f32_e32 v94, v93
	v_rcp_f32_e32 v93, v87
	v_add_f32_e32 v87, v39, v127
	v_mul_f32_e32 v87, 0xbfb8aa3b, v87
	v_exp_f32_e32 v87, v87
	v_mul_f32_e32 v93, 0xc1000000, v93
	v_mul_f32_e32 v93, v148, v93
	v_mul_f32_e32 v93, 0x3fb8aa3b, v93
	v_exp_f32_e32 v93, v93
	v_add_f32_e32 v86, 1.0, v86
	v_add_f32_e32 v87, 1.0, v87
	v_rcp_f32_e32 v86, v86
	v_rcp_f32_e32 v87, v87
	v_fma_f32 v95, -v93, v93, 1.0
	v_sqrt_f32_e32 v95, v95
	v_mov_b32_e32 v122, 1.0
	v_pk_mul_f32 v[86:87], v[86:87], v[136:137]
	v_mov_b32_e32 v123, 1.0
	v_pk_mul_f32 v[86:87], v[94:95], v[86:87]
	v_mov_b32_dpp v122, v92 row_shr:1 row_mask:0xf bank_mask:0xf
	v_mov_b32_dpp v123, v93 row_shr:1 row_mask:0xf bank_mask:0xf
	v_mov_b32_dpp v94, v86 row_shr:1 row_mask:0xf bank_mask:0xf bound_ctrl:1
	v_mov_b32_dpp v95, v87 row_shr:1 row_mask:0xf bank_mask:0xf bound_ctrl:1
	v_pk_mul_f32 v[122:123], v[92:93], v[122:123]
; __device__ __forceinline__ unsigned pk2(float lo, float hi) { const f32x2_t v = {lo, hi}; const bf16x2_t b = __builtin_convertvector(v, bf16x2_t); return __builtin_bit_cast(unsigned, b); }
; __device__ __forceinline__ float sigmoidf_(float x) { return __builtin_amdgcn_rcpf(1.0f + __expf(-x)); }
; __device__ __forceinline__ float bcast15(float v, int lane) { return bperm_f((lane & 48) | 15, v); }
; __device__ __forceinline__ void w_lru_m1(const Args& a, int l, unsigned char* ws, const bf16_t* proj, bf16_t* y, LAS unsigned char* wl, int b, int ck_, int h, int lane) {
;     ...
;         for (int tb = 0; tb < 4; ++tb) { const int tok = 16 * tb + lo;
;             f32x4 ga = {0.f, 0.f, 0.f, 0.f}, gx = {0.f, 0.f, 0.f, 0.f};
; #pragma unroll
;             for (int kk = 0; kk < 2; ++kk) { ga = __builtin_amdgcn_mfma_f32_16x16x32_bf16(WaF[kk], Xf[tb][kk], ga, 0, 0, 0); gx = __builtin_amdgcn_mfma_f32_16x16x32_bf16(WxF[kk], Xf[tb][kk], gx, 0, 0, 0); }
;             float hv[4], pv[4];
; #pragma unroll
;             for (int r = 0; r < 4; ++r) {
;                 const float rg = sigmoidf_(ga[r] + bav[r]), ig = sigmoidf_(gx[r] + bxv[r]);
;                 const float la = -8.0f * rg * sp[r]; float A = __expf(la);
;                 float U = __builtin_amdgcn_sqrtf(1.0f - A * A) * (ig * xcf[tok * 65 + j0 + r]);
;                 { const float As = dpp_shr1<1>(A), Us = dpp_shr0<1>(U); U = A * Us + U; A = A * As; }
;                 { const float As = dpp_shr1<2>(A), Us = dpp_shr0<2>(U); U = A * Us + U; A = A * As; }
;                 { const float As = dpp_shr1<4>(A), Us = dpp_shr0<4>(U); U = A * Us + U; A = A * As; }
;                 { const float As = dpp_shr1<8>(A), Us = dpp_shr0<8>(U); U = A * Us + U; A = A * As; }
;                 const float hh = U + A * hc[r], PP = A * Pc[r];
;                 hc[r] = bcast15(hh, lane); Pc[r] = bcast15(PP, lane); hv[r] = hh; pv[r] = PP; }
;             *(unsigned long long*)(y + (size_t)(row0 + tok) * DM + 64 * h + j0) = (unsigned long long)pk2(hv[0], hv[1]) | ((unsigned long long)pk2(hv[2], hv[3]) << 32);
;             *(unsigned long long*)((bf16_t*)(ws + WS_P) + (size_t)(row0 + tok) * 512 + 64 * h + j0) = (unsigned long long)pk2(pv[0], pv[1]) | ((unsigned long long)pk2(pv[2], pv[3]) << 32);
;         }
	v_mov_b32_e32 v126, 1.0
	v_mov_b32_e32 v127, 1.0
	v_pk_fma_f32 v[86:87], v[92:93], v[94:95], v[86:87]
	v_mov_b32_dpp v126, v122 row_shr:2 row_mask:0xf bank_mask:0xf
	v_mov_b32_dpp v127, v123 row_shr:2 row_mask:0xf bank_mask:0xf
	v_mov_b32_dpp v92, v86 row_shr:2 row_mask:0xf bank_mask:0xf bound_ctrl:1
	v_mov_b32_dpp v93, v87 row_shr:2 row_mask:0xf bank_mask:0xf bound_ctrl:1
	v_pk_mul_f32 v[126:127], v[122:123], v[126:127]
	v_mov_b32_e32 v128, 1.0
	v_mov_b32_e32 v129, 1.0
	v_pk_fma_f32 v[86:87], v[122:123], v[92:93], v[86:87]
	v_mov_b32_dpp v132, v130 row_shr:8 row_mask:0xf bank_mask:0xf
	v_mov_b32_dpp v133, v131 row_shr:8 row_mask:0xf bank_mask:0xf
	v_mov_b32_dpp v128, v126 row_shr:4 row_mask:0xf bank_mask:0xf
	v_mov_b32_dpp v129, v127 row_shr:4 row_mask:0xf bank_mask:0xf
	v_mov_b32_dpp v92, v86 row_shr:4 row_mask:0xf bank_mask:0xf bound_ctrl:1
	v_mov_b32_dpp v93, v87 row_shr:4 row_mask:0xf bank_mask:0xf bound_ctrl:1
	v_pk_mul_f32 v[134:135], v[130:131], v[132:133]
	v_pk_mul_f32 v[128:129], v[126:127], v[128:129]
	v_mov_b32_e32 v130, 1.0
	v_mov_b32_e32 v131, 1.0
	v_pk_fma_f32 v[86:87], v[126:127], v[92:93], v[86:87]
	v_mov_b32_dpp v130, v128 row_shr:8 row_mask:0xf bank_mask:0xf
	v_mov_b32_dpp v131, v129 row_shr:8 row_mask:0xf bank_mask:0xf
	v_mov_b32_dpp v92, v86 row_shr:8 row_mask:0xf bank_mask:0xf bound_ctrl:1
	v_mov_b32_dpp v93, v87 row_shr:8 row_mask:0xf bank_mask:0xf bound_ctrl:1
	v_pk_mul_f32 v[130:131], v[128:129], v[130:131]
	v_pk_fma_f32 v[86:87], v[128:129], v[92:93], v[86:87]
	v_pk_fma_f32 v[84:85], v[134:135], 0, v[84:85] op_sel_hi:[1,0,1]
	v_pk_fma_f32 v[86:87], v[130:131], 0, v[86:87] op_sel_hi:[1,0,1]
	ds_bpermute_b32 v124, v1, v84
	ds_bpermute_b32 v125, v1, v85
	v_cvt_pk_bf16_f32 v84, v84, v85
	v_cvt_pk_bf16_f32 v85, v86, v87
	global_store_dwordx2 v[100:101], v[84:85], off offset:32
	v_cvt_pk_bf16_f32 v84, v134, v135
	v_cvt_pk_bf16_f32 v85, v130, v131
	ds_bpermute_b32 v122, v1, v86
	ds_bpermute_b32 v123, v1, v87
	global_store_dwordx2 v[102:103], v[84:85], off offset:32
	v_mfma_f32_16x16x32_bf16 v[84:87], v[68:71], v[12:15], 0
	ds_bpermute_b32 v132, v1, v130
	ds_bpermute_b32 v133, v1, v131
	ds_bpermute_b32 v150, v1, v134
	v_mfma_f32_16x16x32_bf16 v[126:129], v[72:75], v[12:15], 0
	ds_bpermute_b32 v151, v1, v135
	v_mfma_f32_16x16x32_bf16 v[92:95], v[76:79], v[28:31], v[84:87]
	v_mfma_f32_16x16x32_bf16 v[84:87], v[80:83], v[28:31], v[126:129]
	s_nop 6
	v_add_f32_e32 v92, v40, v92
	v_mul_f32_e32 v92, 0xbfb8aa3b, v92
	v_exp_f32_e32 v92, v92
	v_add_f32_e32 v84, v36, v84
	v_mul_f32_e32 v84, 0xbfb8aa3b, v84
	v_exp_f32_e32 v84, v84
	v_add_f32_e32 v92, 1.0, v92
	v_rcp_f32_e32 v92, v92
	v_add_f32_e32 v85, v37, v85
	v_add_f32_e32 v84, 1.0, v84
	v_rcp_f32_e32 v126, v84
	v_mul_f32_e32 v84, 0xc1000000, v92
	v_add_f32_e32 v92, v41, v93
	v_mul_f32_e32 v92, 0xbfb8aa3b, v92
	v_exp_f32_e32 v92, v92
	v_mul_f32_e32 v85, 0xbfb8aa3b, v85
	v_exp_f32_e32 v85, v85
	v_mul_f32_e32 v84, v147, v84
	v_add_f32_e32 v92, 1.0, v92
	v_rcp_f32_e32 v92, v92
	v_add_f32_e32 v85, 1.0, v85
	v_rcp_f32_e32 v127, v85
	v_mul_f32_e32 v84, 0x3fb8aa3b, v84
	v_mul_f32_e32 v85, 0xc1000000, v92
	v_mul_f32_e32 v85, v149, v85
	v_mul_f32_e32 v85, 0x3fb8aa3b, v85
	v_exp_f32_e32 v128, v84
	v_exp_f32_e32 v129, v85
	v_add_f32_e32 v94, v42, v94
	v_add_f32_e32 v95, v43, v95
	v_fma_f32 v84, -v128, v128, 1.0
	v_fma_f32 v85, -v129, v129, 1.0
	v_sqrt_f32_e32 v130, v84
	v_mov_b32_e32 v84, 1.0
	v_sqrt_f32_e32 v131, v85
	v_mov_b32_e32 v85, 1.0
	v_mov_b32_dpp v84, v128 row_shr:1 row_mask:0xf bank_mask:0xf
	v_mul_f32_e32 v94, 0xbfb8aa3b, v94
	v_mov_b32_dpp v85, v129 row_shr:1 row_mask:0xf bank_mask:0xf
	v_pk_mul_f32 v[134:135], v[128:129], v[84:85]
	v_mov_b32_e32 v84, 1.0
	v_mov_b32_e32 v85, 1.0
	v_mul_f32_e32 v95, 0xbfb8aa3b, v95
	v_mov_b32_dpp v84, v134 row_shr:2 row_mask:0xf bank_mask:0xf
	v_mov_b32_dpp v85, v135 row_shr:2 row_mask:0xf bank_mask:0xf
	v_pk_mul_f32 v[136:137], v[134:135], v[84:85]
	v_mov_b32_e32 v84, 1.0
	v_mov_b32_e32 v85, 1.0
	v_exp_f32_e32 v94, v94
	v_mov_b32_dpp v84, v136 row_shr:4 row_mask:0xf bank_mask:0xf
	v_mov_b32_dpp v85, v137 row_shr:4 row_mask:0xf bank_mask:0xf
	v_pk_mul_f32 v[138:139], v[136:137], v[84:85]
	v_mov_b32_e32 v84, 1.0
	v_mov_b32_e32 v85, 1.0
	v_exp_f32_e32 v95, v95
	v_mov_b32_dpp v84, v138 row_shr:8 row_mask:0xf bank_mask:0xf
	v_mov_b32_dpp v85, v139 row_shr:8 row_mask:0xf bank_mask:0xf
	v_pk_mul_f32 v[140:141], v[138:139], v[84:85]
	v_add_u32_e32 v85, 0x1080, v145
	ds_read2_b32 v[142:143], v85 offset1:1
	v_add_f32_e32 v86, v38, v86
	v_add_f32_e32 v87, v39, v87
	v_mul_f32_e32 v86, 0xbfb8aa3b, v86
	v_mul_f32_e32 v87, 0xbfb8aa3b, v87
	s_waitcnt lgkmcnt(0)
; __device__ __forceinline__ unsigned pk2(float lo, float hi) { const f32x2_t v = {lo, hi}; const bf16x2_t b = __builtin_convertvector(v, bf16x2_t); return __builtin_bit_cast(unsigned, b); }
; __device__ __forceinline__ float sigmoidf_(float x) { return __builtin_amdgcn_rcpf(1.0f + __expf(-x)); }
; __device__ __forceinline__ float bcast15(float v, int lane) { return bperm_f((lane & 48) | 15, v); }
; __device__ __forceinline__ void w_lru_m1(const Args& a, int l, unsigned char* ws, const bf16_t* proj, bf16_t* y, LAS unsigned char* wl, int b, int ck_, int h, int lane) {
;     ...
;         for (int tb = 0; tb < 4; ++tb) { const int tok = 16 * tb + lo;
;             f32x4 ga = {0.f, 0.f, 0.f, 0.f}, gx = {0.f, 0.f, 0.f, 0.f};
; #pragma unroll
;             for (int kk = 0; kk < 2; ++kk) { ga = __builtin_amdgcn_mfma_f32_16x16x32_bf16(WaF[kk], Xf[tb][kk], ga, 0, 0, 0); gx = __builtin_amdgcn_mfma_f32_16x16x32_bf16(WxF[kk], Xf[tb][kk], gx, 0, 0, 0); }
;             float hv[4], pv[4];
; #pragma unroll
;             for (int r = 0; r < 4; ++r) {
;                 const float rg = sigmoidf_(ga[r] + bav[r]), ig = sigmoidf_(gx[r] + bxv[r]);
;                 const float la = -8.0f * rg * sp[r]; float A = __expf(la);
;                 float U = __builtin_amdgcn_sqrtf(1.0f - A * A) * (ig * xcf[tok * 65 + j0 + r]);
;                 { const float As = dpp_shr1<1>(A), Us = dpp_shr0<1>(U); U = A * Us + U; A = A * As; }
;                 { const float As = dpp_shr1<2>(A), Us = dpp_shr0<2>(U); U = A * Us + U; A = A * As; }
;                 { const float As = dpp_shr1<4>(A), Us = dpp_shr0<4>(U); U = A * Us + U; A = A * As; }
;                 { const float As = dpp_shr1<8>(A), Us = dpp_shr0<8>(U); U = A * Us + U; A = A * As; }
;                 const float hh = U + A * hc[r], PP = A * Pc[r];
;                 hc[r] = bcast15(hh, lane); Pc[r] = bcast15(PP, lane); hv[r] = hh; pv[r] = PP; }
;             *(unsigned long long*)(y + (size_t)(row0 + tok) * DM + 64 * h + j0) = (unsigned long long)pk2(hv[0], hv[1]) | ((unsigned long long)pk2(hv[2], hv[3]) << 32);
;             *(unsigned long long*)((bf16_t*)(ws + WS_P) + (size_t)(row0 + tok) * 512 + 64 * h + j0) = (unsigned long long)pk2(pv[0], pv[1]) | ((unsigned long long)pk2(pv[2], pv[3]) << 32);
;         }
	v_pk_mul_f32 v[126:127], v[142:143], v[126:127]
	v_add_f32_e32 v94, 1.0, v94
	v_pk_mul_f32 v[126:127], v[126:127], v[130:131]
	v_exp_f32_e32 v86, v86
	v_add_f32_e32 v95, 1.0, v95
	v_mov_b32_dpp v130, v126 row_shr:1 row_mask:0xf bank_mask:0xf bound_ctrl:1
	v_mov_b32_dpp v131, v127 row_shr:1 row_mask:0xf bank_mask:0xf bound_ctrl:1
	v_pk_fma_f32 v[126:127], v[128:129], v[130:131], v[126:127]
	v_exp_f32_e32 v87, v87
	v_rcp_f32_e32 v94, v94
	v_mov_b32_dpp v128, v126 row_shr:2 row_mask:0xf bank_mask:0xf bound_ctrl:1
	v_mov_b32_dpp v129, v127 row_shr:2 row_mask:0xf bank_mask:0xf bound_ctrl:1
	v_pk_fma_f32 v[126:127], v[134:135], v[128:129], v[126:127]
	v_rcp_f32_e32 v95, v95
	v_add_f32_e32 v86, 1.0, v86
	v_mov_b32_dpp v128, v126 row_shr:4 row_mask:0xf bank_mask:0xf bound_ctrl:1
	v_mov_b32_dpp v129, v127 row_shr:4 row_mask:0xf bank_mask:0xf bound_ctrl:1
	v_pk_fma_f32 v[126:127], v[136:137], v[128:129], v[126:127]
	v_add_f32_e32 v87, 1.0, v87
	v_pk_mul_f32 v[92:93], v[140:141], v[150:151]
	v_mov_b32_dpp v128, v126 row_shr:8 row_mask:0xf bank_mask:0xf bound_ctrl:1
	v_mov_b32_dpp v129, v127 row_shr:8 row_mask:0xf bank_mask:0xf bound_ctrl:1
	v_pk_fma_f32 v[126:127], v[138:139], v[128:129], v[126:127]
	v_rcp_f32_e32 v128, v86
	v_mul_f32_e32 v86, 0xc1000000, v94
	v_rcp_f32_e32 v129, v87
	v_mul_f32_e32 v87, 0xc1000000, v95
	v_mul_f32_e32 v86, v2, v86
	v_mul_f32_e32 v87, v148, v87
	v_mul_f32_e32 v86, 0x3fb8aa3b, v86
	v_mul_f32_e32 v87, 0x3fb8aa3b, v87
	v_exp_f32_e32 v94, v86
	v_exp_f32_e32 v95, v87
	v_pk_fma_f32 v[126:127], v[140:141], v[124:125], v[126:127]
	ds_bpermute_b32 v84, v1, v92
	v_fma_f32 v86, -v94, v94, 1.0
	v_fma_f32 v87, -v95, v95, 1.0
	v_sqrt_f32_e32 v130, v86
	v_mov_b32_e32 v86, 1.0
	v_sqrt_f32_e32 v131, v87
	v_mov_b32_e32 v87, 1.0
	v_mov_b32_dpp v86, v94 row_shr:1 row_mask:0xf bank_mask:0xf
	ds_bpermute_b32 v124, v1, v126
	v_mov_b32_dpp v87, v95 row_shr:1 row_mask:0xf bank_mask:0xf
	v_pk_mul_f32 v[134:135], v[94:95], v[86:87]
	v_mov_b32_e32 v86, 1.0
	v_mov_b32_e32 v87, 1.0
	ds_bpermute_b32 v125, v1, v127
	v_mov_b32_dpp v86, v134 row_shr:2 row_mask:0xf bank_mask:0xf
	v_mov_b32_dpp v87, v135 row_shr:2 row_mask:0xf bank_mask:0xf
	v_pk_mul_f32 v[136:137], v[134:135], v[86:87]
	v_mov_b32_e32 v86, 1.0
	v_mov_b32_e32 v87, 1.0
	ds_bpermute_b32 v85, v1, v93
	v_mov_b32_dpp v86, v136 row_shr:4 row_mask:0xf bank_mask:0xf
	v_mov_b32_dpp v87, v137 row_shr:4 row_mask:0xf bank_mask:0xf
	v_pk_mul_f32 v[138:139], v[136:137], v[86:87]
	v_mov_b32_e32 v86, 1.0
	v_mov_b32_e32 v87, 1.0
	v_cvt_pk_bf16_f32 v126, v126, v127
	v_mov_b32_dpp v86, v138 row_shr:8 row_mask:0xf bank_mask:0xf
	v_mov_b32_dpp v87, v139 row_shr:8 row_mask:0xf bank_mask:0xf
	v_pk_mul_f32 v[140:141], v[138:139], v[86:87]
	v_add_u32_e32 v87, 0x1088, v145
	ds_read2_b32 v[142:143], v87 offset1:1
	v_pk_mul_f32 v[132:133], v[140:141], v[132:133]
	v_cvt_pk_bf16_f32 v92, v92, v93
	v_cvt_pk_bf16_f32 v93, v132, v133
	ds_bpermute_b32 v86, v1, v132
	s_waitcnt lgkmcnt(0)
	v_pk_mul_f32 v[128:129], v[128:129], v[142:143]
	ds_bpermute_b32 v87, v1, v133
	v_pk_mul_f32 v[128:129], v[130:131], v[128:129]
	s_nop 1
	v_mov_b32_dpp v130, v128 row_shr:1 row_mask:0xf bank_mask:0xf bound_ctrl:1
	v_mov_b32_dpp v131, v129 row_shr:1 row_mask:0xf bank_mask:0xf bound_ctrl:1
	v_pk_fma_f32 v[94:95], v[94:95], v[130:131], v[128:129]
	s_nop 1
	v_mov_b32_dpp v128, v94 row_shr:2 row_mask:0xf bank_mask:0xf bound_ctrl:1
	v_mov_b32_dpp v129, v95 row_shr:2 row_mask:0xf bank_mask:0xf bound_ctrl:1
	v_pk_fma_f32 v[94:95], v[134:135], v[128:129], v[94:95]
	s_nop 1
	v_mov_b32_dpp v128, v94 row_shr:4 row_mask:0xf bank_mask:0xf bound_ctrl:1
	v_mov_b32_dpp v129, v95 row_shr:4 row_mask:0xf bank_mask:0xf bound_ctrl:1
	v_pk_fma_f32 v[94:95], v[136:137], v[128:129], v[94:95]
	s_nop 1
	v_mov_b32_dpp v128, v94 row_shr:8 row_mask:0xf bank_mask:0xf bound_ctrl:1
	v_mov_b32_dpp v129, v95 row_shr:8 row_mask:0xf bank_mask:0xf bound_ctrl:1
	v_pk_fma_f32 v[94:95], v[138:139], v[128:129], v[94:95]
	s_nop 0
	v_pk_fma_f32 v[94:95], v[140:141], v[122:123], v[94:95]
	ds_bpermute_b32 v122, v1, v94
	v_cvt_pk_bf16_f32 v127, v94, v95
	ds_bpermute_b32 v123, v1, v95
	global_store_dwordx2 v[104:105], v[126:127], off offset:32
	global_store_dwordx2 v[106:107], v[92:93], off offset:32
	v_mfma_f32_16x16x32_bf16 v[92:95], v[68:71], v[8:11], 0
	v_mfma_f32_16x16x32_bf16 v[130:133], v[76:79], v[24:27], v[92:95]
	v_mfma_f32_16x16x32_bf16 v[126:129], v[72:75], v[8:11], 0
	v_mfma_f32_16x16x32_bf16 v[134:137], v[80:83], v[24:27], v[126:129]
	s_nop 5
	v_add_f32_e32 v92, v40, v130
	v_mul_f32_e32 v92, 0xbfb8aa3b, v92
	v_exp_f32_e32 v92, v92
	v_mov_b32_e32 v126, 1.0
	v_mfma_f32_16x16x32_bf16 v[68:71], v[68:71], v[4:7], 0
	v_add_f32_e32 v92, 1.0, v92
	v_rcp_f32_e32 v93, v92
	v_add_f32_e32 v92, v36, v134
	v_mul_f32_e32 v92, 0xbfb8aa3b, v92
	v_exp_f32_e32 v92, v92
	v_mul_f32_e32 v93, 0xc1000000, v93
	v_mul_f32_e32 v93, v147, v93
	v_mul_f32_e32 v93, 0x3fb8aa3b, v93
	v_exp_f32_e32 v94, v93
	v_add_f32_e32 v92, 1.0, v92
	v_rcp_f32_e32 v92, v92
	v_fma_f32 v93, -v94, v94, 1.0
	v_sqrt_f32_e32 v130, v93
	v_add_f32_e32 v93, v41, v131
	v_mul_f32_e32 v93, 0xbfb8aa3b, v93
	v_exp_f32_e32 v93, v93
	v_mov_b32_dpp v126, v94 row_shr:1 row_mask:0xf bank_mask:0xf
	v_add_f32_e32 v93, 1.0, v93
	v_rcp_f32_e32 v95, v93
	v_add_f32_e32 v93, v37, v135
	v_mul_f32_e32 v93, 0xbfb8aa3b, v93
	v_exp_f32_e32 v93, v93
	v_mul_f32_e32 v95, 0xc1000000, v95
	v_mul_f32_e32 v95, v149, v95
	v_mul_f32_e32 v95, 0x3fb8aa3b, v95
	v_exp_f32_e32 v95, v95
	v_add_f32_e32 v93, 1.0, v93
	v_rcp_f32_e32 v93, v93
	v_fma_f32 v127, -v95, v95, 1.0
	v_sqrt_f32_e32 v131, v127
	v_mov_b32_e32 v127, 1.0
	s_nop 1
	v_mov_b32_dpp v127, v95 row_shr:1 row_mask:0xf bank_mask:0xf
	v_pk_mul_f32 v[134:135], v[94:95], v[126:127]
	v_mov_b32_e32 v126, 1.0
	v_mov_b32_e32 v127, 1.0
	s_nop 0
	v_mov_b32_dpp v126, v134 row_shr:2 row_mask:0xf bank_mask:0xf
	v_mov_b32_dpp v127, v135 row_shr:2 row_mask:0xf bank_mask:0xf
	v_pk_mul_f32 v[138:139], v[134:135], v[126:127]
	v_mov_b32_e32 v126, 1.0
	v_mov_b32_e32 v127, 1.0
	s_nop 0
	v_mov_b32_dpp v126, v138 row_shr:4 row_mask:0xf bank_mask:0xf
	v_mov_b32_dpp v127, v139 row_shr:4 row_mask:0xf bank_mask:0xf
	v_pk_mul_f32 v[140:141], v[138:139], v[126:127]
	v_mov_b32_e32 v126, 1.0
	v_mov_b32_e32 v127, 1.0
	s_nop 0
	v_mov_b32_dpp v126, v140 row_shr:8 row_mask:0xf bank_mask:0xf
	v_mov_b32_dpp v127, v141 row_shr:8 row_mask:0xf bank_mask:0xf
	v_pk_mul_f32 v[142:143], v[140:141], v[126:127]
	s_nop 0
	v_pk_mul_f32 v[128:129], v[142:143], v[84:85]
	v_add_u32_e32 v84, 0x20c0, v145
	ds_read2_b32 v[84:85], v84 offset1:1
	ds_bpermute_b32 v126, v1, v128
	ds_bpermute_b32 v127, v1, v129
	s_waitcnt lgkmcnt(0)
; __device__ __forceinline__ unsigned pk2(float lo, float hi) { const f32x2_t v = {lo, hi}; const bf16x2_t b = __builtin_convertvector(v, bf16x2_t); return __builtin_bit_cast(unsigned, b); }
; __device__ __forceinline__ float sigmoidf_(float x) { return __builtin_amdgcn_rcpf(1.0f + __expf(-x)); }
; __device__ __forceinline__ float bcast15(float v, int lane) { return bperm_f((lane & 48) | 15, v); }
; __device__ __forceinline__ void w_lru_m1(const Args& a, int l, unsigned char* ws, const bf16_t* proj, bf16_t* y, LAS unsigned char* wl, int b, int ck_, int h, int lane) {
;     ...
;         for (int tb = 0; tb < 4; ++tb) { const int tok = 16 * tb + lo;
;             f32x4 ga = {0.f, 0.f, 0.f, 0.f}, gx = {0.f, 0.f, 0.f, 0.f};
; #pragma unroll
;             for (int kk = 0; kk < 2; ++kk) { ga = __builtin_amdgcn_mfma_f32_16x16x32_bf16(WaF[kk], Xf[tb][kk], ga, 0, 0, 0); gx = __builtin_amdgcn_mfma_f32_16x16x32_bf16(WxF[kk], Xf[tb][kk], gx, 0, 0, 0); }
;             float hv[4], pv[4];
; #pragma unroll
;             for (int r = 0; r < 4; ++r) {
;                 const float rg = sigmoidf_(ga[r] + bav[r]), ig = sigmoidf_(gx[r] + bxv[r]);
;                 const float la = -8.0f * rg * sp[r]; float A = __expf(la);
;                 float U = __builtin_amdgcn_sqrtf(1.0f - A * A) * (ig * xcf[tok * 65 + j0 + r]);
;                 { const float As = dpp_shr1<1>(A), Us = dpp_shr0<1>(U); U = A * Us + U; A = A * As; }
;                 { const float As = dpp_shr1<2>(A), Us = dpp_shr0<2>(U); U = A * Us + U; A = A * As; }
;                 { const float As = dpp_shr1<4>(A), Us = dpp_shr0<4>(U); U = A * Us + U; A = A * As; }
;                 { const float As = dpp_shr1<8>(A), Us = dpp_shr0<8>(U); U = A * Us + U; A = A * As; }
;                 const float hh = U + A * hc[r], PP = A * Pc[r];
;                 hc[r] = bcast15(hh, lane); Pc[r] = bcast15(PP, lane); hv[r] = hh; pv[r] = PP; }
;             *(unsigned long long*)(y + (size_t)(row0 + tok) * DM + 64 * h + j0) = (unsigned long long)pk2(hv[0], hv[1]) | ((unsigned long long)pk2(hv[2], hv[3]) << 32);
;             *(unsigned long long*)((bf16_t*)(ws + WS_P) + (size_t)(row0 + tok) * 512 + 64 * h + j0) = (unsigned long long)pk2(pv[0], pv[1]) | ((unsigned long long)pk2(pv[2], pv[3]) << 32);
;         }
	v_pk_mul_f32 v[84:85], v[84:85], v[92:93]
	s_nop 0
	v_pk_mul_f32 v[84:85], v[84:85], v[130:131]
	s_nop 1
	v_mov_b32_dpp v92, v84 row_shr:1 row_mask:0xf bank_mask:0xf bound_ctrl:1
	v_mov_b32_dpp v93, v85 row_shr:1 row_mask:0xf bank_mask:0xf bound_ctrl:1
	v_pk_fma_f32 v[84:85], v[94:95], v[92:93], v[84:85]
	s_nop 1
	v_mov_b32_dpp v92, v84 row_shr:2 row_mask:0xf bank_mask:0xf bound_ctrl:1
	v_mov_b32_dpp v93, v85 row_shr:2 row_mask:0xf bank_mask:0xf bound_ctrl:1
	v_pk_fma_f32 v[84:85], v[134:135], v[92:93], v[84:85]
	s_nop 1
	v_mov_b32_dpp v92, v84 row_shr:4 row_mask:0xf bank_mask:0xf bound_ctrl:1
	v_mov_b32_dpp v93, v85 row_shr:4 row_mask:0xf bank_mask:0xf bound_ctrl:1
	v_pk_fma_f32 v[84:85], v[138:139], v[92:93], v[84:85]
	s_nop 1
	v_mov_b32_dpp v92, v84 row_shr:8 row_mask:0xf bank_mask:0xf bound_ctrl:1
	v_mov_b32_dpp v93, v85 row_shr:8 row_mask:0xf bank_mask:0xf bound_ctrl:1
	v_pk_fma_f32 v[84:85], v[140:141], v[92:93], v[84:85]
	v_mov_b32_e32 v92, 1.0
	v_pk_fma_f32 v[124:125], v[142:143], v[124:125], v[84:85]
	v_add_f32_e32 v84, v42, v132
	v_mul_f32_e32 v84, 0xbfb8aa3b, v84
	v_exp_f32_e32 v84, v84
	ds_bpermute_b32 v94, v1, v124
	ds_bpermute_b32 v95, v1, v125
	v_cvt_pk_bf16_f32 v124, v124, v125
	v_add_f32_e32 v84, 1.0, v84
	v_rcp_f32_e32 v85, v84
	v_add_f32_e32 v84, v38, v136
	v_mul_f32_e32 v84, 0xbfb8aa3b, v84
	v_exp_f32_e32 v84, v84
	v_mul_f32_e32 v85, 0xc1000000, v85
	v_mul_f32_e32 v85, v2, v85
	v_mul_f32_e32 v85, 0x3fb8aa3b, v85
	v_exp_f32_e32 v130, v85
	v_add_f32_e32 v84, 1.0, v84
	v_rcp_f32_e32 v84, v84
	v_fma_f32 v85, -v130, v130, 1.0
	v_sqrt_f32_e32 v132, v85
	v_add_f32_e32 v85, v43, v133
	v_mul_f32_e32 v85, 0xbfb8aa3b, v85
	v_exp_f32_e32 v85, v85
	v_mov_b32_dpp v92, v130 row_shr:1 row_mask:0xf bank_mask:0xf
	v_add_f32_e32 v85, 1.0, v85
	v_rcp_f32_e32 v93, v85
	v_add_f32_e32 v85, v39, v137
	v_mul_f32_e32 v85, 0xbfb8aa3b, v85
	v_exp_f32_e32 v85, v85
	v_mul_f32_e32 v93, 0xc1000000, v93
	v_mul_f32_e32 v93, v148, v93
	v_mul_f32_e32 v93, 0x3fb8aa3b, v93
	v_exp_f32_e32 v131, v93
	v_add_f32_e32 v85, 1.0, v85
	v_rcp_f32_e32 v85, v85
	v_fma_f32 v93, -v131, v131, 1.0
	v_sqrt_f32_e32 v133, v93
	v_mov_b32_e32 v93, 1.0
	s_nop 1
	v_mov_b32_dpp v93, v131 row_shr:1 row_mask:0xf bank_mask:0xf
	v_pk_mul_f32 v[134:135], v[130:131], v[92:93]
	v_mov_b32_e32 v92, 1.0
	v_mov_b32_e32 v93, 1.0
	s_nop 0
	v_mov_b32_dpp v92, v134 row_shr:2 row_mask:0xf bank_mask:0xf
	v_mov_b32_dpp v93, v135 row_shr:2 row_mask:0xf bank_mask:0xf
	v_pk_mul_f32 v[136:137], v[134:135], v[92:93]
	v_mov_b32_e32 v92, 1.0
	v_mov_b32_e32 v93, 1.0
	s_nop 0
	v_mov_b32_dpp v92, v136 row_shr:4 row_mask:0xf bank_mask:0xf
	v_mov_b32_dpp v93, v137 row_shr:4 row_mask:0xf bank_mask:0xf
	v_pk_mul_f32 v[138:139], v[136:137], v[92:93]
	v_mov_b32_e32 v92, 1.0
	v_mov_b32_e32 v93, 1.0
	s_nop 0
	v_mov_b32_dpp v92, v138 row_shr:8 row_mask:0xf bank_mask:0xf
	v_mov_b32_dpp v93, v139 row_shr:8 row_mask:0xf bank_mask:0xf
	v_pk_mul_f32 v[140:141], v[138:139], v[92:93]
	v_add_u32_e32 v93, 0x20c8, v145
	ds_read2_b32 v[142:143], v93 offset1:1
	v_pk_mul_f32 v[86:87], v[140:141], v[86:87]
	ds_bpermute_b32 v92, v1, v86
	ds_bpermute_b32 v93, v1, v87
	s_waitcnt lgkmcnt(0)
	v_pk_mul_f32 v[84:85], v[84:85], v[142:143]
	s_nop 0
	v_pk_mul_f32 v[84:85], v[132:133], v[84:85]
	s_nop 1
	v_mov_b32_dpp v132, v84 row_shr:1 row_mask:0xf bank_mask:0xf bound_ctrl:1
	v_mov_b32_dpp v133, v85 row_shr:1 row_mask:0xf bank_mask:0xf bound_ctrl:1
	v_pk_fma_f32 v[84:85], v[130:131], v[132:133], v[84:85]
	s_nop 1
	v_mov_b32_dpp v130, v84 row_shr:2 row_mask:0xf bank_mask:0xf bound_ctrl:1
	v_mov_b32_dpp v131, v85 row_shr:2 row_mask:0xf bank_mask:0xf bound_ctrl:1
	v_pk_fma_f32 v[84:85], v[134:135], v[130:131], v[84:85]
	s_nop 1
	v_mov_b32_dpp v130, v84 row_shr:4 row_mask:0xf bank_mask:0xf bound_ctrl:1
	v_mov_b32_dpp v131, v85 row_shr:4 row_mask:0xf bank_mask:0xf bound_ctrl:1
	v_pk_fma_f32 v[84:85], v[136:137], v[130:131], v[84:85]
	s_nop 1
	v_mov_b32_dpp v130, v84 row_shr:8 row_mask:0xf bank_mask:0xf bound_ctrl:1
	v_mov_b32_dpp v131, v85 row_shr:8 row_mask:0xf bank_mask:0xf bound_ctrl:1
	v_pk_fma_f32 v[84:85], v[138:139], v[130:131], v[84:85]
	s_nop 0
	v_pk_fma_f32 v[122:123], v[140:141], v[122:123], v[84:85]
	ds_bpermute_b32 v84, v1, v122
	ds_bpermute_b32 v85, v1, v123
	v_cvt_pk_bf16_f32 v125, v122, v123
	v_cvt_pk_bf16_f32 v122, v128, v129
	v_cvt_pk_bf16_f32 v123, v86, v87
	global_store_dwordx2 v[96:97], v[124:125], off offset:32
	global_store_dwordx2 v[98:99], v[122:123], off offset:32
	v_mfma_f32_16x16x32_bf16 v[122:125], v[72:75], v[4:7], 0
	v_mfma_f32_16x16x32_bf16 v[72:75], v[76:79], v[20:23], v[68:71]
	v_mfma_f32_16x16x32_bf16 v[68:71], v[80:83], v[20:23], v[122:125]
	s_nop 6
	v_add_f32_e32 v40, v40, v72
	v_add_f32_e32 v41, v41, v73
	v_add_f32_e32 v42, v42, v74
	v_mul_f32_e32 v40, 0xbfb8aa3b, v40
	v_mul_f32_e32 v41, 0xbfb8aa3b, v41
	v_mul_f32_e32 v42, 0xbfb8aa3b, v42
	v_exp_f32_e32 v40, v40
	v_exp_f32_e32 v41, v41
	v_exp_f32_e32 v42, v42
	v_add_f32_e32 v36, v36, v68
	v_add_f32_e32 v37, v37, v69
	v_add_f32_e32 v38, v38, v70
	v_mul_f32_e32 v36, 0xbfb8aa3b, v36
	v_mul_f32_e32 v37, 0xbfb8aa3b, v37
	v_mul_f32_e32 v38, 0xbfb8aa3b, v38
	v_add_f32_e32 v40, 1.0, v40
	v_exp_f32_e32 v36, v36
	v_add_f32_e32 v41, 1.0, v41
	v_exp_f32_e32 v37, v37
	v_add_f32_e32 v42, 1.0, v42
	v_exp_f32_e32 v38, v38
	v_rcp_f32_e32 v72, v40
	v_rcp_f32_e32 v68, v41
	v_rcp_f32_e32 v42, v42
	v_add_f32_e32 v36, 1.0, v36
	v_add_f32_e32 v37, 1.0, v37
	v_add_f32_e32 v38, 1.0, v38
	v_rcp_f32_e32 v40, v36
	v_mul_f32_e32 v36, 0xc1000000, v72
	v_rcp_f32_e32 v41, v37
	v_mul_f32_e32 v37, 0xc1000000, v68
	v_rcp_f32_e32 v70, v38
	v_mul_f32_e32 v38, 0xc1000000, v42
; __device__ __forceinline__ unsigned pk2(float lo, float hi) { const f32x2_t v = {lo, hi}; const bf16x2_t b = __builtin_convertvector(v, bf16x2_t); return __builtin_bit_cast(unsigned, b); }
; __device__ __forceinline__ float sigmoidf_(float x) { return __builtin_amdgcn_rcpf(1.0f + __expf(-x)); }
; __device__ __forceinline__ float bcast15(float v, int lane) { return bperm_f((lane & 48) | 15, v); }
; __device__ __forceinline__ void w_lru_m1(const Args& a, int l, unsigned char* ws, const bf16_t* proj, bf16_t* y, LAS unsigned char* wl, int b, int ck_, int h, int lane) {
;     ...
;             for (int r = 0; r < 4; ++r) {
;                 const float rg = sigmoidf_(ga[r] + bav[r]), ig = sigmoidf_(gx[r] + bxv[r]);
;                 const float la = -8.0f * rg * sp[r]; float A = __expf(la);
;                 float U = __builtin_amdgcn_sqrtf(1.0f - A * A) * (ig * xcf[tok * 65 + j0 + r]);
;                 { const float As = dpp_shr1<1>(A), Us = dpp_shr0<1>(U); U = A * Us + U; A = A * As; }
;                 { const float As = dpp_shr1<2>(A), Us = dpp_shr0<2>(U); U = A * Us + U; A = A * As; }
;                 { const float As = dpp_shr1<4>(A), Us = dpp_shr0<4>(U); U = A * Us + U; A = A * As; }
;                 { const float As = dpp_shr1<8>(A), Us = dpp_shr0<8>(U); U = A * Us + U; A = A * As; }
;                 const float hh = U + A * hc[r], PP = A * Pc[r];
;                 hc[r] = bcast15(hh, lane); Pc[r] = bcast15(PP, lane); hv[r] = hh; pv[r] = PP; }
;             *(unsigned long long*)(y + (size_t)(row0 + tok) * DM + 64 * h + j0) = (unsigned long long)pk2(hv[0], hv[1]) | ((unsigned long long)pk2(hv[2], hv[3]) << 32);
;             *(unsigned long long*)((bf16_t*)(ws + WS_P) + (size_t)(row0 + tok) * 512 + 64 * h + j0) = (unsigned long long)pk2(pv[0], pv[1]) | ((unsigned long long)pk2(pv[2], pv[3]) << 32);
;         }
;         if (lo == 0) { const size_t so = (size_t)(b * NCH + ck_) * 512 + 64 * h + j0;
; #pragma unroll
;             for (int r = 0; r < 4; ++r) { ((float*)(ws + WS_LRUA))[so + r] = Pc[r]; ((float*)(ws + WS_LRUH))[so + r] = hc[r]; } }
	v_mul_f32_e32 v36, v147, v36
	v_mul_f32_e32 v37, v149, v37
	v_mul_f32_e32 v2, v2, v38
	v_mul_f32_e32 v36, 0x3fb8aa3b, v36
	v_mul_f32_e32 v37, 0x3fb8aa3b, v37
	v_mul_f32_e32 v2, 0x3fb8aa3b, v2
	v_exp_f32_e32 v72, v36
	v_exp_f32_e32 v73, v37
	v_exp_f32_e32 v42, v2
	v_add_f32_e32 v39, v39, v71
	v_fma_f32 v36, -v72, v72, 1.0
	v_fma_f32 v37, -v73, v73, 1.0
	v_fma_f32 v2, -v42, v42, 1.0
	v_sqrt_f32_e32 v76, v36
	v_mov_b32_e32 v36, 1.0
	v_sqrt_f32_e32 v77, v37
	v_mov_b32_e32 v37, 1.0
	v_sqrt_f32_e32 v74, v2
	v_add_f32_e32 v2, v43, v75
	v_mov_b32_dpp v36, v72 row_shr:1 row_mask:0xf bank_mask:0xf
	v_mov_b32_dpp v37, v73 row_shr:1 row_mask:0xf bank_mask:0xf
	v_mul_f32_e32 v2, 0xbfb8aa3b, v2
	v_pk_mul_f32 v[78:79], v[72:73], v[36:37]
	v_mov_b32_e32 v36, 1.0
	v_mov_b32_e32 v37, 1.0
	v_exp_f32_e32 v2, v2
	v_mov_b32_dpp v36, v78 row_shr:2 row_mask:0xf bank_mask:0xf
	v_mov_b32_dpp v37, v79 row_shr:2 row_mask:0xf bank_mask:0xf
	v_pk_mul_f32 v[80:81], v[78:79], v[36:37]
	v_mov_b32_e32 v36, 1.0
	v_mov_b32_e32 v37, 1.0
	v_add_f32_e32 v2, 1.0, v2
	v_mov_b32_dpp v36, v80 row_shr:4 row_mask:0xf bank_mask:0xf
	v_mov_b32_dpp v37, v81 row_shr:4 row_mask:0xf bank_mask:0xf
	v_pk_mul_f32 v[82:83], v[80:81], v[36:37]
	v_mov_b32_e32 v36, 1.0
	v_mov_b32_e32 v37, 1.0
	v_rcp_f32_e32 v2, v2
	v_mov_b32_dpp v36, v82 row_shr:8 row_mask:0xf bank_mask:0xf
	v_mov_b32_dpp v37, v83 row_shr:8 row_mask:0xf bank_mask:0xf
	v_pk_mul_f32 v[86:87], v[82:83], v[36:37]
	v_add_u32_e32 v37, 0x3100, v145
	ds_read2_b32 v[122:123], v37 offset1:1
	v_mul_f32_e32 v39, 0xbfb8aa3b, v39
	v_mul_f32_e32 v2, 0xc1000000, v2
	v_exp_f32_e32 v39, v39
	v_mul_f32_e32 v2, v148, v2
	v_mul_f32_e32 v2, 0x3fb8aa3b, v2
	s_waitcnt lgkmcnt(0)
	v_pk_mul_f32 v[40:41], v[122:123], v[40:41]
	v_exp_f32_e32 v43, v2
	v_pk_mul_f32 v[40:41], v[40:41], v[76:77]
	v_add_f32_e32 v39, 1.0, v39
	v_mov_b32_e32 v38, 1.0
	v_mov_b32_dpp v76, v40 row_shr:1 row_mask:0xf bank_mask:0xf bound_ctrl:1
	v_mov_b32_dpp v77, v41 row_shr:1 row_mask:0xf bank_mask:0xf bound_ctrl:1
	v_pk_fma_f32 v[40:41], v[72:73], v[76:77], v[40:41]
	v_rcp_f32_e32 v71, v39
	v_mov_b32_e32 v39, 1.0
	v_mov_b32_dpp v72, v40 row_shr:2 row_mask:0xf bank_mask:0xf bound_ctrl:1
	v_mov_b32_dpp v73, v41 row_shr:2 row_mask:0xf bank_mask:0xf bound_ctrl:1
	v_mov_b32_dpp v38, v42 row_shr:1 row_mask:0xf bank_mask:0xf
	v_mov_b32_dpp v39, v43 row_shr:1 row_mask:0xf bank_mask:0xf
	v_pk_fma_f32 v[40:41], v[78:79], v[72:73], v[40:41]
	v_pk_mul_f32 v[78:79], v[42:43], v[38:39]
	v_mov_b32_e32 v38, 1.0
	v_mov_b32_e32 v39, 1.0
	v_mov_b32_dpp v72, v40 row_shr:4 row_mask:0xf bank_mask:0xf bound_ctrl:1
	v_mov_b32_dpp v73, v41 row_shr:4 row_mask:0xf bank_mask:0xf bound_ctrl:1
	v_mov_b32_dpp v38, v78 row_shr:2 row_mask:0xf bank_mask:0xf
	v_mov_b32_dpp v39, v79 row_shr:2 row_mask:0xf bank_mask:0xf
	v_pk_fma_f32 v[40:41], v[80:81], v[72:73], v[40:41]
	v_pk_mul_f32 v[80:81], v[78:79], v[38:39]
	v_mov_b32_e32 v38, 1.0
	v_mov_b32_e32 v39, 1.0
	v_mov_b32_dpp v72, v40 row_shr:8 row_mask:0xf bank_mask:0xf bound_ctrl:1
	v_mov_b32_dpp v73, v41 row_shr:8 row_mask:0xf bank_mask:0xf bound_ctrl:1
	v_mov_b32_dpp v38, v80 row_shr:4 row_mask:0xf bank_mask:0xf
	v_mov_b32_dpp v39, v81 row_shr:4 row_mask:0xf bank_mask:0xf
	v_pk_fma_f32 v[40:41], v[82:83], v[72:73], v[40:41]
	v_pk_mul_f32 v[82:83], v[80:81], v[38:39]
	v_mov_b32_e32 v38, 1.0
	v_mov_b32_e32 v39, 1.0
	v_fma_f32 v2, -v43, v43, 1.0
	v_mov_b32_dpp v38, v82 row_shr:8 row_mask:0xf bank_mask:0xf
	v_mov_b32_dpp v39, v83 row_shr:8 row_mask:0xf bank_mask:0xf
	v_pk_mul_f32 v[68:69], v[86:87], v[126:127]
	v_pk_fma_f32 v[72:73], v[86:87], v[94:95], v[40:41]
	v_sqrt_f32_e32 v75, v2
	v_pk_mul_f32 v[86:87], v[82:83], v[38:39]
	v_add_u32_e32 v2, 0x3108, v145
	v_pk_mul_f32 v[76:77], v[86:87], v[92:93]
	ds_read2_b32 v[92:93], v2 offset1:1
	ds_bpermute_b32 v36, v1, v68
	ds_bpermute_b32 v40, v1, v72
	ds_bpermute_b32 v41, v1, v73
	ds_bpermute_b32 v37, v1, v69
	s_waitcnt lgkmcnt(0)
	v_pk_mul_f32 v[70:71], v[70:71], v[92:93]
	ds_bpermute_b32 v38, v1, v76
	v_pk_mul_f32 v[70:71], v[74:75], v[70:71]
	ds_bpermute_b32 v39, v1, v77
	v_cvt_pk_bf16_f32 v72, v72, v73
	v_mov_b32_dpp v74, v70 row_shr:1 row_mask:0xf bank_mask:0xf bound_ctrl:1
	v_mov_b32_dpp v75, v71 row_shr:1 row_mask:0xf bank_mask:0xf bound_ctrl:1
	v_pk_fma_f32 v[42:43], v[42:43], v[74:75], v[70:71]
	v_cvt_pk_bf16_f32 v68, v68, v69
	v_cvt_pk_bf16_f32 v69, v76, v77
	v_mov_b32_dpp v70, v42 row_shr:2 row_mask:0xf bank_mask:0xf bound_ctrl:1
	v_mov_b32_dpp v71, v43 row_shr:2 row_mask:0xf bank_mask:0xf bound_ctrl:1
	v_pk_fma_f32 v[42:43], v[78:79], v[70:71], v[42:43]
	s_nop 1
	v_mov_b32_dpp v70, v42 row_shr:4 row_mask:0xf bank_mask:0xf bound_ctrl:1
	v_mov_b32_dpp v71, v43 row_shr:4 row_mask:0xf bank_mask:0xf bound_ctrl:1
	v_pk_fma_f32 v[42:43], v[80:81], v[70:71], v[42:43]
	s_nop 1
	v_mov_b32_dpp v70, v42 row_shr:8 row_mask:0xf bank_mask:0xf bound_ctrl:1
	v_mov_b32_dpp v71, v43 row_shr:8 row_mask:0xf bank_mask:0xf bound_ctrl:1
	v_pk_fma_f32 v[42:43], v[82:83], v[70:71], v[42:43]
	s_nop 0
	v_pk_fma_f32 v[70:71], v[86:87], v[84:85], v[42:43]
	ds_bpermute_b32 v42, v1, v70
	ds_bpermute_b32 v43, v1, v71
	v_cvt_pk_bf16_f32 v73, v70, v71
	global_store_dwordx2 v[114:115], v[72:73], off offset:32
	global_store_dwordx2 v[116:117], v[68:69], off offset:32
	s_and_saveexec_b64 s[34:35], vcc
	s_cbranch_execz .LBB0_525
	v_add_u32_e32 v68, 16, v0
	v_ashrrev_i32_e32 v69, 31, v68
	v_lshl_add_u64 v[68:69], s[42:43], 0, v[68:69]
	v_lshlrev_b64 v[68:69], 2, v[68:69]
	v_lshl_add_u64 v[70:71], s[84:85], 0, v[68:69]
	v_lshl_add_u64 v[68:69], s[86:87], 0, v[68:69]
	s_waitcnt lgkmcnt(0)
	global_store_dwordx4 v[70:71], v[36:39], off
	global_store_dwordx4 v[68:69], v[40:43], off
; __device__ __forceinline__ void w_lru_m1(const Args& a, int l, unsigned char* ws, const bf16_t* proj, bf16_t* y, LAS unsigned char* wl, int b, int ck_, int h, int lane) {
;     ...
;         if (jb < 3) {
; #pragma unroll
;             for (int kk = 0; kk < 2; ++kk) { nWa[kk] = *(const bf16x8*)(waT + (16 * (jb + 1) + lo) * 64 + 32 * kk + 8 * fq); nWx[kk] = *(const bf16x8*)(wxT + (16 * (jb + 1) + lo) * 64 + 32 * kk + 8 * fq); }
;             nba = *(const f32x4*)(ba + 16 * (jb + 1) + 4 * fq); nbx = *(const f32x4*)(bx + 16 * (jb + 1) + 4 * fq); nlam = *(const f32x4*)(lam + 16 * (jb + 1) + 4 * fq);
;         }
;         const int j0 = 16 * jb + 4 * fq;
;         float bav[4], bxv[4], sp[4], hc[4], Pc[4];
; #pragma unroll
;         for (int r = 0; r < 4; ++r) { bav[r] = pba[r]; bxv[r] = pbx[r]; sp[r] = log1pf(__expf(-plam[r])); hc[r] = 0.f; Pc[r] = 1.f; }
; #pragma unroll
;         for (int tb = 0; tb < 4; ++tb) { const int tok = 16 * tb + lo;
;             f32x4 ga = {0.f, 0.f, 0.f, 0.f}, gx = {0.f, 0.f, 0.f, 0.f};
; #pragma unroll
;             for (int kk = 0; kk < 2; ++kk) { ga = __builtin_amdgcn_mfma_f32_16x16x32_bf16(WaF[kk], Xf[tb][kk], ga, 0, 0, 0); gx = __builtin_amdgcn_mfma_f32_16x16x32_bf16(WxF[kk], Xf[tb][kk], gx, 0, 0, 0); }
;             float hv[4], pv[4];
; #pragma unroll
;             for (int r = 0; r < 4; ++r) {
;                 const float rg = sigmoidf_(ga[r] + bav[r]), ig = sigmoidf_(gx[r] + bxv[r]);
;                 const float la = -8.0f * rg * sp[r]; float A = __expf(la);
;                 float U = __builtin_amdgcn_sqrtf(1.0f - A * A) * (ig * xcf[tok * 65 + j0 + r]);
;                 { const float As = dpp_shr1<1>(A), Us = dpp_shr0<1>(U); U = A * Us + U; A = A * As; }
;                 { const float As = dpp_shr1<2>(A), Us = dpp_shr0<2>(U); U = A * Us + U; A = A * As; }
;                 { const float As = dpp_shr1<4>(A), Us = dpp_shr0<4>(U); U = A * Us + U; A = A * As; }
;                 { const float As = dpp_shr1<8>(A), Us = dpp_shr0<8>(U); U = A * Us + U; A = A * As; }
;                 const float hh = U + A * hc[r], PP = A * Pc[r];
;                 hc[r] = bcast15(hh, lane); Pc[r] = bcast15(PP, lane); hv[r] = hh; pv[r] = PP; }
;             *(unsigned long long*)(y + (size_t)(row0 + tok) * DM + 64 * h + j0) = (unsigned long long)pk2(hv[0], hv[1]) | ((unsigned long long)pk2(hv[2], hv[3]) << 32);
.LBB0_525:
	s_or_b64 exec, exec, s[34:35]
	v_lshl_or_b32 v2, v146, 1, v210
	v_lshl_add_u64 v[36:37], v[118:119], 0, v[2:3]
	s_waitcnt lgkmcnt(0)
	v_lshl_add_u64 v[38:39], v[120:121], 0, v[2:3]
	s_waitcnt vmcnt(8)
	s_nop 7
	global_load_dwordx4 v[68:71], v[36:37], off
	global_load_dwordx4 v[72:75], v[38:39], off
	global_load_dwordx4 v[76:79], v[36:37], off offset:64
	global_load_dwordx4 v[80:83], v[38:39], off offset:64
	global_load_dwordx4 v[40:43], v[108:109], off offset:192
	s_nop 0
	global_load_dwordx4 v[36:39], v[110:111], off offset:192
	global_load_dwordx4 v[84:87], v[112:113], off offset:192
	ds_read2_b32 v[124:125], v145 offset0:32 offset1:33
	ds_read2_b32 v[128:129], v145 offset0:34 offset1:35
	s_nop 7
	s_nop 0
	s_nop 7
	s_nop 0
	s_nop 7
	s_nop 0
	s_nop 7
	s_nop 1
	s_nop 7
	s_nop 1
	s_nop 7
	s_nop 1
	s_nop 7
	v_mov_b32_e32 v2, v88
	s_nop 7
	s_nop 0
	s_nop 7
	s_nop 0
	s_nop 7
	s_nop 0
	s_nop 7
	s_nop 0
	s_nop 7
	s_nop 0
	s_nop 7
	s_nop 0
	s_nop 7
	s_nop 1
	s_nop 7
	s_nop 1
	s_nop 7
	s_nop 1
	s_nop 7
	v_mov_b32_e32 v134, v89
	s_nop 7
	s_nop 0
	s_nop 7
	s_nop 0
	s_nop 7
	s_nop 0
	s_nop 7
	s_nop 0
	s_nop 7
	s_nop 0
	s_nop 7
	s_nop 0
	s_nop 7
	s_nop 1
	s_nop 7
	s_nop 1
	s_nop 7
	s_nop 1
	s_nop 7
	v_mov_b32_e32 v135, v90
	s_nop 7
	s_nop 0
	s_nop 7
	s_nop 0
	s_nop 7
	s_nop 0
	s_nop 7
	s_nop 0
	s_nop 7
	s_nop 0
	s_nop 7
	s_nop 0
	s_nop 7
	v_mfma_f32_16x16x32_bf16 v[92:95], v[60:63], v[16:19], 0
	s_nop 0
	s_nop 7
	v_mfma_f32_16x16x32_bf16 v[110:113], v[52:55], v[32:35], v[92:95]
	s_nop 0
	s_nop 7
	s_nop 1
	s_nop 7
	v_mov_b32_e32 v136, v91
	v_mfma_f32_16x16x32_bf16 v[88:91], v[64:67], v[16:19], 0
	s_nop 0
	v_add_f32_e32 v92, v44, v110
	v_add_f32_e32 v93, v45, v111
	v_mul_f32_e32 v92, 0xbfb8aa3b, v92
	v_mfma_f32_16x16x32_bf16 v[88:91], v[56:59], v[32:35], v[88:91]
	v_mul_f32_e32 v93, 0xbfb8aa3b, v93
	v_exp_f32_e32 v92, v92
	v_exp_f32_e32 v93, v93
	v_add_f32_e32 v92, 1.0, v92
	v_add_f32_e32 v93, 1.0, v93
	s_nop 2
	v_add_f32_e32 v88, v48, v88
	v_add_f32_e32 v89, v49, v89
	v_mul_f32_e32 v88, 0xbfb8aa3b, v88
	v_mul_f32_e32 v89, 0xbfb8aa3b, v89
	v_exp_f32_e32 v88, v88
	v_exp_f32_e32 v89, v89
	v_rcp_f32_e32 v92, v92
	v_rcp_f32_e32 v93, v93
	v_add_f32_e32 v88, 1.0, v88
	v_add_f32_e32 v89, 1.0, v89
	v_rcp_f32_e32 v88, v88
	v_rcp_f32_e32 v89, v89
	s_waitcnt lgkmcnt(0)
	v_pk_mul_f32 v[92:93], v[124:125], v[92:93]
	v_add_f32_e32 v90, v50, v90
	v_mul_f32_e32 v88, 0xc1000000, v88
	v_mul_f32_e32 v89, 0xc1000000, v89
	v_mul_f32_e32 v88, v2, v88
	v_mul_f32_e32 v89, v134, v89
	v_mul_f32_e32 v88, 0x3fb8aa3b, v88
	v_mul_f32_e32 v89, 0x3fb8aa3b, v89
	v_exp_f32_e32 v108, v88
	v_exp_f32_e32 v109, v89
	v_add_f32_e32 v91, v51, v91
	v_mul_f32_e32 v90, 0xbfb8aa3b, v90
	v_fma_f32 v88, -v108, v108, 1.0
	v_fma_f32 v89, -v109, v109, 1.0
	v_sqrt_f32_e32 v110, v88
	v_sqrt_f32_e32 v111, v89
	v_mov_b32_e32 v88, 1.0
	v_mov_b32_e32 v89, 1.0
	v_mul_f32_e32 v91, 0xbfb8aa3b, v91
	v_pk_mul_f32 v[92:93], v[92:93], v[110:111]
	v_mov_b32_dpp v88, v108 row_shr:1 row_mask:0xf bank_mask:0xf
	v_mov_b32_dpp v89, v109 row_shr:1 row_mask:0xf bank_mask:0xf
	v_mov_b32_dpp v110, v92 row_shr:1 row_mask:0xf bank_mask:0xf bound_ctrl:1
	v_mov_b32_dpp v111, v93 row_shr:1 row_mask:0xf bank_mask:0xf bound_ctrl:1
	v_pk_fma_f32 v[92:93], v[108:109], v[110:111], v[92:93]
	v_pk_mul_f32 v[118:119], v[108:109], v[88:89]
	v_mov_b32_e32 v88, 1.0
	v_mov_b32_e32 v89, 1.0
	v_mov_b32_dpp v108, v92 row_shr:2 row_mask:0xf bank_mask:0xf bound_ctrl:1
	v_mov_b32_dpp v109, v93 row_shr:2 row_mask:0xf bank_mask:0xf bound_ctrl:1
	v_exp_f32_e32 v90, v90
	v_exp_f32_e32 v91, v91
	v_mov_b32_dpp v88, v118 row_shr:2 row_mask:0xf bank_mask:0xf
	v_mov_b32_dpp v89, v119 row_shr:2 row_mask:0xf bank_mask:0xf
	v_pk_fma_f32 v[92:93], v[118:119], v[108:109], v[92:93]
	v_pk_mul_f32 v[120:121], v[118:119], v[88:89]
	v_mov_b32_e32 v88, 1.0
	v_mov_b32_e32 v89, 1.0
	v_mov_b32_dpp v108, v92 row_shr:4 row_mask:0xf bank_mask:0xf bound_ctrl:1
	v_mov_b32_dpp v109, v93 row_shr:4 row_mask:0xf bank_mask:0xf bound_ctrl:1
	v_mov_b32_dpp v88, v120 row_shr:4 row_mask:0xf bank_mask:0xf
	v_mov_b32_dpp v89, v121 row_shr:4 row_mask:0xf bank_mask:0xf
	v_pk_fma_f32 v[92:93], v[120:121], v[108:109], v[92:93]
	v_pk_mul_f32 v[122:123], v[120:121], v[88:89]
	v_add_f32_e32 v90, 1.0, v90
	v_mov_b32_dpp v108, v92 row_shr:8 row_mask:0xf bank_mask:0xf bound_ctrl:1
	v_mov_b32_dpp v109, v93 row_shr:8 row_mask:0xf bank_mask:0xf bound_ctrl:1
	v_add_f32_e32 v91, 1.0, v91
	v_pk_fma_f32 v[92:93], v[122:123], v[108:109], v[92:93]
	v_rcp_f32_e32 v90, v90
	v_add_f32_e32 v108, v46, v112
	v_rcp_f32_e32 v91, v91
	v_add_f32_e32 v109, v47, v113
	v_mul_f32_e32 v108, 0xbfb8aa3b, v108
	v_mul_f32_e32 v109, 0xbfb8aa3b, v109
	v_exp_f32_e32 v108, v108
	v_exp_f32_e32 v109, v109
	v_mul_f32_e32 v90, 0xc1000000, v90
	v_mul_f32_e32 v91, 0xc1000000, v91
	v_mul_f32_e32 v90, v135, v90
	v_mul_f32_e32 v91, v136, v91
	v_add_f32_e32 v108, 1.0, v108
	v_mul_f32_e32 v90, 0x3fb8aa3b, v90
	v_add_f32_e32 v109, 1.0, v109
	v_mul_f32_e32 v91, 0x3fb8aa3b, v91
	v_rcp_f32_e32 v112, v108
	v_exp_f32_e32 v108, v90
	v_rcp_f32_e32 v113, v109
	v_exp_f32_e32 v109, v91
	v_mov_b32_e32 v88, 1.0
	v_fma_f32 v90, -v108, v108, 1.0
	v_sqrt_f32_e32 v118, v90
	v_fma_f32 v91, -v109, v109, 1.0
	v_sqrt_f32_e32 v119, v91
	v_pk_mul_f32 v[112:113], v[112:113], v[128:129]
	v_mov_b32_e32 v89, 1.0
	v_mov_b32_e32 v90, 1.0
	v_mov_b32_e32 v91, 1.0
	v_pk_mul_f32 v[112:113], v[118:119], v[112:113]
	v_mov_b32_dpp v88, v122 row_shr:8 row_mask:0xf bank_mask:0xf
	v_mov_b32_dpp v89, v123 row_shr:8 row_mask:0xf bank_mask:0xf
	v_mov_b32_dpp v90, v108 row_shr:1 row_mask:0xf bank_mask:0xf
	v_mov_b32_dpp v91, v109 row_shr:1 row_mask:0xf bank_mask:0xf
; __device__ __forceinline__ unsigned pk2(float lo, float hi) { const f32x2_t v = {lo, hi}; const bf16x2_t b = __builtin_convertvector(v, bf16x2_t); return __builtin_bit_cast(unsigned, b); }
; __device__ __forceinline__ float sigmoidf_(float x) { return __builtin_amdgcn_rcpf(1.0f + __expf(-x)); }
; __device__ __forceinline__ float bcast15(float v, int lane) { return bperm_f((lane & 48) | 15, v); }
; __device__ __forceinline__ void w_lru_m1(const Args& a, int l, unsigned char* ws, const bf16_t* proj, bf16_t* y, LAS unsigned char* wl, int b, int ck_, int h, int lane) {
;     ...
;         for (int tb = 0; tb < 4; ++tb) { const int tok = 16 * tb + lo;
;             f32x4 ga = {0.f, 0.f, 0.f, 0.f}, gx = {0.f, 0.f, 0.f, 0.f};
; #pragma unroll
;             for (int kk = 0; kk < 2; ++kk) { ga = __builtin_amdgcn_mfma_f32_16x16x32_bf16(WaF[kk], Xf[tb][kk], ga, 0, 0, 0); gx = __builtin_amdgcn_mfma_f32_16x16x32_bf16(WxF[kk], Xf[tb][kk], gx, 0, 0, 0); }
;             float hv[4], pv[4];
; #pragma unroll
;             for (int r = 0; r < 4; ++r) {
;                 const float rg = sigmoidf_(ga[r] + bav[r]), ig = sigmoidf_(gx[r] + bxv[r]);
;                 const float la = -8.0f * rg * sp[r]; float A = __expf(la);
;                 float U = __builtin_amdgcn_sqrtf(1.0f - A * A) * (ig * xcf[tok * 65 + j0 + r]);
;                 { const float As = dpp_shr1<1>(A), Us = dpp_shr0<1>(U); U = A * Us + U; A = A * As; }
;                 { const float As = dpp_shr1<2>(A), Us = dpp_shr0<2>(U); U = A * Us + U; A = A * As; }
;                 { const float As = dpp_shr1<4>(A), Us = dpp_shr0<4>(U); U = A * Us + U; A = A * As; }
;                 { const float As = dpp_shr1<8>(A), Us = dpp_shr0<8>(U); U = A * Us + U; A = A * As; }
;                 const float hh = U + A * hc[r], PP = A * Pc[r];
;                 hc[r] = bcast15(hh, lane); Pc[r] = bcast15(PP, lane); hv[r] = hh; pv[r] = PP; }
;             *(unsigned long long*)(y + (size_t)(row0 + tok) * DM + 64 * h + j0) = (unsigned long long)pk2(hv[0], hv[1]) | ((unsigned long long)pk2(hv[2], hv[3]) << 32);
;             *(unsigned long long*)((bf16_t*)(ws + WS_P) + (size_t)(row0 + tok) * 512 + 64 * h + j0) = (unsigned long long)pk2(pv[0], pv[1]) | ((unsigned long long)pk2(pv[2], pv[3]) << 32);
;         }
	v_mov_b32_dpp v118, v112 row_shr:1 row_mask:0xf bank_mask:0xf bound_ctrl:1
	v_mov_b32_dpp v119, v113 row_shr:1 row_mask:0xf bank_mask:0xf bound_ctrl:1
	v_pk_mul_f32 v[94:95], v[122:123], v[88:89]
	v_pk_mul_f32 v[122:123], v[108:109], v[90:91]
	v_mov_b32_e32 v90, 1.0
	v_mov_b32_e32 v91, 1.0
	v_pk_fma_f32 v[108:109], v[108:109], v[118:119], v[112:113]
	v_mov_b32_dpp v90, v122 row_shr:2 row_mask:0xf bank_mask:0xf
	v_mov_b32_dpp v91, v123 row_shr:2 row_mask:0xf bank_mask:0xf
	v_mov_b32_dpp v112, v108 row_shr:2 row_mask:0xf bank_mask:0xf bound_ctrl:1
	v_mov_b32_dpp v113, v109 row_shr:2 row_mask:0xf bank_mask:0xf bound_ctrl:1
	v_pk_mul_f32 v[124:125], v[122:123], v[90:91]
	v_mov_b32_e32 v90, 1.0
	v_mov_b32_e32 v91, 1.0
	v_pk_fma_f32 v[108:109], v[122:123], v[112:113], v[108:109]
	v_mov_b32_dpp v90, v124 row_shr:4 row_mask:0xf bank_mask:0xf
	v_mov_b32_dpp v91, v125 row_shr:4 row_mask:0xf bank_mask:0xf
	v_mov_b32_dpp v112, v108 row_shr:4 row_mask:0xf bank_mask:0xf bound_ctrl:1
	v_mov_b32_dpp v113, v109 row_shr:4 row_mask:0xf bank_mask:0xf bound_ctrl:1
	v_pk_mul_f32 v[126:127], v[124:125], v[90:91]
	v_mov_b32_e32 v90, 1.0
	v_mov_b32_e32 v91, 1.0
	v_pk_fma_f32 v[108:109], v[124:125], v[112:113], v[108:109]
	v_mov_b32_dpp v90, v126 row_shr:8 row_mask:0xf bank_mask:0xf
	v_mov_b32_dpp v91, v127 row_shr:8 row_mask:0xf bank_mask:0xf
	v_mov_b32_dpp v112, v108 row_shr:8 row_mask:0xf bank_mask:0xf bound_ctrl:1
	v_mov_b32_dpp v113, v109 row_shr:8 row_mask:0xf bank_mask:0xf bound_ctrl:1
	v_pk_mul_f32 v[120:121], v[126:127], v[90:91]
	v_pk_fma_f32 v[108:109], v[126:127], v[112:113], v[108:109]
	v_pk_fma_f32 v[110:111], v[94:95], 0, v[92:93] op_sel_hi:[1,0,1]
	v_pk_fma_f32 v[112:113], v[120:121], 0, v[108:109] op_sel_hi:[1,0,1]
	ds_bpermute_b32 v92, v1, v110
	ds_bpermute_b32 v93, v1, v111
	v_cvt_pk_bf16_f32 v110, v110, v111
	v_cvt_pk_bf16_f32 v111, v112, v113
	ds_bpermute_b32 v108, v1, v112
	ds_bpermute_b32 v109, v1, v113
	global_store_dwordx2 v[100:101], v[110:111], off offset:64
	v_mfma_f32_16x16x32_bf16 v[110:113], v[64:67], v[12:15], 0
	ds_bpermute_b32 v88, v1, v94
	ds_bpermute_b32 v89, v1, v95
	v_cvt_pk_bf16_f32 v94, v94, v95
	v_mfma_f32_16x16x32_bf16 v[122:125], v[56:59], v[28:31], v[110:113]
	v_cvt_pk_bf16_f32 v95, v120, v121
	global_store_dwordx2 v[102:103], v[94:95], off offset:64
	ds_bpermute_b32 v90, v1, v120
	ds_bpermute_b32 v91, v1, v121
	v_mfma_f32_16x16x32_bf16 v[118:121], v[60:63], v[12:15], 0
	s_nop 2
	v_add_f32_e32 v94, v48, v122
	v_mul_f32_e32 v94, 0xbfb8aa3b, v94
	v_exp_f32_e32 v94, v94
	v_mfma_f32_16x16x32_bf16 v[118:121], v[52:55], v[28:31], v[118:121]
	v_mov_b32_e32 v112, 1.0
	v_add_f32_e32 v94, 1.0, v94
	v_rcp_f32_e32 v95, v94
	s_nop 0
	v_mul_f32_e32 v95, 0xc1000000, v95
	v_mul_f32_e32 v95, v2, v95
	v_mul_f32_e32 v95, 0x3fb8aa3b, v95
	v_exp_f32_e32 v110, v95
	v_add_f32_e32 v94, v44, v118
	v_mul_f32_e32 v94, 0xbfb8aa3b, v94
	v_exp_f32_e32 v94, v94
	v_fma_f32 v95, -v110, v110, 1.0
	v_sqrt_f32_e32 v118, v95
	v_add_f32_e32 v95, v49, v123
	v_mul_f32_e32 v95, 0xbfb8aa3b, v95
	v_exp_f32_e32 v95, v95
	v_mov_b32_dpp v112, v110 row_shr:1 row_mask:0xf bank_mask:0xf
	v_add_f32_e32 v94, 1.0, v94
	v_rcp_f32_e32 v94, v94
	v_add_f32_e32 v95, 1.0, v95
	v_rcp_f32_e32 v111, v95
	v_add_f32_e32 v95, v45, v119
	v_mul_f32_e32 v95, 0xbfb8aa3b, v95
	v_exp_f32_e32 v95, v95
	v_mul_f32_e32 v111, 0xc1000000, v111
	v_mul_f32_e32 v111, v134, v111
	v_mul_f32_e32 v111, 0x3fb8aa3b, v111
	v_exp_f32_e32 v111, v111
	v_add_f32_e32 v95, 1.0, v95
	v_rcp_f32_e32 v95, v95
	v_fma_f32 v113, -v111, v111, 1.0
	v_sqrt_f32_e32 v119, v113
	v_mov_b32_e32 v113, 1.0
	s_nop 1
	v_mov_b32_dpp v113, v111 row_shr:1 row_mask:0xf bank_mask:0xf
	v_pk_mul_f32 v[122:123], v[110:111], v[112:113]
	v_mov_b32_e32 v112, 1.0
	v_mov_b32_e32 v113, 1.0
	s_nop 0
	v_mov_b32_dpp v112, v122 row_shr:2 row_mask:0xf bank_mask:0xf
	v_mov_b32_dpp v113, v123 row_shr:2 row_mask:0xf bank_mask:0xf
	v_pk_mul_f32 v[126:127], v[122:123], v[112:113]
	v_mov_b32_e32 v112, 1.0
	v_mov_b32_e32 v113, 1.0
	s_nop 0
	v_mov_b32_dpp v112, v126 row_shr:4 row_mask:0xf bank_mask:0xf
	v_mov_b32_dpp v113, v127 row_shr:4 row_mask:0xf bank_mask:0xf
	v_pk_mul_f32 v[128:129], v[126:127], v[112:113]
	v_mov_b32_e32 v112, 1.0
	v_mov_b32_e32 v113, 1.0
	s_nop 0
	v_mov_b32_dpp v112, v128 row_shr:8 row_mask:0xf bank_mask:0xf
	v_mov_b32_dpp v113, v129 row_shr:8 row_mask:0xf bank_mask:0xf
	v_pk_mul_f32 v[130:131], v[128:129], v[112:113]
	v_add_u32_e32 v113, 0x10c0, v145
	ds_read2_b32 v[132:133], v113 offset1:1
	s_waitcnt lgkmcnt(0)
; __device__ __forceinline__ unsigned pk2(float lo, float hi) { const f32x2_t v = {lo, hi}; const bf16x2_t b = __builtin_convertvector(v, bf16x2_t); return __builtin_bit_cast(unsigned, b); }
; __device__ __forceinline__ float sigmoidf_(float x) { return __builtin_amdgcn_rcpf(1.0f + __expf(-x)); }
; __device__ __forceinline__ float bcast15(float v, int lane) { return bperm_f((lane & 48) | 15, v); }
; __device__ __forceinline__ void w_lru_m1(const Args& a, int l, unsigned char* ws, const bf16_t* proj, bf16_t* y, LAS unsigned char* wl, int b, int ck_, int h, int lane) {
;     ...
;         for (int tb = 0; tb < 4; ++tb) { const int tok = 16 * tb + lo;
;             f32x4 ga = {0.f, 0.f, 0.f, 0.f}, gx = {0.f, 0.f, 0.f, 0.f};
; #pragma unroll
;             for (int kk = 0; kk < 2; ++kk) { ga = __builtin_amdgcn_mfma_f32_16x16x32_bf16(WaF[kk], Xf[tb][kk], ga, 0, 0, 0); gx = __builtin_amdgcn_mfma_f32_16x16x32_bf16(WxF[kk], Xf[tb][kk], gx, 0, 0, 0); }
;             float hv[4], pv[4];
; #pragma unroll
;             for (int r = 0; r < 4; ++r) {
;                 const float rg = sigmoidf_(ga[r] + bav[r]), ig = sigmoidf_(gx[r] + bxv[r]);
;                 const float la = -8.0f * rg * sp[r]; float A = __expf(la);
;                 float U = __builtin_amdgcn_sqrtf(1.0f - A * A) * (ig * xcf[tok * 65 + j0 + r]);
;                 { const float As = dpp_shr1<1>(A), Us = dpp_shr0<1>(U); U = A * Us + U; A = A * As; }
;                 { const float As = dpp_shr1<2>(A), Us = dpp_shr0<2>(U); U = A * Us + U; A = A * As; }
;                 { const float As = dpp_shr1<4>(A), Us = dpp_shr0<4>(U); U = A * Us + U; A = A * As; }
;                 { const float As = dpp_shr1<8>(A), Us = dpp_shr0<8>(U); U = A * Us + U; A = A * As; }
;                 const float hh = U + A * hc[r], PP = A * Pc[r];
;                 hc[r] = bcast15(hh, lane); Pc[r] = bcast15(PP, lane); hv[r] = hh; pv[r] = PP; }
;             *(unsigned long long*)(y + (size_t)(row0 + tok) * DM + 64 * h + j0) = (unsigned long long)pk2(hv[0], hv[1]) | ((unsigned long long)pk2(hv[2], hv[3]) << 32);
;             *(unsigned long long*)((bf16_t*)(ws + WS_P) + (size_t)(row0 + tok) * 512 + 64 * h + j0) = (unsigned long long)pk2(pv[0], pv[1]) | ((unsigned long long)pk2(pv[2], pv[3]) << 32);
;         }
	v_pk_mul_f32 v[88:89], v[130:131], v[88:89]
	ds_bpermute_b32 v112, v1, v88
	ds_bpermute_b32 v113, v1, v89
	v_cvt_pk_bf16_f32 v88, v88, v89
	v_pk_mul_f32 v[94:95], v[132:133], v[94:95]
	s_nop 0
	v_pk_mul_f32 v[94:95], v[94:95], v[118:119]
	s_nop 1
	v_mov_b32_dpp v118, v94 row_shr:1 row_mask:0xf bank_mask:0xf bound_ctrl:1
	v_mov_b32_dpp v119, v95 row_shr:1 row_mask:0xf bank_mask:0xf bound_ctrl:1
	v_pk_fma_f32 v[94:95], v[110:111], v[118:119], v[94:95]
	s_nop 1
	v_mov_b32_dpp v110, v94 row_shr:2 row_mask:0xf bank_mask:0xf bound_ctrl:1
	v_mov_b32_dpp v111, v95 row_shr:2 row_mask:0xf bank_mask:0xf bound_ctrl:1
	v_pk_fma_f32 v[94:95], v[122:123], v[110:111], v[94:95]
	v_mov_b32_e32 v122, 1.0
	v_mov_b32_e32 v123, 1.0
	v_mov_b32_dpp v110, v94 row_shr:4 row_mask:0xf bank_mask:0xf bound_ctrl:1
	v_mov_b32_dpp v111, v95 row_shr:4 row_mask:0xf bank_mask:0xf bound_ctrl:1
	v_pk_fma_f32 v[94:95], v[126:127], v[110:111], v[94:95]
	s_nop 1
	v_mov_b32_dpp v110, v94 row_shr:8 row_mask:0xf bank_mask:0xf bound_ctrl:1
	v_mov_b32_dpp v111, v95 row_shr:8 row_mask:0xf bank_mask:0xf bound_ctrl:1
	v_pk_fma_f32 v[94:95], v[128:129], v[110:111], v[94:95]
	s_nop 0
	v_pk_fma_f32 v[92:93], v[130:131], v[92:93], v[94:95]
	v_add_f32_e32 v94, v50, v124
	v_mul_f32_e32 v94, 0xbfb8aa3b, v94
	v_exp_f32_e32 v94, v94
	ds_bpermute_b32 v110, v1, v92
	ds_bpermute_b32 v111, v1, v93
	v_cvt_pk_bf16_f32 v92, v92, v93
	v_add_f32_e32 v94, 1.0, v94
	v_rcp_f32_e32 v95, v94
	v_add_f32_e32 v94, v46, v120
	v_mul_f32_e32 v94, 0xbfb8aa3b, v94
	v_exp_f32_e32 v94, v94
	v_mul_f32_e32 v95, 0xc1000000, v95
	v_mul_f32_e32 v95, v135, v95
	v_mul_f32_e32 v95, 0x3fb8aa3b, v95
	v_exp_f32_e32 v118, v95
	v_add_f32_e32 v94, 1.0, v94
	v_rcp_f32_e32 v94, v94
	v_fma_f32 v95, -v118, v118, 1.0
	v_sqrt_f32_e32 v120, v95
	v_add_f32_e32 v95, v51, v125
	v_mul_f32_e32 v95, 0xbfb8aa3b, v95
	v_exp_f32_e32 v95, v95
	v_mov_b32_dpp v122, v118 row_shr:1 row_mask:0xf bank_mask:0xf
	v_add_f32_e32 v95, 1.0, v95
	v_rcp_f32_e32 v119, v95
	v_add_f32_e32 v95, v47, v121
	v_mul_f32_e32 v95, 0xbfb8aa3b, v95
	v_exp_f32_e32 v95, v95
	v_mul_f32_e32 v119, 0xc1000000, v119
	v_mul_f32_e32 v119, v136, v119
	v_mul_f32_e32 v119, 0x3fb8aa3b, v119
	v_exp_f32_e32 v119, v119
	v_add_f32_e32 v95, 1.0, v95
	v_rcp_f32_e32 v95, v95
	v_mov_b32_dpp v123, v119 row_shr:1 row_mask:0xf bank_mask:0xf
	v_pk_mul_f32 v[124:125], v[118:119], v[122:123]
	v_mov_b32_e32 v122, 1.0
	v_mov_b32_e32 v123, 1.0
	v_fma_f32 v121, -v119, v119, 1.0
	v_mov_b32_dpp v122, v124 row_shr:2 row_mask:0xf bank_mask:0xf
	v_mov_b32_dpp v123, v125 row_shr:2 row_mask:0xf bank_mask:0xf
	v_pk_mul_f32 v[126:127], v[124:125], v[122:123]
	v_mov_b32_e32 v122, 1.0
	v_mov_b32_e32 v123, 1.0
	v_sqrt_f32_e32 v121, v121
	v_mov_b32_dpp v122, v126 row_shr:4 row_mask:0xf bank_mask:0xf
	v_mov_b32_dpp v123, v127 row_shr:4 row_mask:0xf bank_mask:0xf
	v_pk_mul_f32 v[128:129], v[126:127], v[122:123]
	v_mov_b32_e32 v122, 1.0
	v_mov_b32_e32 v123, 1.0
	s_nop 0
	v_mov_b32_dpp v122, v128 row_shr:8 row_mask:0xf bank_mask:0xf
	v_mov_b32_dpp v123, v129 row_shr:8 row_mask:0xf bank_mask:0xf
	v_pk_mul_f32 v[130:131], v[128:129], v[122:123]
	v_add_u32_e32 v123, 0x10c8, v145
	ds_read2_b32 v[132:133], v123 offset1:1
	v_pk_mul_f32 v[90:91], v[130:131], v[90:91]
	ds_bpermute_b32 v122, v1, v90
	v_cvt_pk_bf16_f32 v89, v90, v91
	ds_bpermute_b32 v123, v1, v91
	s_waitcnt lgkmcnt(0)
	v_pk_mul_f32 v[94:95], v[94:95], v[132:133]
	s_nop 0
	v_pk_mul_f32 v[94:95], v[120:121], v[94:95]
	s_nop 1
	v_mov_b32_dpp v120, v94 row_shr:1 row_mask:0xf bank_mask:0xf bound_ctrl:1
	v_mov_b32_dpp v121, v95 row_shr:1 row_mask:0xf bank_mask:0xf bound_ctrl:1
	v_pk_fma_f32 v[94:95], v[118:119], v[120:121], v[94:95]
	s_nop 1
	v_mov_b32_dpp v118, v94 row_shr:2 row_mask:0xf bank_mask:0xf bound_ctrl:1
	v_mov_b32_dpp v119, v95 row_shr:2 row_mask:0xf bank_mask:0xf bound_ctrl:1
	v_pk_fma_f32 v[94:95], v[124:125], v[118:119], v[94:95]
	s_nop 1
	v_mov_b32_dpp v118, v94 row_shr:4 row_mask:0xf bank_mask:0xf bound_ctrl:1
	v_mov_b32_dpp v119, v95 row_shr:4 row_mask:0xf bank_mask:0xf bound_ctrl:1
	v_pk_fma_f32 v[94:95], v[126:127], v[118:119], v[94:95]
	s_nop 1
	v_mov_b32_dpp v118, v94 row_shr:8 row_mask:0xf bank_mask:0xf bound_ctrl:1
	v_mov_b32_dpp v119, v95 row_shr:8 row_mask:0xf bank_mask:0xf bound_ctrl:1
	v_pk_fma_f32 v[94:95], v[128:129], v[118:119], v[94:95]
	v_mfma_f32_16x16x32_bf16 v[118:121], v[60:63], v[8:11], 0
	v_fma_f32 v94, v130, v108, v94
	v_fma_f32 v95, v131, v109, v95
	ds_bpermute_b32 v108, v1, v94
	v_cvt_pk_bf16_f32 v93, v94, v95
	global_store_dwordx2 v[104:105], v[92:93], off offset:64
	global_store_dwordx2 v[106:107], v[88:89], off offset:64
	v_mfma_f32_16x16x32_bf16 v[88:91], v[64:67], v[8:11], 0
	ds_bpermute_b32 v109, v1, v95
	v_mfma_f32_16x16x32_bf16 v[92:95], v[56:59], v[24:27], v[88:91]
	v_mfma_f32_16x16x32_bf16 v[88:91], v[52:55], v[24:27], v[118:121]
	v_mfma_f32_16x16x32_bf16 v[64:67], v[64:67], v[4:7], 0
	s_nop 5
	v_add_f32_e32 v92, v48, v92
	v_mul_f32_e32 v92, 0xbfb8aa3b, v92
	v_exp_f32_e32 v92, v92
	v_add_f32_e32 v88, v44, v88
	v_mul_f32_e32 v88, 0xbfb8aa3b, v88
	v_exp_f32_e32 v88, v88
	v_add_f32_e32 v92, 1.0, v92
	v_rcp_f32_e32 v92, v92
	v_add_f32_e32 v89, v45, v89
	v_add_f32_e32 v88, 1.0, v88
	v_rcp_f32_e32 v118, v88
	v_mul_f32_e32 v88, 0xc1000000, v92
	v_add_f32_e32 v92, v49, v93
	v_mul_f32_e32 v92, 0xbfb8aa3b, v92
	v_exp_f32_e32 v92, v92
	v_mul_f32_e32 v89, 0xbfb8aa3b, v89
	v_exp_f32_e32 v89, v89
	v_mul_f32_e32 v88, v2, v88
	v_add_f32_e32 v92, 1.0, v92
	v_rcp_f32_e32 v92, v92
	v_add_f32_e32 v89, 1.0, v89
	v_rcp_f32_e32 v119, v89
	v_mul_f32_e32 v88, 0x3fb8aa3b, v88
	v_mul_f32_e32 v89, 0xc1000000, v92
	v_mul_f32_e32 v89, v134, v89
; __device__ __forceinline__ float sigmoidf_(float x) { return __builtin_amdgcn_rcpf(1.0f + __expf(-x)); }
; __device__ __forceinline__ float bcast15(float v, int lane) { return bperm_f((lane & 48) | 15, v); }
; __device__ __forceinline__ void w_lru_m1(const Args& a, int l, unsigned char* ws, const bf16_t* proj, bf16_t* y, LAS unsigned char* wl, int b, int ck_, int h, int lane) {
;     ...
;         for (int tb = 0; tb < 4; ++tb) { const int tok = 16 * tb + lo;
;             f32x4 ga = {0.f, 0.f, 0.f, 0.f}, gx = {0.f, 0.f, 0.f, 0.f};
; #pragma unroll
;             for (int kk = 0; kk < 2; ++kk) { ga = __builtin_amdgcn_mfma_f32_16x16x32_bf16(WaF[kk], Xf[tb][kk], ga, 0, 0, 0); gx = __builtin_amdgcn_mfma_f32_16x16x32_bf16(WxF[kk], Xf[tb][kk], gx, 0, 0, 0); }
;             float hv[4], pv[4];
; #pragma unroll
;             for (int r = 0; r < 4; ++r) {
;                 const float rg = sigmoidf_(ga[r] + bav[r]), ig = sigmoidf_(gx[r] + bxv[r]);
;                 const float la = -8.0f * rg * sp[r]; float A = __expf(la);
;                 float U = __builtin_amdgcn_sqrtf(1.0f - A * A) * (ig * xcf[tok * 65 + j0 + r]);
;                 { const float As = dpp_shr1<1>(A), Us = dpp_shr0<1>(U); U = A * Us + U; A = A * As; }
;                 { const float As = dpp_shr1<2>(A), Us = dpp_shr0<2>(U); U = A * Us + U; A = A * As; }
;                 { const float As = dpp_shr1<4>(A), Us = dpp_shr0<4>(U); U = A * Us + U; A = A * As; }
;                 { const float As = dpp_shr1<8>(A), Us = dpp_shr0<8>(U); U = A * Us + U; A = A * As; }
;                 const float hh = U + A * hc[r], PP = A * Pc[r];
;                 hc[r] = bcast15(hh, lane); Pc[r] = bcast15(PP, lane); hv[r] = hh; pv[r] = PP; }
	v_mul_f32_e32 v89, 0x3fb8aa3b, v89
	v_exp_f32_e32 v120, v88
	v_exp_f32_e32 v121, v89
	v_mfma_f32_16x16x32_bf16 v[60:63], v[60:63], v[4:7], 0
	v_add_f32_e32 v94, v50, v94
	v_fma_f32 v88, -v120, v120, 1.0
	v_fma_f32 v89, -v121, v121, 1.0
	v_sqrt_f32_e32 v124, v88
	v_mov_b32_e32 v88, 1.0
	v_sqrt_f32_e32 v125, v89
	v_mov_b32_e32 v89, 1.0
	v_mov_b32_dpp v88, v120 row_shr:1 row_mask:0xf bank_mask:0xf
	v_mfma_f32_16x16x32_bf16 v[56:59], v[56:59], v[20:23], v[64:67]
	v_mov_b32_dpp v89, v121 row_shr:1 row_mask:0xf bank_mask:0xf
	v_pk_mul_f32 v[126:127], v[120:121], v[88:89]
	v_mov_b32_e32 v88, 1.0
	v_mov_b32_e32 v89, 1.0
	v_add_f32_e32 v95, v51, v95
	v_mov_b32_dpp v88, v126 row_shr:2 row_mask:0xf bank_mask:0xf
	v_mov_b32_dpp v89, v127 row_shr:2 row_mask:0xf bank_mask:0xf
	v_pk_mul_f32 v[128:129], v[126:127], v[88:89]
	v_mov_b32_e32 v88, 1.0
	v_mov_b32_e32 v89, 1.0
	v_mul_f32_e32 v94, 0xbfb8aa3b, v94
	v_mov_b32_dpp v88, v128 row_shr:4 row_mask:0xf bank_mask:0xf
	v_mov_b32_dpp v89, v129 row_shr:4 row_mask:0xf bank_mask:0xf
	v_pk_mul_f32 v[130:131], v[128:129], v[88:89]
	v_mov_b32_e32 v88, 1.0
	v_mov_b32_e32 v89, 1.0
	v_mul_f32_e32 v95, 0xbfb8aa3b, v95
	v_mov_b32_dpp v88, v130 row_shr:8 row_mask:0xf bank_mask:0xf
	v_mov_b32_dpp v89, v131 row_shr:8 row_mask:0xf bank_mask:0xf
	v_pk_mul_f32 v[132:133], v[130:131], v[88:89]
	v_add_u32_e32 v89, 0x2100, v145
	v_pk_mul_f32 v[92:93], v[132:133], v[112:113]
	ds_read2_b32 v[112:113], v89 offset1:1
	v_mfma_f32_16x16x32_bf16 v[60:63], v[52:55], v[20:23], v[60:63]
	v_add_f32_e32 v48, v48, v56
	v_exp_f32_e32 v94, v94
	v_exp_f32_e32 v95, v95
	s_waitcnt lgkmcnt(0)
	v_pk_mul_f32 v[112:113], v[112:113], v[118:119]
	v_mul_f32_e32 v48, 0xbfb8aa3b, v48
	v_pk_mul_f32 v[112:113], v[112:113], v[124:125]
	v_exp_f32_e32 v48, v48
	v_add_f32_e32 v90, v46, v90
	v_mov_b32_dpp v118, v112 row_shr:1 row_mask:0xf bank_mask:0xf bound_ctrl:1
	v_mov_b32_dpp v119, v113 row_shr:1 row_mask:0xf bank_mask:0xf bound_ctrl:1
	v_add_f32_e32 v91, v47, v91
	v_pk_fma_f32 v[112:113], v[120:121], v[118:119], v[112:113]
	v_mul_f32_e32 v90, 0xbfb8aa3b, v90
	v_mul_f32_e32 v91, 0xbfb8aa3b, v91
	v_add_f32_e32 v44, v44, v60
	v_mov_b32_dpp v118, v112 row_shr:2 row_mask:0xf bank_mask:0xf bound_ctrl:1
	v_mov_b32_dpp v119, v113 row_shr:2 row_mask:0xf bank_mask:0xf bound_ctrl:1
	v_add_f32_e32 v94, 1.0, v94
	v_exp_f32_e32 v90, v90
	v_add_f32_e32 v95, 1.0, v95
	v_exp_f32_e32 v91, v91
	v_mul_f32_e32 v44, 0xbfb8aa3b, v44
	v_pk_fma_f32 v[112:113], v[126:127], v[118:119], v[112:113]
	v_rcp_f32_e32 v94, v94
	v_rcp_f32_e32 v95, v95
	v_add_f32_e32 v48, 1.0, v48
	v_exp_f32_e32 v44, v44
	v_mov_b32_dpp v118, v112 row_shr:4 row_mask:0xf bank_mask:0xf bound_ctrl:1
	v_mov_b32_dpp v119, v113 row_shr:4 row_mask:0xf bank_mask:0xf bound_ctrl:1
	v_rcp_f32_e32 v52, v48
	v_pk_fma_f32 v[112:113], v[128:129], v[118:119], v[112:113]
	v_add_f32_e32 v90, 1.0, v90
	v_add_f32_e32 v91, 1.0, v91
	v_mov_b32_dpp v118, v112 row_shr:8 row_mask:0xf bank_mask:0xf bound_ctrl:1
	v_mov_b32_dpp v119, v113 row_shr:8 row_mask:0xf bank_mask:0xf bound_ctrl:1
	v_pk_fma_f32 v[112:113], v[130:131], v[118:119], v[112:113]
	v_rcp_f32_e32 v118, v90
	v_mul_f32_e32 v90, 0xc1000000, v94
	v_rcp_f32_e32 v119, v91
	v_mul_f32_e32 v91, 0xc1000000, v95
	v_add_f32_e32 v44, 1.0, v44
	v_mul_f32_e32 v90, v135, v90
	v_mul_f32_e32 v91, v136, v91
	v_rcp_f32_e32 v48, v44
	v_mul_f32_e32 v44, 0xc1000000, v52
	v_mul_f32_e32 v90, 0x3fb8aa3b, v90
	v_mul_f32_e32 v91, 0x3fb8aa3b, v91
	v_mul_f32_e32 v2, v2, v44
	v_exp_f32_e32 v94, v90
	v_exp_f32_e32 v95, v91
	v_mul_f32_e32 v2, 0x3fb8aa3b, v2
	v_exp_f32_e32 v54, v2
	v_fma_f32 v90, -v94, v94, 1.0
	v_fma_f32 v91, -v95, v95, 1.0
	v_sqrt_f32_e32 v120, v90
	v_mov_b32_e32 v90, 1.0
	v_sqrt_f32_e32 v121, v91
	v_mov_b32_e32 v91, 1.0
	v_fma_f32 v2, -v54, v54, 1.0
	v_mov_b32_dpp v90, v94 row_shr:1 row_mask:0xf bank_mask:0xf
	v_mov_b32_dpp v91, v95 row_shr:1 row_mask:0xf bank_mask:0xf
	v_sqrt_f32_e32 v56, v2
	v_add_f32_e32 v2, v49, v57
	v_pk_mul_f32 v[124:125], v[94:95], v[90:91]
	v_mov_b32_e32 v90, 1.0
	v_mov_b32_e32 v91, 1.0
	v_mul_f32_e32 v2, 0xbfb8aa3b, v2
	v_mov_b32_dpp v90, v124 row_shr:2 row_mask:0xf bank_mask:0xf
	v_mov_b32_dpp v91, v125 row_shr:2 row_mask:0xf bank_mask:0xf
	v_exp_f32_e32 v2, v2
	v_pk_mul_f32 v[126:127], v[124:125], v[90:91]
	v_mov_b32_e32 v90, 1.0
	v_mov_b32_e32 v91, 1.0
	v_add_f32_e32 v2, 1.0, v2
	v_mov_b32_dpp v90, v126 row_shr:4 row_mask:0xf bank_mask:0xf
	v_mov_b32_dpp v91, v127 row_shr:4 row_mask:0xf bank_mask:0xf
	v_pk_mul_f32 v[128:129], v[126:127], v[90:91]
	v_mov_b32_e32 v90, 1.0
	v_mov_b32_e32 v91, 1.0
	v_rcp_f32_e32 v2, v2
	v_mov_b32_dpp v90, v128 row_shr:8 row_mask:0xf bank_mask:0xf
	v_mov_b32_dpp v91, v129 row_shr:8 row_mask:0xf bank_mask:0xf
	v_pk_mul_f32 v[130:131], v[128:129], v[90:91]
	v_add_u32_e32 v91, 0x2108, v145
	v_pk_fma_f32 v[112:113], v[132:133], v[110:111], v[112:113]
	ds_read2_b32 v[132:133], v91 offset1:1
	v_add_f32_e32 v45, v45, v61
	v_mul_f32_e32 v45, 0xbfb8aa3b, v45
	v_mul_f32_e32 v2, 0xc1000000, v2
	v_exp_f32_e32 v45, v45
	v_mul_f32_e32 v2, v134, v2
	s_waitcnt lgkmcnt(0)
; __device__ __forceinline__ unsigned pk2(float lo, float hi) { const f32x2_t v = {lo, hi}; const bf16x2_t b = __builtin_convertvector(v, bf16x2_t); return __builtin_bit_cast(unsigned, b); }
; __device__ __forceinline__ float sigmoidf_(float x) { return __builtin_amdgcn_rcpf(1.0f + __expf(-x)); }
; __device__ __forceinline__ float bcast15(float v, int lane) { return bperm_f((lane & 48) | 15, v); }
; __device__ __forceinline__ void w_lru_m1(const Args& a, int l, unsigned char* ws, const bf16_t* proj, bf16_t* y, LAS unsigned char* wl, int b, int ck_, int h, int lane) {
;     ...
;         for (int tb = 0; tb < 4; ++tb) { const int tok = 16 * tb + lo;
;             f32x4 ga = {0.f, 0.f, 0.f, 0.f}, gx = {0.f, 0.f, 0.f, 0.f};
; #pragma unroll
;             for (int kk = 0; kk < 2; ++kk) { ga = __builtin_amdgcn_mfma_f32_16x16x32_bf16(WaF[kk], Xf[tb][kk], ga, 0, 0, 0); gx = __builtin_amdgcn_mfma_f32_16x16x32_bf16(WxF[kk], Xf[tb][kk], gx, 0, 0, 0); }
;             float hv[4], pv[4];
; #pragma unroll
;             for (int r = 0; r < 4; ++r) {
;                 const float rg = sigmoidf_(ga[r] + bav[r]), ig = sigmoidf_(gx[r] + bxv[r]);
;                 const float la = -8.0f * rg * sp[r]; float A = __expf(la);
;                 float U = __builtin_amdgcn_sqrtf(1.0f - A * A) * (ig * xcf[tok * 65 + j0 + r]);
;                 { const float As = dpp_shr1<1>(A), Us = dpp_shr0<1>(U); U = A * Us + U; A = A * As; }
;                 { const float As = dpp_shr1<2>(A), Us = dpp_shr0<2>(U); U = A * Us + U; A = A * As; }
;                 { const float As = dpp_shr1<4>(A), Us = dpp_shr0<4>(U); U = A * Us + U; A = A * As; }
;                 { const float As = dpp_shr1<8>(A), Us = dpp_shr0<8>(U); U = A * Us + U; A = A * As; }
;                 const float hh = U + A * hc[r], PP = A * Pc[r];
;                 hc[r] = bcast15(hh, lane); Pc[r] = bcast15(PP, lane); hv[r] = hh; pv[r] = PP; }
;             *(unsigned long long*)(y + (size_t)(row0 + tok) * DM + 64 * h + j0) = (unsigned long long)pk2(hv[0], hv[1]) | ((unsigned long long)pk2(hv[2], hv[3]) << 32);
;             *(unsigned long long*)((bf16_t*)(ws + WS_P) + (size_t)(row0 + tok) * 512 + 64 * h + j0) = (unsigned long long)pk2(pv[0], pv[1]) | ((unsigned long long)pk2(pv[2], pv[3]) << 32);
;         }
	v_pk_mul_f32 v[118:119], v[118:119], v[132:133]
	v_mul_f32_e32 v2, 0x3fb8aa3b, v2
	v_pk_mul_f32 v[118:119], v[120:121], v[118:119]
	v_exp_f32_e32 v55, v2
	v_add_f32_e32 v45, 1.0, v45
	v_mov_b32_dpp v120, v118 row_shr:1 row_mask:0xf bank_mask:0xf bound_ctrl:1
	v_mov_b32_dpp v121, v119 row_shr:1 row_mask:0xf bank_mask:0xf bound_ctrl:1
	v_pk_fma_f32 v[94:95], v[94:95], v[120:121], v[118:119]
	v_mov_b32_e32 v44, 1.0
	v_rcp_f32_e32 v49, v45
	v_mov_b32_dpp v118, v94 row_shr:2 row_mask:0xf bank_mask:0xf bound_ctrl:1
	v_mov_b32_dpp v119, v95 row_shr:2 row_mask:0xf bank_mask:0xf bound_ctrl:1
	v_mov_b32_e32 v45, 1.0
	v_pk_fma_f32 v[94:95], v[124:125], v[118:119], v[94:95]
	v_mov_b32_dpp v44, v54 row_shr:1 row_mask:0xf bank_mask:0xf
	v_mov_b32_dpp v45, v55 row_shr:1 row_mask:0xf bank_mask:0xf
	v_mov_b32_dpp v118, v94 row_shr:4 row_mask:0xf bank_mask:0xf bound_ctrl:1
	v_mov_b32_dpp v119, v95 row_shr:4 row_mask:0xf bank_mask:0xf bound_ctrl:1
	v_pk_mul_f32 v[60:61], v[54:55], v[44:45]
	v_mov_b32_e32 v44, 1.0
	v_mov_b32_e32 v45, 1.0
	v_pk_fma_f32 v[94:95], v[126:127], v[118:119], v[94:95]
	v_mov_b32_dpp v44, v60 row_shr:2 row_mask:0xf bank_mask:0xf
	v_mov_b32_dpp v45, v61 row_shr:2 row_mask:0xf bank_mask:0xf
	ds_bpermute_b32 v88, v1, v92
	ds_bpermute_b32 v89, v1, v93
	v_mov_b32_dpp v118, v94 row_shr:8 row_mask:0xf bank_mask:0xf bound_ctrl:1
	v_mov_b32_dpp v119, v95 row_shr:8 row_mask:0xf bank_mask:0xf bound_ctrl:1
	v_pk_mul_f32 v[64:65], v[60:61], v[44:45]
	v_mov_b32_e32 v44, 1.0
	v_mov_b32_e32 v45, 1.0
	v_pk_fma_f32 v[94:95], v[128:129], v[118:119], v[94:95]
	v_mov_b32_dpp v44, v64 row_shr:4 row_mask:0xf bank_mask:0xf
	v_mov_b32_dpp v45, v65 row_shr:4 row_mask:0xf bank_mask:0xf
	v_pk_mul_f32 v[122:123], v[130:131], v[122:123]
	v_pk_fma_f32 v[108:109], v[130:131], v[108:109], v[94:95]
	v_pk_mul_f32 v[66:67], v[64:65], v[44:45]
	v_mov_b32_e32 v44, 1.0
	v_mov_b32_e32 v45, 1.0
	ds_bpermute_b32 v110, v1, v112
	ds_bpermute_b32 v111, v1, v113
	v_cvt_pk_bf16_f32 v112, v112, v113
	v_cvt_pk_bf16_f32 v113, v108, v109
	v_cvt_pk_bf16_f32 v92, v92, v93
	v_cvt_pk_bf16_f32 v93, v122, v123
	v_fma_f32 v2, -v55, v55, 1.0
	v_mov_b32_dpp v44, v66 row_shr:8 row_mask:0xf bank_mask:0xf
	v_mov_b32_dpp v45, v67 row_shr:8 row_mask:0xf bank_mask:0xf
	global_store_dwordx2 v[96:97], v[112:113], off offset:64
	global_store_dwordx2 v[98:99], v[92:93], off offset:64
	v_sqrt_f32_e32 v57, v2
	v_pk_mul_f32 v[92:93], v[66:67], v[44:45]
	v_add_u32_e32 v2, 0x3140, v145
	s_waitcnt lgkmcnt(0)
	v_pk_mul_f32 v[52:53], v[92:93], v[88:89]
	ds_read2_b32 v[88:89], v2 offset1:1
	v_add_f32_e32 v2, v50, v58
	v_mul_f32_e32 v2, 0xbfb8aa3b, v2
	v_exp_f32_e32 v2, v2
	v_add_f32_e32 v46, v46, v62
	v_add_f32_e32 v47, v47, v63
	v_mul_f32_e32 v46, 0xbfb8aa3b, v46
	v_add_f32_e32 v2, 1.0, v2
	v_rcp_f32_e32 v2, v2
	v_mul_f32_e32 v47, 0xbfb8aa3b, v47
	v_exp_f32_e32 v46, v46
	v_exp_f32_e32 v47, v47
	v_mul_f32_e32 v2, 0xc1000000, v2
	v_mul_f32_e32 v2, v135, v2
	v_mul_f32_e32 v2, 0x3fb8aa3b, v2
	v_exp_f32_e32 v50, v2
	s_waitcnt lgkmcnt(0)
	v_pk_mul_f32 v[48:49], v[88:89], v[48:49]
	v_add_f32_e32 v46, 1.0, v46
	v_pk_mul_f32 v[48:49], v[48:49], v[56:57]
	v_fma_f32 v2, -v50, v50, 1.0
	v_sqrt_f32_e32 v58, v2
	v_add_f32_e32 v2, v51, v59
	v_mul_f32_e32 v2, 0xbfb8aa3b, v2
	v_exp_f32_e32 v2, v2
	v_mov_b32_dpp v56, v48 row_shr:1 row_mask:0xf bank_mask:0xf bound_ctrl:1
	v_mov_b32_dpp v57, v49 row_shr:1 row_mask:0xf bank_mask:0xf bound_ctrl:1
	v_add_f32_e32 v47, 1.0, v47
	v_add_f32_e32 v2, 1.0, v2
	v_rcp_f32_e32 v2, v2
	v_pk_fma_f32 v[48:49], v[54:55], v[56:57], v[48:49]
	v_rcp_f32_e32 v56, v46
	v_mov_b32_e32 v46, 1.0
	v_mul_f32_e32 v2, 0xc1000000, v2
	v_mul_f32_e32 v2, v136, v2
	v_mul_f32_e32 v2, 0x3fb8aa3b, v2
	v_exp_f32_e32 v51, v2
	v_rcp_f32_e32 v57, v47
	v_mov_b32_e32 v47, 1.0
	v_mov_b32_dpp v54, v48 row_shr:2 row_mask:0xf bank_mask:0xf bound_ctrl:1
	v_mov_b32_dpp v55, v49 row_shr:2 row_mask:0xf bank_mask:0xf bound_ctrl:1
	v_mov_b32_dpp v46, v50 row_shr:1 row_mask:0xf bank_mask:0xf
	v_mov_b32_dpp v47, v51 row_shr:1 row_mask:0xf bank_mask:0xf
	v_pk_fma_f32 v[48:49], v[60:61], v[54:55], v[48:49]
	v_pk_mul_f32 v[62:63], v[50:51], v[46:47]
	v_mov_b32_e32 v46, 1.0
	v_mov_b32_e32 v47, 1.0
	v_mov_b32_dpp v54, v48 row_shr:4 row_mask:0xf bank_mask:0xf bound_ctrl:1
	v_mov_b32_dpp v55, v49 row_shr:4 row_mask:0xf bank_mask:0xf bound_ctrl:1
	v_mov_b32_dpp v46, v62 row_shr:2 row_mask:0xf bank_mask:0xf
	v_mov_b32_dpp v47, v63 row_shr:2 row_mask:0xf bank_mask:0xf
	ds_bpermute_b32 v90, v1, v122
	ds_bpermute_b32 v91, v1, v123
	v_pk_fma_f32 v[48:49], v[64:65], v[54:55], v[48:49]
	v_pk_mul_f32 v[64:65], v[62:63], v[46:47]
	v_mov_b32_e32 v46, 1.0
	v_mov_b32_e32 v47, 1.0
	v_mov_b32_dpp v54, v48 row_shr:8 row_mask:0xf bank_mask:0xf bound_ctrl:1
	v_mov_b32_dpp v55, v49 row_shr:8 row_mask:0xf bank_mask:0xf bound_ctrl:1
	v_mov_b32_dpp v46, v64 row_shr:4 row_mask:0xf bank_mask:0xf
	v_mov_b32_dpp v47, v65 row_shr:4 row_mask:0xf bank_mask:0xf
	v_pk_fma_f32 v[48:49], v[66:67], v[54:55], v[48:49]
	v_pk_mul_f32 v[66:67], v[64:65], v[46:47]
	v_mov_b32_e32 v46, 1.0
	v_mov_b32_e32 v47, 1.0
	v_fma_f32 v2, -v51, v51, 1.0
	v_mov_b32_dpp v46, v66 row_shr:8 row_mask:0xf bank_mask:0xf
	v_mov_b32_dpp v47, v67 row_shr:8 row_mask:0xf bank_mask:0xf
	v_sqrt_f32_e32 v59, v2
	v_pk_mul_f32 v[88:89], v[66:67], v[46:47]
	v_add_u32_e32 v2, 0x3148, v145
	s_waitcnt lgkmcnt(0)
	v_pk_mul_f32 v[60:61], v[88:89], v[90:91]
	ds_read2_b32 v[90:91], v2 offset1:1
	ds_bpermute_b32 v94, v1, v108
	ds_bpermute_b32 v95, v1, v109
	v_pk_fma_f32 v[54:55], v[92:93], v[110:111], v[48:49]
	ds_bpermute_b32 v44, v1, v52
	s_waitcnt lgkmcnt(0)
; __device__ __forceinline__ void w_lru_m1(const Args& a, int l, unsigned char* ws, const bf16_t* proj, bf16_t* y, LAS unsigned char* wl, int b, int ck_, int h, int lane) {
;     ...
;     for (int jb = 0; jb < 4; ++jb) {
;         bf16x8 WaF[2], WxF[2]; f32x4 pba, pbx, plam;
; #pragma unroll
;         for (int kk = 0; kk < 2; ++kk) { WaF[kk] = nWa[kk]; WxF[kk] = nWx[kk]; }
;         pba = nba; pbx = nbx; plam = nlam;
;         if (jb < 3) {
; #pragma unroll
;             for (int kk = 0; kk < 2; ++kk) { nWa[kk] = *(const bf16x8*)(waT + (16 * (jb + 1) + lo) * 64 + 32 * kk + 8 * fq); nWx[kk] = *(const bf16x8*)(wxT + (16 * (jb + 1) + lo) * 64 + 32 * kk + 8 * fq); }
;             nba = *(const f32x4*)(ba + 16 * (jb + 1) + 4 * fq); nbx = *(const f32x4*)(bx + 16 * (jb + 1) + 4 * fq); nlam = *(const f32x4*)(lam + 16 * (jb + 1) + 4 * fq);
;         }
;         const int j0 = 16 * jb + 4 * fq;
;         float bav[4], bxv[4], sp[4], hc[4], Pc[4];
; #pragma unroll
;         for (int r = 0; r < 4; ++r) { bav[r] = pba[r]; bxv[r] = pbx[r]; sp[r] = log1pf(__expf(-plam[r])); hc[r] = 0.f; Pc[r] = 1.f; }
; #pragma unroll
;         for (int tb = 0; tb < 4; ++tb) { const int tok = 16 * tb + lo;
;             f32x4 ga = {0.f, 0.f, 0.f, 0.f}, gx = {0.f, 0.f, 0.f, 0.f};
; #pragma unroll
;             for (int kk = 0; kk < 2; ++kk) { ga = __builtin_amdgcn_mfma_f32_16x16x32_bf16(WaF[kk], Xf[tb][kk], ga, 0, 0, 0); gx = __builtin_amdgcn_mfma_f32_16x16x32_bf16(WxF[kk], Xf[tb][kk], gx, 0, 0, 0); }
;             float hv[4], pv[4];
; #pragma unroll
;             for (int r = 0; r < 4; ++r) {
;                 const float rg = sigmoidf_(ga[r] + bav[r]), ig = sigmoidf_(gx[r] + bxv[r]);
;                 const float la = -8.0f * rg * sp[r]; float A = __expf(la);
;                 float U = __builtin_amdgcn_sqrtf(1.0f - A * A) * (ig * xcf[tok * 65 + j0 + r]);
;                 { const float As = dpp_shr1<1>(A), Us = dpp_shr0<1>(U); U = A * Us + U; A = A * As; }
;                 { const float As = dpp_shr1<2>(A), Us = dpp_shr0<2>(U); U = A * Us + U; A = A * As; }
;                 { const float As = dpp_shr1<4>(A), Us = dpp_shr0<4>(U); U = A * Us + U; A = A * As; }
;                 { const float As = dpp_shr1<8>(A), Us = dpp_shr0<8>(U); U = A * Us + U; A = A * As; }
;                 const float hh = U + A * hc[r], PP = A * Pc[r];
	v_pk_mul_f32 v[56:57], v[56:57], v[90:91]
	ds_bpermute_b32 v48, v1, v54
	v_pk_mul_f32 v[56:57], v[58:59], v[56:57]
	ds_bpermute_b32 v49, v1, v55
	ds_bpermute_b32 v45, v1, v53
	v_mov_b32_dpp v58, v56 row_shr:1 row_mask:0xf bank_mask:0xf bound_ctrl:1
	v_mov_b32_dpp v59, v57 row_shr:1 row_mask:0xf bank_mask:0xf bound_ctrl:1
	v_pk_fma_f32 v[50:51], v[50:51], v[58:59], v[56:57]
	ds_bpermute_b32 v46, v1, v60
	ds_bpermute_b32 v47, v1, v61
	v_mov_b32_dpp v56, v50 row_shr:2 row_mask:0xf bank_mask:0xf bound_ctrl:1
	v_mov_b32_dpp v57, v51 row_shr:2 row_mask:0xf bank_mask:0xf bound_ctrl:1
	v_pk_fma_f32 v[50:51], v[62:63], v[56:57], v[50:51]
	v_cvt_pk_bf16_f32 v54, v54, v55
	v_cvt_pk_bf16_f32 v52, v52, v53
	v_mov_b32_dpp v56, v50 row_shr:4 row_mask:0xf bank_mask:0xf bound_ctrl:1
	v_mov_b32_dpp v57, v51 row_shr:4 row_mask:0xf bank_mask:0xf bound_ctrl:1
	v_pk_fma_f32 v[50:51], v[64:65], v[56:57], v[50:51]
	v_cvt_pk_bf16_f32 v53, v60, v61
	s_nop 0
	v_mov_b32_dpp v56, v50 row_shr:8 row_mask:0xf bank_mask:0xf bound_ctrl:1
	v_mov_b32_dpp v57, v51 row_shr:8 row_mask:0xf bank_mask:0xf bound_ctrl:1
	v_pk_fma_f32 v[50:51], v[66:67], v[56:57], v[50:51]
	s_nop 0
	v_pk_fma_f32 v[56:57], v[88:89], v[94:95], v[50:51]
	ds_bpermute_b32 v50, v1, v56
	ds_bpermute_b32 v51, v1, v57
	v_cvt_pk_bf16_f32 v55, v56, v57
	global_store_dwordx2 v[114:115], v[54:55], off offset:64
	global_store_dwordx2 v[116:117], v[52:53], off offset:64
	s_and_saveexec_b64 s[34:35], vcc
	s_cbranch_execz .LBB0_527
	v_add_u32_e32 v52, 32, v0
	v_ashrrev_i32_e32 v53, 31, v52
	v_lshl_add_u64 v[52:53], s[42:43], 0, v[52:53]
	v_lshlrev_b64 v[52:53], 2, v[52:53]
	v_lshl_add_u64 v[54:55], s[84:85], 0, v[52:53]
	v_lshl_add_u64 v[52:53], s[86:87], 0, v[52:53]
	s_waitcnt lgkmcnt(0)
	global_store_dwordx4 v[54:55], v[44:47], off
	global_store_dwordx4 v[52:53], v[48:51], off
.LBB0_527:
	s_or_b64 exec, exec, s[34:35]
	s_waitcnt vmcnt(8)
	s_nop 7
	ds_read2_b32 v[64:65], v145 offset0:50 offset1:51
	s_waitcnt lgkmcnt(0)
	s_nop 7
	s_nop 0
	s_nop 7
	s_nop 0
	s_nop 7
	s_nop 0
	s_nop 7
	s_nop 0
	s_nop 7
	s_nop 0
	s_nop 7
	s_nop 1
	s_nop 7
	s_nop 1
	s_nop 7
	s_nop 1
	s_nop 7
	v_mov_b32_e32 v58, v84
	s_nop 7
	s_nop 0
	s_nop 7
	s_nop 0
	s_nop 7
	s_nop 0
	s_nop 7
	s_nop 0
	s_nop 7
	s_nop 0
	s_nop 7
	s_nop 0
	s_nop 7
	s_nop 1
	s_nop 7
	s_nop 1
	s_nop 7
	s_nop 1
	s_nop 7
	v_mov_b32_e32 v60, v85
	s_nop 7
	s_nop 0
	s_nop 7
	s_nop 0
	s_nop 7
	s_nop 0
	s_nop 7
	s_nop 0
	s_nop 7
	s_nop 0
	s_nop 7
	s_nop 0
	s_nop 7
	s_nop 1
	s_nop 7
	s_nop 1
	s_nop 7
	s_nop 1
	s_nop 7
	v_mov_b32_e32 v2, v86
	s_nop 7
	s_nop 0
	s_nop 7
	s_nop 0
	s_nop 7
	s_nop 0
	s_nop 7
	s_nop 0
	s_nop 7
	s_nop 0
	s_nop 7
	s_nop 0
	s_nop 7
	ds_read2_b32 v[54:55], v145 offset0:48 offset1:49
	v_mov_b32_e32 v48, 1.0
	s_nop 7
	v_mov_b32_e32 v49, 1.0
	v_mov_b32_e32 v50, 1.0
	s_nop 7
	v_mov_b32_e32 v51, 1.0
	v_mov_b32_e32 v52, 1.0
	s_nop 7
	v_mov_b32_e32 v59, v87
	v_mfma_f32_16x16x32_bf16 v[44:47], v[68:71], v[16:19], 0
	v_mov_b32_e32 v53, 1.0
	v_mfma_f32_16x16x32_bf16 v[16:19], v[72:75], v[16:19], 0
	v_mfma_f32_16x16x32_bf16 v[44:47], v[76:79], v[32:35], v[44:47]
	v_mfma_f32_16x16x32_bf16 v[16:19], v[80:83], v[32:35], v[16:19]
	s_nop 6
	v_add_f32_e32 v32, v40, v44
	v_mul_f32_e32 v32, 0xbfb8aa3b, v32
	v_exp_f32_e32 v32, v32
	v_add_f32_e32 v16, v36, v16
	v_add_f32_e32 v17, v37, v17
	v_mul_f32_e32 v16, 0xbfb8aa3b, v16
	v_add_f32_e32 v32, 1.0, v32
	v_rcp_f32_e32 v32, v32
	v_mul_f32_e32 v17, 0xbfb8aa3b, v17
	v_exp_f32_e32 v16, v16
	v_exp_f32_e32 v17, v17
	v_mul_f32_e32 v32, 0xc1000000, v32
	v_mul_f32_e32 v32, v58, v32
	v_mul_f32_e32 v32, 0x3fb8aa3b, v32
	v_exp_f32_e32 v32, v32
	v_add_f32_e32 v16, 1.0, v16
	v_add_f32_e32 v17, 1.0, v17
	v_rcp_f32_e32 v16, v16
	v_fma_f32 v33, -v32, v32, 1.0
	v_sqrt_f32_e32 v34, v33
	v_add_f32_e32 v33, v41, v45
	v_mul_f32_e32 v33, 0xbfb8aa3b, v33
	v_exp_f32_e32 v33, v33
	v_rcp_f32_e32 v17, v17
	v_mov_b32_e32 v44, 1.0
	v_mov_b32_e32 v45, 1.0
	v_add_f32_e32 v33, 1.0, v33
	v_rcp_f32_e32 v33, v33
	s_waitcnt lgkmcnt(0)
	v_pk_mul_f32 v[16:17], v[54:55], v[16:17]
	v_mov_b32_dpp v44, v32 row_shr:1 row_mask:0xf bank_mask:0xf
	v_add_f32_e32 v18, v38, v18
	v_mul_f32_e32 v33, 0xc1000000, v33
	v_mul_f32_e32 v33, v60, v33
	v_mul_f32_e32 v33, 0x3fb8aa3b, v33
	v_exp_f32_e32 v33, v33
	v_add_f32_e32 v19, v39, v19
	v_mul_f32_e32 v18, 0xbfb8aa3b, v18
	v_mul_f32_e32 v19, 0xbfb8aa3b, v19
	v_fma_f32 v35, -v33, v33, 1.0
	v_sqrt_f32_e32 v35, v35
	v_mov_b32_dpp v45, v33 row_shr:1 row_mask:0xf bank_mask:0xf
	v_pk_mul_f32 v[44:45], v[32:33], v[44:45]
	v_exp_f32_e32 v18, v18
	v_pk_mul_f32 v[16:17], v[16:17], v[34:35]
	v_mov_b32_dpp v48, v44 row_shr:2 row_mask:0xf bank_mask:0xf
	v_mov_b32_dpp v49, v45 row_shr:2 row_mask:0xf bank_mask:0xf
	v_mov_b32_dpp v34, v16 row_shr:1 row_mask:0xf bank_mask:0xf bound_ctrl:1
	v_mov_b32_dpp v35, v17 row_shr:1 row_mask:0xf bank_mask:0xf bound_ctrl:1
	v_pk_fma_f32 v[16:17], v[32:33], v[34:35], v[16:17]
	v_pk_mul_f32 v[48:49], v[44:45], v[48:49]
	v_exp_f32_e32 v19, v19
	v_mov_b32_dpp v32, v16 row_shr:2 row_mask:0xf bank_mask:0xf bound_ctrl:1
	v_mov_b32_dpp v33, v17 row_shr:2 row_mask:0xf bank_mask:0xf bound_ctrl:1
	v_pk_fma_f32 v[16:17], v[44:45], v[32:33], v[16:17]
	v_mov_b32_dpp v50, v48 row_shr:4 row_mask:0xf bank_mask:0xf
	v_mov_b32_dpp v51, v49 row_shr:4 row_mask:0xf bank_mask:0xf
	v_mov_b32_dpp v32, v16 row_shr:4 row_mask:0xf bank_mask:0xf bound_ctrl:1
	v_mov_b32_dpp v33, v17 row_shr:4 row_mask:0xf bank_mask:0xf bound_ctrl:1
	v_pk_fma_f32 v[16:17], v[48:49], v[32:33], v[16:17]
	v_pk_mul_f32 v[50:51], v[48:49], v[50:51]
	v_add_f32_e32 v18, 1.0, v18
	v_mov_b32_dpp v32, v16 row_shr:8 row_mask:0xf bank_mask:0xf bound_ctrl:1
; __device__ __forceinline__ unsigned pk2(float lo, float hi) { const f32x2_t v = {lo, hi}; const bf16x2_t b = __builtin_convertvector(v, bf16x2_t); return __builtin_bit_cast(unsigned, b); }
; __device__ __forceinline__ float sigmoidf_(float x) { return __builtin_amdgcn_rcpf(1.0f + __expf(-x)); }
; __device__ __forceinline__ float bcast15(float v, int lane) { return bperm_f((lane & 48) | 15, v); }
; __device__ __forceinline__ void w_lru_m1(const Args& a, int l, unsigned char* ws, const bf16_t* proj, bf16_t* y, LAS unsigned char* wl, int b, int ck_, int h, int lane) {
;     ...
;         for (int tb = 0; tb < 4; ++tb) { const int tok = 16 * tb + lo;
;             f32x4 ga = {0.f, 0.f, 0.f, 0.f}, gx = {0.f, 0.f, 0.f, 0.f};
; #pragma unroll
;             for (int kk = 0; kk < 2; ++kk) { ga = __builtin_amdgcn_mfma_f32_16x16x32_bf16(WaF[kk], Xf[tb][kk], ga, 0, 0, 0); gx = __builtin_amdgcn_mfma_f32_16x16x32_bf16(WxF[kk], Xf[tb][kk], gx, 0, 0, 0); }
;             float hv[4], pv[4];
; #pragma unroll
;             for (int r = 0; r < 4; ++r) {
;                 const float rg = sigmoidf_(ga[r] + bav[r]), ig = sigmoidf_(gx[r] + bxv[r]);
;                 const float la = -8.0f * rg * sp[r]; float A = __expf(la);
;                 float U = __builtin_amdgcn_sqrtf(1.0f - A * A) * (ig * xcf[tok * 65 + j0 + r]);
;                 { const float As = dpp_shr1<1>(A), Us = dpp_shr0<1>(U); U = A * Us + U; A = A * As; }
;                 { const float As = dpp_shr1<2>(A), Us = dpp_shr0<2>(U); U = A * Us + U; A = A * As; }
;                 { const float As = dpp_shr1<4>(A), Us = dpp_shr0<4>(U); U = A * Us + U; A = A * As; }
;                 { const float As = dpp_shr1<8>(A), Us = dpp_shr0<8>(U); U = A * Us + U; A = A * As; }
;                 const float hh = U + A * hc[r], PP = A * Pc[r];
;                 hc[r] = bcast15(hh, lane); Pc[r] = bcast15(PP, lane); hv[r] = hh; pv[r] = PP; }
;             *(unsigned long long*)(y + (size_t)(row0 + tok) * DM + 64 * h + j0) = (unsigned long long)pk2(hv[0], hv[1]) | ((unsigned long long)pk2(hv[2], hv[3]) << 32);
;             *(unsigned long long*)((bf16_t*)(ws + WS_P) + (size_t)(row0 + tok) * 512 + 64 * h + j0) = (unsigned long long)pk2(pv[0], pv[1]) | ((unsigned long long)pk2(pv[2], pv[3]) << 32);
;         }
	v_mov_b32_dpp v33, v17 row_shr:8 row_mask:0xf bank_mask:0xf bound_ctrl:1
	v_pk_fma_f32 v[16:17], v[50:51], v[32:33], v[16:17]
	v_add_f32_e32 v32, v42, v46
	v_mul_f32_e32 v32, 0xbfb8aa3b, v32
	v_exp_f32_e32 v32, v32
	v_add_f32_e32 v19, 1.0, v19
	v_rcp_f32_e32 v18, v18
	v_rcp_f32_e32 v19, v19
	v_add_f32_e32 v32, 1.0, v32
	v_rcp_f32_e32 v32, v32
	v_mov_b32_e32 v46, 1.0
	v_pk_mul_f32 v[18:19], v[18:19], v[64:65]
	v_mov_b32_dpp v52, v50 row_shr:8 row_mask:0xf bank_mask:0xf
	v_mul_f32_e32 v32, 0xc1000000, v32
	v_mul_f32_e32 v32, v2, v32
	v_mul_f32_e32 v32, 0x3fb8aa3b, v32
	v_exp_f32_e32 v32, v32
	v_mov_b32_dpp v53, v51 row_shr:8 row_mask:0xf bank_mask:0xf
	v_pk_mul_f32 v[52:53], v[50:51], v[52:53]
	ds_bpermute_b32 v56, v1, v52
	v_fma_f32 v33, -v32, v32, 1.0
	v_sqrt_f32_e32 v44, v33
	v_add_f32_e32 v33, v43, v47
	v_mul_f32_e32 v33, 0xbfb8aa3b, v33
	v_exp_f32_e32 v33, v33
	v_mov_b32_e32 v47, 1.0
	v_mov_b32_dpp v46, v32 row_shr:1 row_mask:0xf bank_mask:0xf
	v_pk_fma_f32 v[16:17], v[52:53], 0, v[16:17] op_sel_hi:[1,0,1]
	v_add_f32_e32 v33, 1.0, v33
	v_rcp_f32_e32 v33, v33
	ds_bpermute_b32 v34, v1, v16
	ds_bpermute_b32 v35, v1, v17
	v_cvt_pk_bf16_f32 v16, v16, v17
	v_mul_f32_e32 v33, 0xc1000000, v33
	v_mul_f32_e32 v33, v59, v33
	v_mul_f32_e32 v33, 0x3fb8aa3b, v33
	v_exp_f32_e32 v33, v33
	ds_bpermute_b32 v57, v1, v53
	v_fma_f32 v45, -v33, v33, 1.0
	v_sqrt_f32_e32 v45, v45
	v_mov_b32_dpp v47, v33 row_shr:1 row_mask:0xf bank_mask:0xf
	v_pk_mul_f32 v[48:49], v[32:33], v[46:47]
	v_mov_b32_e32 v46, 1.0
	v_pk_mul_f32 v[18:19], v[44:45], v[18:19]
	v_mov_b32_e32 v47, 1.0
	v_mov_b32_dpp v46, v48 row_shr:2 row_mask:0xf bank_mask:0xf
	v_mov_b32_dpp v44, v18 row_shr:1 row_mask:0xf bank_mask:0xf bound_ctrl:1
	v_mov_b32_dpp v45, v19 row_shr:1 row_mask:0xf bank_mask:0xf bound_ctrl:1
	v_pk_fma_f32 v[18:19], v[32:33], v[44:45], v[18:19]
	v_mov_b32_dpp v47, v49 row_shr:2 row_mask:0xf bank_mask:0xf
	v_pk_mul_f32 v[50:51], v[48:49], v[46:47]
	v_mov_b32_dpp v32, v18 row_shr:2 row_mask:0xf bank_mask:0xf bound_ctrl:1
	v_mov_b32_dpp v33, v19 row_shr:2 row_mask:0xf bank_mask:0xf bound_ctrl:1
	v_mov_b32_e32 v46, 1.0
	v_mov_b32_e32 v47, 1.0
	v_pk_fma_f32 v[18:19], v[48:49], v[32:33], v[18:19]
	v_mov_b32_dpp v46, v50 row_shr:4 row_mask:0xf bank_mask:0xf
	v_mov_b32_dpp v47, v51 row_shr:4 row_mask:0xf bank_mask:0xf
	v_mov_b32_dpp v32, v18 row_shr:4 row_mask:0xf bank_mask:0xf bound_ctrl:1
	v_mov_b32_dpp v33, v19 row_shr:4 row_mask:0xf bank_mask:0xf bound_ctrl:1
	v_pk_mul_f32 v[54:55], v[50:51], v[46:47]
	v_mov_b32_e32 v46, 1.0
	v_mov_b32_e32 v47, 1.0
	v_pk_fma_f32 v[18:19], v[50:51], v[32:33], v[18:19]
	v_mov_b32_dpp v46, v54 row_shr:8 row_mask:0xf bank_mask:0xf
	v_mov_b32_dpp v47, v55 row_shr:8 row_mask:0xf bank_mask:0xf
	v_mov_b32_dpp v32, v18 row_shr:8 row_mask:0xf bank_mask:0xf bound_ctrl:1
	v_mov_b32_dpp v33, v19 row_shr:8 row_mask:0xf bank_mask:0xf bound_ctrl:1
	v_pk_mul_f32 v[62:63], v[54:55], v[46:47]
	v_pk_fma_f32 v[18:19], v[54:55], v[32:33], v[18:19]
	ds_bpermute_b32 v46, v1, v62
	v_pk_fma_f32 v[18:19], v[62:63], 0, v[18:19] op_sel_hi:[1,0,1]
	ds_bpermute_b32 v32, v1, v18
	v_cvt_pk_bf16_f32 v17, v18, v19
	global_store_dwordx2 v[100:101], v[16:17], off offset:96
	v_cvt_pk_bf16_f32 v16, v52, v53
	v_cvt_pk_bf16_f32 v17, v62, v63
	ds_bpermute_b32 v33, v1, v19
	global_store_dwordx2 v[102:103], v[16:17], off offset:96
	v_mfma_f32_16x16x32_bf16 v[16:19], v[68:71], v[12:15], 0
	ds_bpermute_b32 v47, v1, v63
	v_mfma_f32_16x16x32_bf16 v[12:15], v[72:75], v[12:15], 0
	v_mfma_f32_16x16x32_bf16 v[16:19], v[76:79], v[28:31], v[16:19]
	v_mfma_f32_16x16x32_bf16 v[12:15], v[80:83], v[28:31], v[12:15]
	s_nop 6
	v_add_f32_e32 v16, v40, v16
	v_mul_f32_e32 v16, 0xbfb8aa3b, v16
	v_exp_f32_e32 v16, v16
	v_add_f32_e32 v12, v36, v12
	v_mul_f32_e32 v12, 0xbfb8aa3b, v12
	v_exp_f32_e32 v12, v12
	v_add_f32_e32 v16, 1.0, v16
	v_rcp_f32_e32 v16, v16
	v_add_f32_e32 v13, v37, v13
	v_add_f32_e32 v12, 1.0, v12
	v_rcp_f32_e32 v28, v12
	v_mul_f32_e32 v12, 0xc1000000, v16
	v_add_f32_e32 v16, v41, v17
	v_mul_f32_e32 v16, 0xbfb8aa3b, v16
	v_exp_f32_e32 v16, v16
	v_mul_f32_e32 v13, 0xbfb8aa3b, v13
	v_exp_f32_e32 v13, v13
	v_mul_f32_e32 v12, v58, v12
	v_add_f32_e32 v16, 1.0, v16
	v_rcp_f32_e32 v16, v16
	v_add_f32_e32 v13, 1.0, v13
	v_rcp_f32_e32 v29, v13
	v_mul_f32_e32 v12, 0x3fb8aa3b, v12
	v_mul_f32_e32 v13, 0xc1000000, v16
	v_mul_f32_e32 v13, v60, v13
	v_mul_f32_e32 v13, 0x3fb8aa3b, v13
	v_exp_f32_e32 v30, v12
	v_exp_f32_e32 v31, v13
	v_add_f32_e32 v18, v42, v18
	v_add_f32_e32 v19, v43, v19
	v_fma_f32 v12, -v30, v30, 1.0
	v_fma_f32 v13, -v31, v31, 1.0
	v_sqrt_f32_e32 v44, v12
	v_mov_b32_e32 v12, 1.0
	v_sqrt_f32_e32 v45, v13
	v_mov_b32_e32 v13, 1.0
	v_mov_b32_dpp v12, v30 row_shr:1 row_mask:0xf bank_mask:0xf
	v_mul_f32_e32 v18, 0xbfb8aa3b, v18
	v_mov_b32_dpp v13, v31 row_shr:1 row_mask:0xf bank_mask:0xf
	v_pk_mul_f32 v[48:49], v[30:31], v[12:13]
	v_mov_b32_e32 v12, 1.0
	v_mov_b32_e32 v13, 1.0
	v_mul_f32_e32 v19, 0xbfb8aa3b, v19
	v_mov_b32_dpp v12, v48 row_shr:2 row_mask:0xf bank_mask:0xf
	v_mov_b32_dpp v13, v49 row_shr:2 row_mask:0xf bank_mask:0xf
	v_pk_mul_f32 v[50:51], v[48:49], v[12:13]
	v_mov_b32_e32 v12, 1.0
	v_mov_b32_e32 v13, 1.0
	v_exp_f32_e32 v18, v18
	v_mov_b32_dpp v12, v50 row_shr:4 row_mask:0xf bank_mask:0xf
	v_mov_b32_dpp v13, v51 row_shr:4 row_mask:0xf bank_mask:0xf
	v_pk_mul_f32 v[52:53], v[50:51], v[12:13]
	v_mov_b32_e32 v12, 1.0
	v_mov_b32_e32 v13, 1.0
	v_exp_f32_e32 v19, v19
	v_mov_b32_dpp v12, v52 row_shr:8 row_mask:0xf bank_mask:0xf
	v_mov_b32_dpp v13, v53 row_shr:8 row_mask:0xf bank_mask:0xf
	v_pk_mul_f32 v[54:55], v[52:53], v[12:13]
	v_add_u32_e32 v13, 0x1100, v145
	s_waitcnt lgkmcnt(0)
; __device__ __forceinline__ unsigned pk2(float lo, float hi) { const f32x2_t v = {lo, hi}; const bf16x2_t b = __builtin_convertvector(v, bf16x2_t); return __builtin_bit_cast(unsigned, b); }
; __device__ __forceinline__ float sigmoidf_(float x) { return __builtin_amdgcn_rcpf(1.0f + __expf(-x)); }
; __device__ __forceinline__ float bcast15(float v, int lane) { return bperm_f((lane & 48) | 15, v); }
; __device__ __forceinline__ void w_lru_m1(const Args& a, int l, unsigned char* ws, const bf16_t* proj, bf16_t* y, LAS unsigned char* wl, int b, int ck_, int h, int lane) {
;     ...
;         for (int tb = 0; tb < 4; ++tb) { const int tok = 16 * tb + lo;
;             f32x4 ga = {0.f, 0.f, 0.f, 0.f}, gx = {0.f, 0.f, 0.f, 0.f};
; #pragma unroll
;             for (int kk = 0; kk < 2; ++kk) { ga = __builtin_amdgcn_mfma_f32_16x16x32_bf16(WaF[kk], Xf[tb][kk], ga, 0, 0, 0); gx = __builtin_amdgcn_mfma_f32_16x16x32_bf16(WxF[kk], Xf[tb][kk], gx, 0, 0, 0); }
;             float hv[4], pv[4];
; #pragma unroll
;             for (int r = 0; r < 4; ++r) {
;                 const float rg = sigmoidf_(ga[r] + bav[r]), ig = sigmoidf_(gx[r] + bxv[r]);
;                 const float la = -8.0f * rg * sp[r]; float A = __expf(la);
;                 float U = __builtin_amdgcn_sqrtf(1.0f - A * A) * (ig * xcf[tok * 65 + j0 + r]);
;                 { const float As = dpp_shr1<1>(A), Us = dpp_shr0<1>(U); U = A * Us + U; A = A * As; }
;                 { const float As = dpp_shr1<2>(A), Us = dpp_shr0<2>(U); U = A * Us + U; A = A * As; }
;                 { const float As = dpp_shr1<4>(A), Us = dpp_shr0<4>(U); U = A * Us + U; A = A * As; }
;                 { const float As = dpp_shr1<8>(A), Us = dpp_shr0<8>(U); U = A * Us + U; A = A * As; }
;                 const float hh = U + A * hc[r], PP = A * Pc[r];
;                 hc[r] = bcast15(hh, lane); Pc[r] = bcast15(PP, lane); hv[r] = hh; pv[r] = PP; }
;             *(unsigned long long*)(y + (size_t)(row0 + tok) * DM + 64 * h + j0) = (unsigned long long)pk2(hv[0], hv[1]) | ((unsigned long long)pk2(hv[2], hv[3]) << 32);
;             *(unsigned long long*)((bf16_t*)(ws + WS_P) + (size_t)(row0 + tok) * 512 + 64 * h + j0) = (unsigned long long)pk2(pv[0], pv[1]) | ((unsigned long long)pk2(pv[2], pv[3]) << 32);
;         }
	v_pk_mul_f32 v[16:17], v[54:55], v[56:57]
	ds_read2_b32 v[56:57], v13 offset1:1
	v_add_f32_e32 v14, v38, v14
	v_add_f32_e32 v15, v39, v15
	v_mul_f32_e32 v14, 0xbfb8aa3b, v14
	v_mul_f32_e32 v15, 0xbfb8aa3b, v15
	s_waitcnt lgkmcnt(0)
	v_pk_mul_f32 v[28:29], v[56:57], v[28:29]
	v_add_f32_e32 v18, 1.0, v18
	v_pk_mul_f32 v[28:29], v[28:29], v[44:45]
	v_exp_f32_e32 v14, v14
	v_add_f32_e32 v19, 1.0, v19
	v_mov_b32_dpp v44, v28 row_shr:1 row_mask:0xf bank_mask:0xf bound_ctrl:1
	v_mov_b32_dpp v45, v29 row_shr:1 row_mask:0xf bank_mask:0xf bound_ctrl:1
	v_pk_fma_f32 v[28:29], v[30:31], v[44:45], v[28:29]
	v_exp_f32_e32 v15, v15
	v_rcp_f32_e32 v18, v18
	v_mov_b32_dpp v30, v28 row_shr:2 row_mask:0xf bank_mask:0xf bound_ctrl:1
	v_mov_b32_dpp v31, v29 row_shr:2 row_mask:0xf bank_mask:0xf bound_ctrl:1
	v_pk_fma_f32 v[28:29], v[48:49], v[30:31], v[28:29]
	v_rcp_f32_e32 v19, v19
	v_add_f32_e32 v14, 1.0, v14
	v_mov_b32_dpp v30, v28 row_shr:4 row_mask:0xf bank_mask:0xf bound_ctrl:1
	v_mov_b32_dpp v31, v29 row_shr:4 row_mask:0xf bank_mask:0xf bound_ctrl:1
	v_pk_fma_f32 v[28:29], v[50:51], v[30:31], v[28:29]
	v_add_f32_e32 v15, 1.0, v15
	ds_bpermute_b32 v12, v1, v16
	v_mov_b32_dpp v30, v28 row_shr:8 row_mask:0xf bank_mask:0xf bound_ctrl:1
	v_mov_b32_dpp v31, v29 row_shr:8 row_mask:0xf bank_mask:0xf bound_ctrl:1
	v_pk_fma_f32 v[28:29], v[52:53], v[30:31], v[28:29]
	ds_bpermute_b32 v13, v1, v17
	v_pk_fma_f32 v[30:31], v[54:55], v[34:35], v[28:29]
	v_rcp_f32_e32 v34, v14
	v_mul_f32_e32 v14, 0xc1000000, v18
	v_rcp_f32_e32 v35, v15
	v_mul_f32_e32 v15, 0xc1000000, v19
	v_mul_f32_e32 v14, v2, v14
	v_mul_f32_e32 v15, v59, v15
	v_mul_f32_e32 v14, 0x3fb8aa3b, v14
	v_mul_f32_e32 v15, 0x3fb8aa3b, v15
	v_exp_f32_e32 v18, v14
	v_exp_f32_e32 v19, v15
	ds_bpermute_b32 v28, v1, v30
	ds_bpermute_b32 v29, v1, v31
	v_fma_f32 v14, -v18, v18, 1.0
	v_fma_f32 v15, -v19, v19, 1.0
	v_sqrt_f32_e32 v44, v14
	v_mov_b32_e32 v14, 1.0
	v_sqrt_f32_e32 v45, v15
	v_mov_b32_e32 v15, 1.0
	v_mov_b32_dpp v14, v18 row_shr:1 row_mask:0xf bank_mask:0xf
	v_cvt_pk_bf16_f32 v30, v30, v31
	v_mov_b32_dpp v15, v19 row_shr:1 row_mask:0xf bank_mask:0xf
	v_pk_mul_f32 v[48:49], v[18:19], v[14:15]
	v_mov_b32_e32 v14, 1.0
	v_mov_b32_e32 v15, 1.0
	v_cvt_pk_bf16_f32 v16, v16, v17
	v_mov_b32_dpp v14, v48 row_shr:2 row_mask:0xf bank_mask:0xf
	v_mov_b32_dpp v15, v49 row_shr:2 row_mask:0xf bank_mask:0xf
	v_pk_mul_f32 v[50:51], v[48:49], v[14:15]
	v_mov_b32_e32 v14, 1.0
	v_mov_b32_e32 v15, 1.0
	s_nop 0
	v_mov_b32_dpp v14, v50 row_shr:4 row_mask:0xf bank_mask:0xf
	v_mov_b32_dpp v15, v51 row_shr:4 row_mask:0xf bank_mask:0xf
	v_pk_mul_f32 v[52:53], v[50:51], v[14:15]
	v_mov_b32_e32 v14, 1.0
	v_mov_b32_e32 v15, 1.0
	s_nop 0
	v_mov_b32_dpp v14, v52 row_shr:8 row_mask:0xf bank_mask:0xf
	v_mov_b32_dpp v15, v53 row_shr:8 row_mask:0xf bank_mask:0xf
	v_pk_mul_f32 v[54:55], v[52:53], v[14:15]
	v_add_u32_e32 v15, 0x1108, v145
	ds_read2_b32 v[56:57], v15 offset1:1
	v_pk_mul_f32 v[46:47], v[54:55], v[46:47]
	ds_bpermute_b32 v14, v1, v46
	v_cvt_pk_bf16_f32 v17, v46, v47
	ds_bpermute_b32 v15, v1, v47
	s_waitcnt lgkmcnt(0)
	v_pk_mul_f32 v[34:35], v[34:35], v[56:57]
	s_nop 0
	v_pk_mul_f32 v[34:35], v[44:45], v[34:35]
	s_nop 1
	v_mov_b32_dpp v44, v34 row_shr:1 row_mask:0xf bank_mask:0xf bound_ctrl:1
	v_mov_b32_dpp v45, v35 row_shr:1 row_mask:0xf bank_mask:0xf bound_ctrl:1
	v_pk_fma_f32 v[18:19], v[18:19], v[44:45], v[34:35]
	s_nop 1
	v_mov_b32_dpp v34, v18 row_shr:2 row_mask:0xf bank_mask:0xf bound_ctrl:1
	v_mov_b32_dpp v35, v19 row_shr:2 row_mask:0xf bank_mask:0xf bound_ctrl:1
	v_pk_fma_f32 v[18:19], v[48:49], v[34:35], v[18:19]
	s_nop 1
	v_mov_b32_dpp v34, v18 row_shr:4 row_mask:0xf bank_mask:0xf bound_ctrl:1
	v_mov_b32_dpp v35, v19 row_shr:4 row_mask:0xf bank_mask:0xf bound_ctrl:1
	v_pk_fma_f32 v[18:19], v[50:51], v[34:35], v[18:19]
	s_nop 1
	v_mov_b32_dpp v34, v18 row_shr:8 row_mask:0xf bank_mask:0xf bound_ctrl:1
	v_mov_b32_dpp v35, v19 row_shr:8 row_mask:0xf bank_mask:0xf bound_ctrl:1
	v_pk_fma_f32 v[18:19], v[52:53], v[34:35], v[18:19]
	s_nop 0
	v_pk_fma_f32 v[32:33], v[54:55], v[32:33], v[18:19]
	ds_bpermute_b32 v18, v1, v32
	v_cvt_pk_bf16_f32 v31, v32, v33
	ds_bpermute_b32 v19, v1, v33
	global_store_dwordx2 v[104:105], v[30:31], off offset:96
	v_mfma_f32_16x16x32_bf16 v[30:33], v[68:71], v[8:11], 0
	global_store_dwordx2 v[106:107], v[16:17], off offset:96
	v_mfma_f32_16x16x32_bf16 v[8:11], v[72:75], v[8:11], 0
	v_mfma_f32_16x16x32_bf16 v[30:33], v[76:79], v[24:27], v[30:33]
	v_mfma_f32_16x16x32_bf16 v[24:27], v[80:83], v[24:27], v[8:11]
	s_nop 6
	v_add_f32_e32 v8, v40, v30
	v_add_f32_e32 v9, v36, v24
	v_mul_f32_e32 v9, 0xbfb8aa3b, v9
	v_exp_f32_e32 v9, v9
	v_mul_f32_e32 v8, 0xbfb8aa3b, v8
	v_exp_f32_e32 v8, v8
	v_add_f32_e32 v11, v37, v25
	v_add_f32_e32 v9, 1.0, v9
	v_rcp_f32_e32 v10, v9
	v_add_f32_e32 v9, v41, v31
	v_mul_f32_e32 v9, 0xbfb8aa3b, v9
	v_exp_f32_e32 v9, v9
	v_add_f32_e32 v8, 1.0, v8
	v_rcp_f32_e32 v8, v8
	v_mul_f32_e32 v11, 0xbfb8aa3b, v11
	v_add_f32_e32 v9, 1.0, v9
	v_rcp_f32_e32 v9, v9
	v_mul_f32_e32 v8, 0xc1000000, v8
	v_mul_f32_e32 v8, v58, v8
	v_mul_f32_e32 v8, 0x3fb8aa3b, v8
	v_mul_f32_e32 v9, 0xc1000000, v9
	v_mul_f32_e32 v9, v60, v9
	v_mul_f32_e32 v9, 0x3fb8aa3b, v9
	v_exp_f32_e32 v16, v8
	v_exp_f32_e32 v17, v9
	v_exp_f32_e32 v11, v11
	v_fma_f32 v8, -v16, v16, 1.0
	v_fma_f32 v9, -v17, v17, 1.0
	v_sqrt_f32_e32 v30, v8
	v_mov_b32_e32 v8, 1.0
	v_sqrt_f32_e32 v31, v9
	v_mov_b32_e32 v9, 1.0
	v_mov_b32_dpp v8, v16 row_shr:1 row_mask:0xf bank_mask:0xf
	v_add_f32_e32 v11, 1.0, v11
	v_mov_b32_dpp v9, v17 row_shr:1 row_mask:0xf bank_mask:0xf
	v_pk_mul_f32 v[34:35], v[16:17], v[8:9]
	v_mov_b32_e32 v8, 1.0
	v_mov_b32_e32 v9, 1.0
	v_rcp_f32_e32 v11, v11
	v_mov_b32_dpp v8, v34 row_shr:2 row_mask:0xf bank_mask:0xf
	v_mov_b32_dpp v9, v35 row_shr:2 row_mask:0xf bank_mask:0xf
	v_pk_mul_f32 v[44:45], v[34:35], v[8:9]
	v_mov_b32_e32 v8, 1.0
	v_mov_b32_e32 v9, 1.0
	s_nop 0
	v_mov_b32_dpp v8, v44 row_shr:4 row_mask:0xf bank_mask:0xf
	v_mov_b32_dpp v9, v45 row_shr:4 row_mask:0xf bank_mask:0xf
	v_pk_mul_f32 v[46:47], v[44:45], v[8:9]
	v_mov_b32_e32 v8, 1.0
	v_mov_b32_e32 v9, 1.0
	s_nop 0
	v_mov_b32_dpp v8, v46 row_shr:8 row_mask:0xf bank_mask:0xf
	v_mov_b32_dpp v9, v47 row_shr:8 row_mask:0xf bank_mask:0xf
	v_pk_mul_f32 v[48:49], v[46:47], v[8:9]
	s_nop 0
	v_pk_mul_f32 v[8:9], v[48:49], v[12:13]
	v_add_u32_e32 v12, 0x2140, v145
	ds_read2_b32 v[12:13], v12 offset1:1
	ds_bpermute_b32 v24, v1, v8
	ds_bpermute_b32 v25, v1, v9
	v_cvt_pk_bf16_f32 v8, v8, v9
	s_waitcnt lgkmcnt(0)
; __device__ __forceinline__ unsigned pk2(float lo, float hi) { const f32x2_t v = {lo, hi}; const bf16x2_t b = __builtin_convertvector(v, bf16x2_t); return __builtin_bit_cast(unsigned, b); }
; __device__ __forceinline__ float sigmoidf_(float x) { return __builtin_amdgcn_rcpf(1.0f + __expf(-x)); }
; __device__ __forceinline__ float bcast15(float v, int lane) { return bperm_f((lane & 48) | 15, v); }
; __device__ __forceinline__ void w_lru_m1(const Args& a, int l, unsigned char* ws, const bf16_t* proj, bf16_t* y, LAS unsigned char* wl, int b, int ck_, int h, int lane) {
;     ...
;         for (int tb = 0; tb < 4; ++tb) { const int tok = 16 * tb + lo;
;             f32x4 ga = {0.f, 0.f, 0.f, 0.f}, gx = {0.f, 0.f, 0.f, 0.f};
; #pragma unroll
;             for (int kk = 0; kk < 2; ++kk) { ga = __builtin_amdgcn_mfma_f32_16x16x32_bf16(WaF[kk], Xf[tb][kk], ga, 0, 0, 0); gx = __builtin_amdgcn_mfma_f32_16x16x32_bf16(WxF[kk], Xf[tb][kk], gx, 0, 0, 0); }
;             float hv[4], pv[4];
; #pragma unroll
;             for (int r = 0; r < 4; ++r) {
;                 const float rg = sigmoidf_(ga[r] + bav[r]), ig = sigmoidf_(gx[r] + bxv[r]);
;                 const float la = -8.0f * rg * sp[r]; float A = __expf(la);
;                 float U = __builtin_amdgcn_sqrtf(1.0f - A * A) * (ig * xcf[tok * 65 + j0 + r]);
;                 { const float As = dpp_shr1<1>(A), Us = dpp_shr0<1>(U); U = A * Us + U; A = A * As; }
;                 { const float As = dpp_shr1<2>(A), Us = dpp_shr0<2>(U); U = A * Us + U; A = A * As; }
;                 { const float As = dpp_shr1<4>(A), Us = dpp_shr0<4>(U); U = A * Us + U; A = A * As; }
;                 { const float As = dpp_shr1<8>(A), Us = dpp_shr0<8>(U); U = A * Us + U; A = A * As; }
;                 const float hh = U + A * hc[r], PP = A * Pc[r];
;                 hc[r] = bcast15(hh, lane); Pc[r] = bcast15(PP, lane); hv[r] = hh; pv[r] = PP; }
;             *(unsigned long long*)(y + (size_t)(row0 + tok) * DM + 64 * h + j0) = (unsigned long long)pk2(hv[0], hv[1]) | ((unsigned long long)pk2(hv[2], hv[3]) << 32);
;             *(unsigned long long*)((bf16_t*)(ws + WS_P) + (size_t)(row0 + tok) * 512 + 64 * h + j0) = (unsigned long long)pk2(pv[0], pv[1]) | ((unsigned long long)pk2(pv[2], pv[3]) << 32);
;         }
	v_pk_mul_f32 v[10:11], v[12:13], v[10:11]
	s_nop 0
	v_pk_mul_f32 v[10:11], v[10:11], v[30:31]
	v_mov_b32_e32 v30, 1.0
	v_mov_b32_e32 v31, 1.0
	v_mov_b32_dpp v12, v10 row_shr:1 row_mask:0xf bank_mask:0xf bound_ctrl:1
	v_mov_b32_dpp v13, v11 row_shr:1 row_mask:0xf bank_mask:0xf bound_ctrl:1
	v_pk_fma_f32 v[10:11], v[16:17], v[12:13], v[10:11]
	s_nop 1
	v_mov_b32_dpp v12, v10 row_shr:2 row_mask:0xf bank_mask:0xf bound_ctrl:1
	v_mov_b32_dpp v13, v11 row_shr:2 row_mask:0xf bank_mask:0xf bound_ctrl:1
	v_pk_fma_f32 v[10:11], v[34:35], v[12:13], v[10:11]
	s_nop 1
	v_mov_b32_dpp v12, v10 row_shr:4 row_mask:0xf bank_mask:0xf bound_ctrl:1
	v_mov_b32_dpp v13, v11 row_shr:4 row_mask:0xf bank_mask:0xf bound_ctrl:1
	v_pk_fma_f32 v[10:11], v[44:45], v[12:13], v[10:11]
	s_nop 1
	v_mov_b32_dpp v12, v10 row_shr:8 row_mask:0xf bank_mask:0xf bound_ctrl:1
	v_mov_b32_dpp v13, v11 row_shr:8 row_mask:0xf bank_mask:0xf bound_ctrl:1
	v_pk_fma_f32 v[10:11], v[46:47], v[12:13], v[10:11]
	v_add_f32_e32 v12, v42, v32
	v_mul_f32_e32 v12, 0xbfb8aa3b, v12
	v_exp_f32_e32 v12, v12
	v_pk_fma_f32 v[10:11], v[48:49], v[28:29], v[10:11]
	v_mov_b32_e32 v32, 1.0
	ds_bpermute_b32 v16, v1, v10
	v_add_f32_e32 v12, 1.0, v12
	v_rcp_f32_e32 v13, v12
	v_add_f32_e32 v12, v38, v26
	v_mul_f32_e32 v12, 0xbfb8aa3b, v12
	v_exp_f32_e32 v12, v12
	v_mul_f32_e32 v13, 0xc1000000, v13
	v_mul_f32_e32 v13, v2, v13
	v_mul_f32_e32 v13, 0x3fb8aa3b, v13
	v_exp_f32_e32 v26, v13
	v_add_f32_e32 v12, 1.0, v12
	v_rcp_f32_e32 v12, v12
	ds_bpermute_b32 v17, v1, v11
	v_fma_f32 v13, -v26, v26, 1.0
	v_sqrt_f32_e32 v28, v13
	v_add_f32_e32 v13, v43, v33
	v_mul_f32_e32 v13, 0xbfb8aa3b, v13
	v_exp_f32_e32 v13, v13
	v_mov_b32_dpp v30, v26 row_shr:1 row_mask:0xf bank_mask:0xf
	v_mov_b32_e32 v33, 1.0
	v_cvt_pk_bf16_f32 v10, v10, v11
	v_add_f32_e32 v13, 1.0, v13
	v_rcp_f32_e32 v29, v13
	v_add_f32_e32 v13, v39, v27
	v_mul_f32_e32 v13, 0xbfb8aa3b, v13
	v_exp_f32_e32 v13, v13
	v_mul_f32_e32 v27, 0xc1000000, v29
	v_mul_f32_e32 v27, v59, v27
	v_mul_f32_e32 v27, 0x3fb8aa3b, v27
	v_exp_f32_e32 v27, v27
	v_add_f32_e32 v13, 1.0, v13
	v_rcp_f32_e32 v13, v13
	v_mov_b32_dpp v31, v27 row_shr:1 row_mask:0xf bank_mask:0xf
	v_pk_mul_f32 v[30:31], v[26:27], v[30:31]
	v_fma_f32 v29, -v27, v27, 1.0
	v_sqrt_f32_e32 v29, v29
	v_mov_b32_dpp v32, v30 row_shr:2 row_mask:0xf bank_mask:0xf
	v_mov_b32_dpp v33, v31 row_shr:2 row_mask:0xf bank_mask:0xf
	v_pk_mul_f32 v[34:35], v[30:31], v[32:33]
	v_mov_b32_e32 v32, 1.0
	v_mov_b32_e32 v33, 1.0
	s_nop 0
	v_mov_b32_dpp v32, v34 row_shr:4 row_mask:0xf bank_mask:0xf
	v_mov_b32_dpp v33, v35 row_shr:4 row_mask:0xf bank_mask:0xf
	v_pk_mul_f32 v[44:45], v[34:35], v[32:33]
	v_mov_b32_e32 v32, 1.0
	v_mov_b32_e32 v33, 1.0
	s_nop 0
	v_mov_b32_dpp v32, v44 row_shr:8 row_mask:0xf bank_mask:0xf
	v_mov_b32_dpp v33, v45 row_shr:8 row_mask:0xf bank_mask:0xf
	v_pk_mul_f32 v[46:47], v[44:45], v[32:33]
	v_add_u32_e32 v33, 0x2148, v145
	ds_read2_b32 v[48:49], v33 offset1:1
	v_pk_mul_f32 v[14:15], v[46:47], v[14:15]
	ds_bpermute_b32 v32, v1, v14
	v_cvt_pk_bf16_f32 v9, v14, v15
	ds_bpermute_b32 v33, v1, v15
	s_waitcnt lgkmcnt(0)
	v_pk_mul_f32 v[12:13], v[12:13], v[48:49]
	s_nop 0
	v_pk_mul_f32 v[12:13], v[28:29], v[12:13]
	s_nop 1
	v_mov_b32_dpp v28, v12 row_shr:1 row_mask:0xf bank_mask:0xf bound_ctrl:1
	v_mov_b32_dpp v29, v13 row_shr:1 row_mask:0xf bank_mask:0xf bound_ctrl:1
	v_pk_fma_f32 v[12:13], v[26:27], v[28:29], v[12:13]
	s_nop 1
	v_mov_b32_dpp v26, v12 row_shr:2 row_mask:0xf bank_mask:0xf bound_ctrl:1
	v_mov_b32_dpp v27, v13 row_shr:2 row_mask:0xf bank_mask:0xf bound_ctrl:1
	v_pk_fma_f32 v[12:13], v[30:31], v[26:27], v[12:13]
	s_nop 1
	v_mov_b32_dpp v26, v12 row_shr:4 row_mask:0xf bank_mask:0xf bound_ctrl:1
	v_mov_b32_dpp v27, v13 row_shr:4 row_mask:0xf bank_mask:0xf bound_ctrl:1
	v_pk_fma_f32 v[12:13], v[34:35], v[26:27], v[12:13]
	s_nop 1
	v_mov_b32_dpp v26, v12 row_shr:8 row_mask:0xf bank_mask:0xf bound_ctrl:1
	v_mov_b32_dpp v27, v13 row_shr:8 row_mask:0xf bank_mask:0xf bound_ctrl:1
	v_pk_fma_f32 v[12:13], v[44:45], v[26:27], v[12:13]
	s_nop 0
	v_pk_fma_f32 v[18:19], v[46:47], v[18:19], v[12:13]
	ds_bpermute_b32 v12, v1, v18
	v_cvt_pk_bf16_f32 v11, v18, v19
	global_store_dwordx2 v[96:97], v[10:11], off offset:96
	global_store_dwordx2 v[98:99], v[8:9], off offset:96
	v_mfma_f32_16x16x32_bf16 v[8:11], v[68:71], v[4:7], 0
	ds_bpermute_b32 v13, v1, v19
	v_mfma_f32_16x16x32_bf16 v[4:7], v[72:75], v[4:7], 0
	v_mfma_f32_16x16x32_bf16 v[8:11], v[76:79], v[20:23], v[8:11]
	v_mfma_f32_16x16x32_bf16 v[4:7], v[80:83], v[20:23], v[4:7]
	s_nop 6
	v_add_f32_e32 v8, v40, v8
	v_mul_f32_e32 v8, 0xbfb8aa3b, v8
	v_exp_f32_e32 v8, v8
	v_add_f32_e32 v4, v36, v4
	v_add_f32_e32 v9, v41, v9
	v_mul_f32_e32 v4, 0xbfb8aa3b, v4
	v_mul_f32_e32 v9, 0xbfb8aa3b, v9
	v_add_f32_e32 v8, 1.0, v8
	v_exp_f32_e32 v4, v4
	v_exp_f32_e32 v9, v9
	v_rcp_f32_e32 v14, v8
	v_add_f32_e32 v5, v37, v5
	v_mul_f32_e32 v5, 0xbfb8aa3b, v5
	v_add_f32_e32 v4, 1.0, v4
	v_add_f32_e32 v9, 1.0, v9
	v_exp_f32_e32 v5, v5
	v_rcp_f32_e32 v8, v4
	v_mul_f32_e32 v4, 0xc1000000, v14
	v_rcp_f32_e32 v14, v9
	v_add_f32_e32 v5, 1.0, v5
	v_rcp_f32_e32 v9, v5
	v_mul_f32_e32 v4, v58, v4
	v_mul_f32_e32 v5, 0xc1000000, v14
	v_mul_f32_e32 v5, v60, v5
	v_mul_f32_e32 v4, 0x3fb8aa3b, v4
	v_mul_f32_e32 v5, 0x3fb8aa3b, v5
	v_exp_f32_e32 v18, v4
	v_exp_f32_e32 v19, v5
	v_add_f32_e32 v10, v42, v10
	v_mul_f32_e32 v10, 0xbfb8aa3b, v10
	v_fma_f32 v4, -v18, v18, 1.0
	v_fma_f32 v5, -v19, v19, 1.0
	v_sqrt_f32_e32 v20, v4
	v_mov_b32_e32 v4, 1.0
	v_sqrt_f32_e32 v21, v5
	v_mov_b32_e32 v5, 1.0
	v_mov_b32_dpp v4, v18 row_shr:1 row_mask:0xf bank_mask:0xf
	v_exp_f32_e32 v10, v10
	v_mov_b32_dpp v5, v19 row_shr:1 row_mask:0xf bank_mask:0xf
	v_pk_mul_f32 v[22:23], v[18:19], v[4:5]
	v_mov_b32_e32 v4, 1.0
	v_mov_b32_e32 v5, 1.0
	v_add_f32_e32 v6, v38, v6
	v_mov_b32_dpp v4, v22 row_shr:2 row_mask:0xf bank_mask:0xf
	v_mov_b32_dpp v5, v23 row_shr:2 row_mask:0xf bank_mask:0xf
	v_pk_mul_f32 v[26:27], v[22:23], v[4:5]
	v_mov_b32_e32 v4, 1.0
	v_mov_b32_e32 v5, 1.0
	v_mul_f32_e32 v6, 0xbfb8aa3b, v6
	v_mov_b32_dpp v4, v26 row_shr:4 row_mask:0xf bank_mask:0xf
	v_mov_b32_dpp v5, v27 row_shr:4 row_mask:0xf bank_mask:0xf
	v_pk_mul_f32 v[28:29], v[26:27], v[4:5]
	v_mov_b32_e32 v4, 1.0
	v_mov_b32_e32 v5, 1.0
	v_add_f32_e32 v10, 1.0, v10
	v_mov_b32_dpp v4, v28 row_shr:8 row_mask:0xf bank_mask:0xf
	v_mov_b32_dpp v5, v29 row_shr:8 row_mask:0xf bank_mask:0xf
	v_pk_mul_f32 v[30:31], v[28:29], v[4:5]
	v_add_u32_e32 v5, 0x3180, v145
	v_pk_mul_f32 v[14:15], v[30:31], v[24:25]
	ds_read2_b32 v[24:25], v5 offset1:1
	v_exp_f32_e32 v6, v6
	v_rcp_f32_e32 v10, v10
	v_add_f32_e32 v7, v39, v7
	v_mul_f32_e32 v7, 0xbfb8aa3b, v7
	s_waitcnt lgkmcnt(0)
; __device__ __forceinline__ unsigned pk2(float lo, float hi) { const f32x2_t v = {lo, hi}; const bf16x2_t b = __builtin_convertvector(v, bf16x2_t); return __builtin_bit_cast(unsigned, b); }
; __device__ __forceinline__ float sigmoidf_(float x) { return __builtin_amdgcn_rcpf(1.0f + __expf(-x)); }
; __device__ __forceinline__ void w_lru_m1(const Args& a, int l, unsigned char* ws, const bf16_t* proj, bf16_t* y, LAS unsigned char* wl, int b, int ck_, int h, int lane) {
;     ...
;         for (int tb = 0; tb < 4; ++tb) { const int tok = 16 * tb + lo;
;             f32x4 ga = {0.f, 0.f, 0.f, 0.f}, gx = {0.f, 0.f, 0.f, 0.f};
; #pragma unroll
;             for (int kk = 0; kk < 2; ++kk) { ga = __builtin_amdgcn_mfma_f32_16x16x32_bf16(WaF[kk], Xf[tb][kk], ga, 0, 0, 0); gx = __builtin_amdgcn_mfma_f32_16x16x32_bf16(WxF[kk], Xf[tb][kk], gx, 0, 0, 0); }
;             float hv[4], pv[4];
; #pragma unroll
;             for (int r = 0; r < 4; ++r) {
;                 const float rg = sigmoidf_(ga[r] + bav[r]), ig = sigmoidf_(gx[r] + bxv[r]);
;                 const float la = -8.0f * rg * sp[r]; float A = __expf(la);
;                 float U = __builtin_amdgcn_sqrtf(1.0f - A * A) * (ig * xcf[tok * 65 + j0 + r]);
;                 { const float As = dpp_shr1<1>(A), Us = dpp_shr0<1>(U); U = A * Us + U; A = A * As; }
;                 { const float As = dpp_shr1<2>(A), Us = dpp_shr0<2>(U); U = A * Us + U; A = A * As; }
;                 { const float As = dpp_shr1<4>(A), Us = dpp_shr0<4>(U); U = A * Us + U; A = A * As; }
;                 { const float As = dpp_shr1<8>(A), Us = dpp_shr0<8>(U); U = A * Us + U; A = A * As; }
;                 const float hh = U + A * hc[r], PP = A * Pc[r];
;                 hc[r] = bcast15(hh, lane); Pc[r] = bcast15(PP, lane); hv[r] = hh; pv[r] = PP; }
;             *(unsigned long long*)(y + (size_t)(row0 + tok) * DM + 64 * h + j0) = (unsigned long long)pk2(hv[0], hv[1]) | ((unsigned long long)pk2(hv[2], hv[3]) << 32);
;             *(unsigned long long*)((bf16_t*)(ws + WS_P) + (size_t)(row0 + tok) * 512 + 64 * h + j0) = (unsigned long long)pk2(pv[0], pv[1]) | ((unsigned long long)pk2(pv[2], pv[3]) << 32);
;         }
;         if (lo == 0) { const size_t so = (size_t)(b * NCH + ck_) * 512 + 64 * h + j0;
; #pragma unroll
;             for (int r = 0; r < 4; ++r) { ((float*)(ws + WS_LRUA))[so + r] = Pc[r]; ((float*)(ws + WS_LRUH))[so + r] = hc[r]; } }
	v_pk_mul_f32 v[8:9], v[24:25], v[8:9]
	v_add_f32_e32 v6, 1.0, v6
	v_pk_mul_f32 v[8:9], v[8:9], v[20:21]
	v_exp_f32_e32 v7, v7
	ds_bpermute_b32 v4, v1, v14
	v_mov_b32_dpp v20, v8 row_shr:1 row_mask:0xf bank_mask:0xf bound_ctrl:1
	v_mov_b32_dpp v21, v9 row_shr:1 row_mask:0xf bank_mask:0xf bound_ctrl:1
	v_pk_fma_f32 v[8:9], v[18:19], v[20:21], v[8:9]
	v_add_f32_e32 v7, 1.0, v7
	ds_bpermute_b32 v5, v1, v15
	v_mov_b32_dpp v18, v8 row_shr:2 row_mask:0xf bank_mask:0xf bound_ctrl:1
	v_mov_b32_dpp v19, v9 row_shr:2 row_mask:0xf bank_mask:0xf bound_ctrl:1
	v_pk_fma_f32 v[8:9], v[22:23], v[18:19], v[8:9]
	s_nop 1
	v_mov_b32_dpp v18, v8 row_shr:4 row_mask:0xf bank_mask:0xf bound_ctrl:1
	v_mov_b32_dpp v19, v9 row_shr:4 row_mask:0xf bank_mask:0xf bound_ctrl:1
	v_pk_fma_f32 v[8:9], v[26:27], v[18:19], v[8:9]
	s_nop 1
	v_mov_b32_dpp v18, v8 row_shr:8 row_mask:0xf bank_mask:0xf bound_ctrl:1
	v_mov_b32_dpp v19, v9 row_shr:8 row_mask:0xf bank_mask:0xf bound_ctrl:1
	v_pk_fma_f32 v[8:9], v[28:29], v[18:19], v[8:9]
	v_rcp_f32_e32 v18, v6
	v_mul_f32_e32 v6, 0xc1000000, v10
	v_mul_f32_e32 v2, v2, v6
	v_mul_f32_e32 v2, 0x3fb8aa3b, v2
	v_exp_f32_e32 v10, v2
	v_mov_b32_e32 v6, 1.0
	v_rcp_f32_e32 v19, v7
	v_mov_b32_e32 v7, 1.0
	v_fma_f32 v2, -v10, v10, 1.0
	v_sqrt_f32_e32 v20, v2
	v_add_f32_e32 v2, v43, v11
	v_mul_f32_e32 v2, 0xbfb8aa3b, v2
	v_exp_f32_e32 v2, v2
	v_mov_b32_dpp v6, v10 row_shr:1 row_mask:0xf bank_mask:0xf
	v_pk_fma_f32 v[16:17], v[30:31], v[16:17], v[8:9]
	ds_bpermute_b32 v8, v1, v16
	v_add_f32_e32 v2, 1.0, v2
	v_rcp_f32_e32 v2, v2
	ds_bpermute_b32 v9, v1, v17
	v_cvt_pk_bf16_f32 v16, v16, v17
	v_mul_f32_e32 v2, 0xc1000000, v2
	v_mul_f32_e32 v2, v59, v2
	v_mul_f32_e32 v2, 0x3fb8aa3b, v2
	v_exp_f32_e32 v11, v2
	s_nop 0
	v_fma_f32 v2, -v11, v11, 1.0
	v_mov_b32_dpp v7, v11 row_shr:1 row_mask:0xf bank_mask:0xf
	v_pk_mul_f32 v[24:25], v[10:11], v[6:7]
	v_mov_b32_e32 v6, 1.0
	v_mov_b32_e32 v7, 1.0
	v_sqrt_f32_e32 v21, v2
	v_mov_b32_dpp v6, v24 row_shr:2 row_mask:0xf bank_mask:0xf
	v_mov_b32_dpp v7, v25 row_shr:2 row_mask:0xf bank_mask:0xf
	v_pk_mul_f32 v[26:27], v[24:25], v[6:7]
	v_mov_b32_e32 v6, 1.0
	v_mov_b32_e32 v7, 1.0
	v_add_u32_e32 v2, 0x3188, v145
	v_mov_b32_dpp v6, v26 row_shr:4 row_mask:0xf bank_mask:0xf
	v_mov_b32_dpp v7, v27 row_shr:4 row_mask:0xf bank_mask:0xf
	v_pk_mul_f32 v[28:29], v[26:27], v[6:7]
	v_mov_b32_e32 v6, 1.0
	v_mov_b32_e32 v7, 1.0
	s_nop 0
	v_mov_b32_dpp v6, v28 row_shr:8 row_mask:0xf bank_mask:0xf
	v_mov_b32_dpp v7, v29 row_shr:8 row_mask:0xf bank_mask:0xf
	v_pk_mul_f32 v[30:31], v[28:29], v[6:7]
	s_nop 0
	v_pk_mul_f32 v[22:23], v[30:31], v[32:33]
	ds_read2_b32 v[32:33], v2 offset1:1
	ds_bpermute_b32 v6, v1, v22
	ds_bpermute_b32 v7, v1, v23
	s_waitcnt lgkmcnt(0)
	v_pk_mul_f32 v[18:19], v[18:19], v[32:33]
	s_nop 0
	v_pk_mul_f32 v[18:19], v[20:21], v[18:19]
	s_nop 1
	v_mov_b32_dpp v20, v18 row_shr:1 row_mask:0xf bank_mask:0xf bound_ctrl:1
	v_mov_b32_dpp v21, v19 row_shr:1 row_mask:0xf bank_mask:0xf bound_ctrl:1
	v_pk_fma_f32 v[10:11], v[10:11], v[20:21], v[18:19]
	s_nop 1
	v_mov_b32_dpp v18, v10 row_shr:2 row_mask:0xf bank_mask:0xf bound_ctrl:1
	v_mov_b32_dpp v19, v11 row_shr:2 row_mask:0xf bank_mask:0xf bound_ctrl:1
	v_pk_fma_f32 v[10:11], v[24:25], v[18:19], v[10:11]
	s_nop 1
	v_mov_b32_dpp v18, v10 row_shr:4 row_mask:0xf bank_mask:0xf bound_ctrl:1
	v_mov_b32_dpp v19, v11 row_shr:4 row_mask:0xf bank_mask:0xf bound_ctrl:1
	v_pk_fma_f32 v[10:11], v[26:27], v[18:19], v[10:11]
	s_nop 1
	v_mov_b32_dpp v18, v10 row_shr:8 row_mask:0xf bank_mask:0xf bound_ctrl:1
	v_mov_b32_dpp v19, v11 row_shr:8 row_mask:0xf bank_mask:0xf bound_ctrl:1
	v_pk_fma_f32 v[10:11], v[28:29], v[18:19], v[10:11]
	s_nop 0
	v_pk_fma_f32 v[12:13], v[30:31], v[12:13], v[10:11]
	ds_bpermute_b32 v10, v1, v12
	ds_bpermute_b32 v11, v1, v13
	v_cvt_pk_bf16_f32 v17, v12, v13
	v_cvt_pk_bf16_f32 v12, v14, v15
	v_cvt_pk_bf16_f32 v13, v22, v23
	global_store_dwordx2 v[114:115], v[16:17], off offset:96
	global_store_dwordx2 v[116:117], v[12:13], off offset:96
	s_and_saveexec_b64 s[34:35], vcc
	s_cbranch_execz .LBB0_518
	v_add_u32_e32 v0, 48, v0
	v_ashrrev_i32_e32 v1, 31, v0
	v_lshl_add_u64 v[0:1], s[42:43], 0, v[0:1]
	v_lshlrev_b64 v[0:1], 2, v[0:1]
	v_lshl_add_u64 v[12:13], s[84:85], 0, v[0:1]
	v_lshl_add_u64 v[0:1], s[86:87], 0, v[0:1]
	global_store_dwordx4 v[12:13], v[4:7], off
	s_waitcnt lgkmcnt(0)
	global_store_dwordx4 v[0:1], v[8:11], off
	s_branch .LBB0_518

; __device__ __forceinline__ const float* in_ptr(const Args& a, int i) { asm volatile("" : "+s"(i)); return a.in[i]; }
; __device__ __forceinline__ void w_lru_m1(const Args& a, int l, unsigned char* ws, const bf16_t* proj, bf16_t* y, LAS unsigned char* wl, int b, int ck_, int h, int lane) {
;     ...
;     const float* ba = in_ptr(a, I_BA) + l * 512 + 64 * h; const float* bx = in_ptr(a, I_BX) + l * 512 + 64 * h; const float* lam = in_ptr(a, I_LAM) + l * 512 + 64 * h;
;     ...
;         for (int r = 0; r < 4; ++r) { bav[r] = pba[r]; bxv[r] = pbx[r]; sp[r] = log1pf(__expf(-plam[r])); hc[r] = 0.f; Pc[r] = 1.f; }
.LBB0_842:
	s_cmp_gt_u32 s81, 1
	s_cbranch_scc1 .Lsp_tab_done
	s_load_dwordx2 s[40:41], s[0:1], 0x48
	v_lshl_add_u32 v85, s81, 9, v220
	v_lshlrev_b32_e32 v85, 2, v85
	s_waitcnt lgkmcnt(0)
	global_load_dword v84, v85, s[40:41]
	s_waitcnt vmcnt(0)
	v_mul_f32_e32 v2, 0xbfb8aa3b, v84
	v_exp_f32_e32 v2, v2
	s_nop 0
	s_nop 0
	s_nop 0
	s_nop 0
	s_nop 0
	s_nop 0
	s_nop 0
	s_nop 0
	s_nop 0
	s_nop 0
	v_add_f32_e32 v84, 1.0, v2
	v_add_f32_e32 v93, -1.0, v84
	v_sub_f32_e32 v94, v93, v84
	v_add_f32_e32 v94, 1.0, v94
	v_sub_f32_e32 v93, v2, v93
	v_add_f32_e32 v93, v93, v94
	v_frexp_mant_f32_e32 v94, v84
	v_cmp_gt_f32_e64 s[40:41], s77, v94
	v_cvt_f64_f32_e32 v[94:95], v84
	v_frexp_exp_i32_f64_e32 v94, v[94:95]
	v_subbrev_co_u32_e64 v128, s[40:41], 0, v94, s[40:41]
	v_sub_u32_e32 v94, 0, v128
	v_ldexp_f32 v84, v84, v94
	v_ldexp_f32 v93, v93, v94
	v_add_f32_e32 v94, -1.0, v84
	v_add_f32_e32 v95, 1.0, v94
	v_sub_f32_e32 v95, v84, v95
	v_add_f32_e32 v122, v93, v95
	v_add_f32_e32 v95, 1.0, v84
	v_add_f32_e32 v123, -1.0, v95
	v_sub_f32_e32 v84, v84, v123
	v_add_f32_e32 v84, v93, v84
	v_add_f32_e32 v93, v95, v84
	v_rcp_f32_e32 v129, v93
	v_sub_f32_e32 v95, v93, v95
	v_sub_f32_e32 v84, v84, v95
	v_add_f32_e32 v95, v94, v122
	v_sub_f32_e32 v94, v95, v94
	v_mul_f32_e32 v131, v95, v129
	v_sub_f32_e32 v130, v122, v94
	v_mul_f32_e32 v122, v93, v131
	v_fma_f32 v124, v131, v93, -v122
	v_fmac_f32_e32 v124, v131, v84
	v_add_f32_e32 v94, v122, v124
	v_sub_f32_e32 v123, v95, v94
	v_pk_add_f32 v[126:127], v[94:95], v[122:123] neg_lo:[0,1] neg_hi:[0,1]
	v_mov_b32_e32 v125, v94
	v_pk_add_f32 v[94:95], v[126:127], v[124:125] neg_lo:[0,1] neg_hi:[0,1]
	v_cmp_neq_f32_e64 s[40:41], s22, v2
	v_add_f32_e32 v95, v130, v95
	v_add_f32_e32 v94, v94, v95
	v_add_f32_e32 v95, v123, v94
	v_mul_f32_e32 v130, v129, v95
	v_mul_f32_e32 v122, v93, v130
	v_fma_f32 v124, v130, v93, -v122
	v_fmac_f32_e32 v124, v130, v84
	v_sub_f32_e32 v84, v123, v95
	v_add_f32_e32 v84, v94, v84
	v_add_f32_e32 v94, v122, v124
	v_sub_f32_e32 v123, v95, v94
	v_pk_add_f32 v[126:127], v[94:95], v[122:123] neg_lo:[0,1] neg_hi:[0,1]
	v_mov_b32_e32 v125, v94
	v_pk_add_f32 v[94:95], v[126:127], v[124:125] neg_lo:[0,1] neg_hi:[0,1]
	v_add_f32_e32 v93, v131, v130
	v_add_f32_e32 v84, v84, v95
	v_add_f32_e32 v84, v94, v84
	v_add_f32_e32 v84, v123, v84
	v_sub_f32_e32 v94, v93, v131
	v_mul_f32_e32 v84, v129, v84
	v_sub_f32_e32 v94, v130, v94
	v_add_f32_e32 v84, v94, v84
	v_add_f32_e32 v95, v93, v84
	v_mul_f32_e32 v122, v95, v95
	v_fmamk_f32 v94, v122, 0x3e9b6dac, v201
	v_fmaak_f32 v169, v122, v94, 0x3f2aaada
	v_cvt_f32_i32_e32 v94, v128
	v_sub_f32_e32 v93, v95, v93
	v_ldexp_f32 v123, v95, 1
	v_mul_f32_e32 v95, v95, v122
	v_pk_mul_f32 v[124:125], v[94:95], v[168:169]
	v_sub_f32_e32 v84, v84, v93
	v_fma_f32 v122, v94, s94, -v124
	v_fmac_f32_e32 v122, 0xb102e308, v94
	v_pk_add_f32 v[94:95], v[124:125], v[122:123]
	v_ldexp_f32 v84, v84, 1
	v_sub_f32_e32 v93, v95, v123
	v_sub_f32_e32 v93, v125, v93
	v_add_f32_e32 v127, v84, v93
	v_mov_b32_e32 v126, v124
	v_pk_add_f32 v[124:125], v[94:95], v[124:125] neg_lo:[0,1] neg_hi:[0,1]
	v_pk_add_f32 v[128:129], v[94:95], v[126:127]
	v_mov_b32_e32 v123, v94
	v_mov_b32_e32 v125, v129
	v_pk_add_f32 v[130:131], v[122:123], v[124:125] neg_lo:[0,1] neg_hi:[0,1]
	v_pk_add_f32 v[122:123], v[122:123], v[124:125]
	v_mov_b32_e32 v126, v127
	v_pk_add_f32 v[124:125], v[122:123], v[94:95] op_sel:[1,0] op_sel_hi:[0,1] neg_lo:[0,1] neg_hi:[0,1]
	v_pk_add_f32 v[132:133], v[128:129], v[124:125] op_sel_hi:[1,0] neg_lo:[0,1] neg_hi:[0,1]
	v_mov_b32_e32 v128, v129
	v_mov_b32_e32 v129, v123
	v_pk_mov_b32 v[124:125], v[94:95], v[124:125] op_sel:[1,0]
	v_mov_b32_e32 v127, v94
	v_pk_add_f32 v[124:125], v[128:129], v[124:125] neg_lo:[0,1] neg_hi:[0,1]
	v_mov_b32_e32 v132, v130
	v_pk_add_f32 v[94:95], v[126:127], v[124:125] neg_lo:[0,1] neg_hi:[0,1]
	v_mov_b32_e32 v131, v123
	v_pk_add_f32 v[124:125], v[132:133], v[94:95]
	s_nop 0
	v_pk_add_f32 v[126:127], v[124:125], v[124:125] op_sel:[0,1] op_sel_hi:[1,0]
	s_nop 0
	v_pk_add_f32 v[122:123], v[122:123], v[126:127] op_sel:[1,0] op_sel_hi:[0,1]
	v_mov_b32_e32 v125, v122
	v_pk_add_f32 v[128:129], v[124:125], v[130:131] neg_lo:[0,1] neg_hi:[0,1]
	v_mov_b32_e32 v95, v126
	v_sub_f32_e32 v84, v124, v128
	v_pk_add_f32 v[94:95], v[94:95], v[128:129] neg_lo:[0,1] neg_hi:[0,1]
	v_sub_f32_e32 v84, v130, v84
	v_add_f32_e32 v84, v94, v84
	v_add_f32_e32 v84, v84, v95
	v_add_f32_e32 v84, v122, v84
	v_cndmask_b32_e64 v84, v208, v84, s[40:41]
	v_cmp_ngt_f32_e64 s[40:41], -1.0, v2
	s_nop 0
	s_nop 0
	v_cndmask_b32_e64 v84, v205, v84, s[40:41]
	v_cmp_neq_f32_e64 s[40:41], -1.0, v2
	s_nop 1
	v_cndmask_b32_e64 v84, v206, v84, s[40:41]
	v_cmp_lt_f32_e64 s[40:41], |v2|, s95
	s_nop 1
	v_cndmask_b32_e64 v147, v84, v2, s[40:41]
	s_add_u32 s40, s78, 0x3b00000
	s_addc_u32 s41, s79, 0x0
	s_nop 0
	global_store_dword v85, v147, s[40:41]
